# v32 plus K-loop back-edge bookkeeping (s_add/s_cmp) moved before the loop-closing barrier in 9 GEMM loops
# baseline (speedup 1.0000x reference)
; #define PG8_STAGE(bufoff, gbase, voff) do { _Pragma("unroll") for (int _i = 0; _i < 2; ++_i) \
;         __builtin_amdgcn_global_load_lds((const unsigned*)((const char*)(gbase) + (voff)[_i]), (LAS unsigned*)(lds + (bufoff) + ldsw + _i * 8192), 16, 0, 0); } while (0)
; #define PG8_LDA(dst, b, h) do { _Pragma("unroll") for (int m = 0; m < 4; ++m) _Pragma("unroll") for (int k = 0; k < 2; ++k) dst[m][k] = *(const LAS bf16x8*)(lds + PG8_SA(b, h) + aoff + m * 2048 + k * 1024); } while (0)
; #define PG8_LDB(dst, b, h) do { _Pragma("unroll") for (int n = 0; n < 2; ++n) _Pragma("unroll") for (int k = 0; k < 2; ++k) dst[n][k] = *(const LAS bf16x8*)(lds + PG8_SB(b, h) + boff + n * 2048 + k * 1024); } while (0)
; #define PG8_MMA(ai, bj, At, Bt) do { __builtin_amdgcn_s_setprio(1); _Pragma("unroll") for (int m = 0; m < 4; ++m) _Pragma("unroll") for (int n = 0; n < 2; ++n) _Pragma("unroll") for (int k = 0; k < 2; ++k) \
;         acc[ai][bj][m][n] = __builtin_amdgcn_mfma_f32_16x16x32_bf16(Bt[n][k], At[m][k], acc[ai][bj][m][n], 0, 0, 0); __builtin_amdgcn_s_setprio(0); } while (0)
; #define PG8_WAIT_V(n) asm volatile("s_waitcnt vmcnt(" #n ")" ::: "memory")
; #define PG8_WAIT_L(n) asm volatile("s_waitcnt lgkmcnt(" #n ")" ::: "memory")
; #define PG8_BAR __builtin_amdgcn_s_barrier()
; #define PG8_SCHED __builtin_amdgcn_sched_barrier(0)
; template <class Epi, bool ALIGN_EPI>
; DI void gemm_phase(lptr lds, const Gemm g, const StaticOrder& S, const Epi& E) {
;     ...
;             const char* a1 = cA + (size_t)(t + 1) * kstep;
;             const char* a2 = last ? nA : cA + (size_t)(t + 2) * kstep; const char* b2 = last ? nB : cB + (size_t)(t + 2) * kstep;
;             const char* a3 = a2 + kstep; const char* b3 = b2 + kstep;
;             PG8_LDB(B0, 0, 0); PG8_LDB(B1, 0, 1); PG8_SCHED; PG8_LDA(At, 0, 0); PG8_STAGE(PG8_SA(1, 1), a1 + hstepA, voffA);
;             PG8_WAIT_V(8); PG8_WAIT_L(0); PG8_BAR; PG8_MMA(0, 0, At, B0); PG8_MMA(0, 1, At, B1); PG8_BAR; PG8_SCHED;
;             PG8_LDA(At, 0, 1); PG8_STAGE(PG8_SB(0, 0), b2, voffB); PG8_STAGE(PG8_SB(0, 1), b2 + hstepB, voffB); PG8_STAGE(PG8_SA(0, 0), a2, voffA);
;             PG8_WAIT_V(8); PG8_WAIT_L(0); PG8_BAR; PG8_MMA(1, 0, At, B0); PG8_MMA(1, 1, At, B1); PG8_BAR; PG8_SCHED;
.LBB0_225:
	ds_read_b128 v[148:151], v211
	ds_read_b128 v[154:157], v211 offset:1024
	ds_read_b128 v[158:161], v211 offset:2048
	ds_read_b128 v[162:165], v211 offset:3072
	ds_read_b128 v[166:169], v212
	ds_read_b128 v[170:173], v212 offset:1024
	ds_read_b128 v[174:177], v212 offset:2048
	ds_read_b128 v[178:181], v212 offset:3072
	s_add_u32 s6, s4, 0xfffc0080
	s_addc_u32 s7, s5, -1
	s_cmp_eq_u32 s37, 12
	s_cselect_b32 s29, s23, s7
	s_cselect_b32 s28, s31, s6
	s_cselect_b32 s7, s21, s36
	s_cselect_b32 s6, s33, s35
	v_lshl_add_u64 v[198:199], s[4:5], 0, v[140:141]
	s_add_i32 m0, s42, 0xc000
	ds_read_b128 v[182:185], v213
	ds_read_b128 v[186:189], v213 offset:1024
	ds_read_b128 v[190:193], v213 offset:2048
	ds_read_b128 v[194:197], v213 offset:3072
	ds_read_b128 v[214:217], v213 offset:4096
	ds_read_b128 v[218:221], v213 offset:5120
	ds_read_b128 v[222:225], v213 offset:6144
	ds_read_b128 v[226:229], v213 offset:7168
	global_load_lds_dwordx4 v[198:199], off
	v_lshl_add_u64 v[198:199], s[4:5], 0, v[142:143]
	s_add_i32 m0, s42, 0xe000
	s_nop 0
	global_load_lds_dwordx4 v[198:199], off
	s_waitcnt vmcnt(8)
	s_waitcnt lgkmcnt(0)
	s_barrier
	s_setprio 1
	s_waitcnt lgkmcnt(0)
	v_mfma_f32_16x16x32_bf16 v[124:127], v[148:151], v[182:185], v[124:127]
	v_mfma_f32_16x16x32_bf16 v[120:123], v[158:161], v[182:185], v[120:123]
	v_mfma_f32_16x16x32_bf16 v[108:111], v[148:151], v[190:193], v[108:111]
	v_mfma_f32_16x16x32_bf16 v[104:107], v[158:161], v[190:193], v[104:107]
	v_mfma_f32_16x16x32_bf16 v[92:95], v[148:151], v[214:217], v[92:95]
	v_mfma_f32_16x16x32_bf16 v[88:91], v[158:161], v[214:217], v[88:91]
	v_mfma_f32_16x16x32_bf16 v[76:79], v[148:151], v[222:225], v[76:79]
	v_mfma_f32_16x16x32_bf16 v[72:75], v[158:161], v[222:225], v[72:75]
	v_mfma_f32_16x16x32_bf16 v[124:127], v[154:157], v[186:189], v[124:127]
	v_mfma_f32_16x16x32_bf16 v[120:123], v[162:165], v[186:189], v[120:123]
	v_mfma_f32_16x16x32_bf16 v[108:111], v[154:157], v[194:197], v[108:111]
	v_mfma_f32_16x16x32_bf16 v[104:107], v[162:165], v[194:197], v[104:107]
	v_mfma_f32_16x16x32_bf16 v[92:95], v[154:157], v[218:221], v[92:95]
	v_mfma_f32_16x16x32_bf16 v[88:91], v[162:165], v[218:221], v[88:91]
	v_mfma_f32_16x16x32_bf16 v[76:79], v[154:157], v[226:229], v[76:79]
	v_mfma_f32_16x16x32_bf16 v[72:75], v[162:165], v[226:229], v[72:75]
	s_setprio 0
	s_setprio 1
	v_mfma_f32_16x16x32_bf16 v[116:119], v[166:169], v[182:185], v[116:119]
	v_mfma_f32_16x16x32_bf16 v[112:115], v[174:177], v[182:185], v[112:115]
	v_mfma_f32_16x16x32_bf16 v[100:103], v[166:169], v[190:193], v[100:103]
	v_mfma_f32_16x16x32_bf16 v[96:99], v[174:177], v[190:193], v[96:99]
	v_mfma_f32_16x16x32_bf16 v[84:87], v[166:169], v[214:217], v[84:87]
	v_mfma_f32_16x16x32_bf16 v[80:83], v[174:177], v[214:217], v[80:83]
	v_mfma_f32_16x16x32_bf16 v[68:71], v[166:169], v[222:225], v[68:71]
	v_mfma_f32_16x16x32_bf16 v[64:67], v[174:177], v[222:225], v[64:67]
	v_mfma_f32_16x16x32_bf16 v[116:119], v[170:173], v[186:189], v[116:119]
	v_mfma_f32_16x16x32_bf16 v[112:115], v[178:181], v[186:189], v[112:115]
	v_mfma_f32_16x16x32_bf16 v[100:103], v[170:173], v[194:197], v[100:103]
	v_mfma_f32_16x16x32_bf16 v[96:99], v[178:181], v[194:197], v[96:99]
	v_mfma_f32_16x16x32_bf16 v[84:87], v[170:173], v[218:221], v[84:87]
	v_mfma_f32_16x16x32_bf16 v[80:83], v[178:181], v[218:221], v[80:83]
	v_mfma_f32_16x16x32_bf16 v[68:71], v[170:173], v[226:229], v[68:71]
	v_mfma_f32_16x16x32_bf16 v[64:67], v[178:181], v[226:229], v[64:67]
	s_setprio 0
	s_barrier
	s_add_i32 s38, s55, s41
	v_lshl_add_u64 v[198:199], s[6:7], 0, v[130:131]
	s_mov_b32 m0, s38
	ds_read_b128 v[182:185], v213 offset:16384
	ds_read_b128 v[186:189], v213 offset:17408
	ds_read_b128 v[190:193], v213 offset:18432
	ds_read_b128 v[194:197], v213 offset:19456
	ds_read_b128 v[214:217], v213 offset:20480
	ds_read_b128 v[218:221], v213 offset:21504
	ds_read_b128 v[222:225], v213 offset:22528
	ds_read_b128 v[226:229], v213 offset:23552
	global_load_lds_dwordx4 v[198:199], off
	s_add_i32 m0, s38, 0x2000
	s_add_u32 s38, s6, 0x40000
	v_lshl_add_u64 v[230:231], s[6:7], 0, v[134:135]
	s_addc_u32 s39, s7, 0
	s_add_i32 s58, s56, s41
	global_load_lds_dwordx4 v[230:231], off
	v_lshl_add_u64 v[232:233], s[38:39], 0, v[130:131]
	s_mov_b32 m0, s58
	v_lshl_add_u64 v[234:235], s[28:29], 0, v[132:133]
	global_load_lds_dwordx4 v[232:233], off
	v_lshl_add_u64 v[232:233], s[38:39], 0, v[134:135]
	s_add_i32 m0, s58, 0x2000
	s_nop 0
	global_load_lds_dwordx4 v[232:233], off
	v_lshl_add_u64 v[232:233], s[28:29], 0, v[128:129]
	s_mov_b32 m0, s42
	s_nop 0
	global_load_lds_dwordx4 v[232:233], off
	s_mov_b32 m0, s43
	s_nop 0
	global_load_lds_dwordx4 v[234:235], off
	s_waitcnt vmcnt(8)
	s_waitcnt lgkmcnt(0)
	s_barrier
; #define PG8_STAGE(bufoff, gbase, voff) do { _Pragma("unroll") for (int _i = 0; _i < 2; ++_i) \
;         __builtin_amdgcn_global_load_lds((const unsigned*)((const char*)(gbase) + (voff)[_i]), (LAS unsigned*)(lds + (bufoff) + ldsw + _i * 8192), 16, 0, 0); } while (0)
; #define PG8_LDA(dst, b, h) do { _Pragma("unroll") for (int m = 0; m < 4; ++m) _Pragma("unroll") for (int k = 0; k < 2; ++k) dst[m][k] = *(const LAS bf16x8*)(lds + PG8_SA(b, h) + aoff + m * 2048 + k * 1024); } while (0)
; #define PG8_LDB(dst, b, h) do { _Pragma("unroll") for (int n = 0; n < 2; ++n) _Pragma("unroll") for (int k = 0; k < 2; ++k) dst[n][k] = *(const LAS bf16x8*)(lds + PG8_SB(b, h) + boff + n * 2048 + k * 1024); } while (0)
; #define PG8_MMA(ai, bj, At, Bt) do { __builtin_amdgcn_s_setprio(1); _Pragma("unroll") for (int m = 0; m < 4; ++m) _Pragma("unroll") for (int n = 0; n < 2; ++n) _Pragma("unroll") for (int k = 0; k < 2; ++k) \
;         acc[ai][bj][m][n] = __builtin_amdgcn_mfma_f32_16x16x32_bf16(Bt[n][k], At[m][k], acc[ai][bj][m][n], 0, 0, 0); __builtin_amdgcn_s_setprio(0); } while (0)
; #define PG8_WAIT_V(n) asm volatile("s_waitcnt vmcnt(" #n ")" ::: "memory")
; #define PG8_WAIT_L(n) asm volatile("s_waitcnt lgkmcnt(" #n ")" ::: "memory")
; #define PG8_BAR __builtin_amdgcn_s_barrier()
; #define PG8_SCHED __builtin_amdgcn_sched_barrier(0)
; template <class Epi, bool ALIGN_EPI>
; DI void gemm_phase(lptr lds, const Gemm g, const StaticOrder& S, const Epi& E) {
;     ...
;             PG8_WAIT_V(8); PG8_WAIT_L(0); PG8_BAR; PG8_MMA(1, 0, At, B0); PG8_MMA(1, 1, At, B1); PG8_BAR; PG8_SCHED;
;             PG8_LDB(B0, 1, 0); PG8_LDB(B1, 1, 1); PG8_SCHED; PG8_LDA(At, 1, 0); PG8_STAGE(PG8_SA(0, 1), a2 + hstepA, voffA);
;             PG8_WAIT_V(8); PG8_WAIT_L(0); PG8_BAR; PG8_MMA(0, 0, At, B0); PG8_MMA(0, 1, At, B1); PG8_BAR; PG8_SCHED;
;             PG8_LDA(At, 1, 1); PG8_STAGE(PG8_SB(1, 0), b3, voffB); PG8_STAGE(PG8_SB(1, 1), b3 + hstepB, voffB); PG8_STAGE(PG8_SA(1, 0), a3, voffA);
	s_setprio 1
	s_waitcnt lgkmcnt(0)
	v_mfma_f32_16x16x32_bf16 v[60:63], v[148:151], v[182:185], v[60:63]
	v_mfma_f32_16x16x32_bf16 v[56:59], v[158:161], v[182:185], v[56:59]
	v_mfma_f32_16x16x32_bf16 v[44:47], v[148:151], v[190:193], v[44:47]
	v_mfma_f32_16x16x32_bf16 v[40:43], v[158:161], v[190:193], v[40:43]
	v_mfma_f32_16x16x32_bf16 v[28:31], v[148:151], v[214:217], v[28:31]
	v_mfma_f32_16x16x32_bf16 v[24:27], v[158:161], v[214:217], v[24:27]
	v_mfma_f32_16x16x32_bf16 v[12:15], v[148:151], v[222:225], v[12:15]
	v_mfma_f32_16x16x32_bf16 v[8:11], v[158:161], v[222:225], v[8:11]
	v_mfma_f32_16x16x32_bf16 v[60:63], v[154:157], v[186:189], v[60:63]
	v_mfma_f32_16x16x32_bf16 v[56:59], v[162:165], v[186:189], v[56:59]
	v_mfma_f32_16x16x32_bf16 v[44:47], v[154:157], v[194:197], v[44:47]
	v_mfma_f32_16x16x32_bf16 v[40:43], v[162:165], v[194:197], v[40:43]
	v_mfma_f32_16x16x32_bf16 v[28:31], v[154:157], v[218:221], v[28:31]
	v_mfma_f32_16x16x32_bf16 v[24:27], v[162:165], v[218:221], v[24:27]
	v_mfma_f32_16x16x32_bf16 v[12:15], v[154:157], v[226:229], v[12:15]
	v_mfma_f32_16x16x32_bf16 v[8:11], v[162:165], v[226:229], v[8:11]
	s_setprio 0
	s_setprio 1
	v_mfma_f32_16x16x32_bf16 v[52:55], v[166:169], v[182:185], v[52:55]
	v_mfma_f32_16x16x32_bf16 v[48:51], v[174:177], v[182:185], v[48:51]
	v_mfma_f32_16x16x32_bf16 v[36:39], v[166:169], v[190:193], v[36:39]
	v_mfma_f32_16x16x32_bf16 v[32:35], v[174:177], v[190:193], v[32:35]
	v_mfma_f32_16x16x32_bf16 v[20:23], v[166:169], v[214:217], v[20:23]
	v_mfma_f32_16x16x32_bf16 v[16:19], v[174:177], v[214:217], v[16:19]
	v_mfma_f32_16x16x32_bf16 v[4:7], v[166:169], v[222:225], v[4:7]
	v_mfma_f32_16x16x32_bf16 v[0:3], v[174:177], v[222:225], v[0:3]
	v_mfma_f32_16x16x32_bf16 v[52:55], v[170:173], v[186:189], v[52:55]
	v_mfma_f32_16x16x32_bf16 v[48:51], v[178:181], v[186:189], v[48:51]
	v_mfma_f32_16x16x32_bf16 v[36:39], v[170:173], v[194:197], v[36:39]
	v_mfma_f32_16x16x32_bf16 v[32:35], v[178:181], v[194:197], v[32:35]
	v_mfma_f32_16x16x32_bf16 v[20:23], v[170:173], v[218:221], v[20:23]
	v_mfma_f32_16x16x32_bf16 v[16:19], v[178:181], v[218:221], v[16:19]
	v_mfma_f32_16x16x32_bf16 v[4:7], v[170:173], v[226:229], v[4:7]
	v_mfma_f32_16x16x32_bf16 v[0:3], v[178:181], v[226:229], v[0:3]
	s_setprio 0
	s_barrier
	s_add_i32 s38, 0, 0x18000
	v_add_u32_e32 v136, s38, v209
	s_add_i32 s39, 0, 0x1c000
	ds_read_b128 v[148:151], v136
	ds_read_b128 v[154:157], v136 offset:1024
	ds_read_b128 v[158:161], v136 offset:2048
	ds_read_b128 v[162:165], v136 offset:3072
	v_add_u32_e32 v136, s39, v209
	ds_read_b128 v[166:169], v136
	ds_read_b128 v[170:173], v136 offset:1024
	ds_read_b128 v[174:177], v136 offset:2048
	ds_read_b128 v[178:181], v136 offset:3072
	s_add_u32 s28, s28, 0x40000
	s_addc_u32 s29, s29, 0
	s_mov_b32 m0, s44
	v_lshl_add_u64 v[236:237], s[28:29], 0, v[128:129]
	ds_read_b128 v[182:185], v213 offset:32768
	ds_read_b128 v[186:189], v213 offset:33792
	ds_read_b128 v[190:193], v213 offset:34816
	ds_read_b128 v[194:197], v213 offset:35840
	ds_read_b128 v[214:217], v213 offset:36864
	ds_read_b128 v[218:221], v213 offset:37888
	ds_read_b128 v[222:225], v213 offset:38912
	ds_read_b128 v[226:229], v213 offset:39936
	global_load_lds_dwordx4 v[236:237], off
	v_lshl_add_u64 v[236:237], s[28:29], 0, v[132:133]
	s_mov_b32 m0, s45
	s_nop 0
	global_load_lds_dwordx4 v[236:237], off
	s_waitcnt vmcnt(8)
	s_waitcnt lgkmcnt(0)
	s_barrier
	s_setprio 1
	s_waitcnt lgkmcnt(0)
	v_mfma_f32_16x16x32_bf16 v[124:127], v[148:151], v[182:185], v[124:127]
	v_mfma_f32_16x16x32_bf16 v[120:123], v[158:161], v[182:185], v[120:123]
	v_mfma_f32_16x16x32_bf16 v[108:111], v[148:151], v[190:193], v[108:111]
	v_mfma_f32_16x16x32_bf16 v[104:107], v[158:161], v[190:193], v[104:107]
	v_mfma_f32_16x16x32_bf16 v[92:95], v[148:151], v[214:217], v[92:95]
	v_mfma_f32_16x16x32_bf16 v[88:91], v[158:161], v[214:217], v[88:91]
	v_mfma_f32_16x16x32_bf16 v[76:79], v[148:151], v[222:225], v[76:79]
	v_mfma_f32_16x16x32_bf16 v[72:75], v[158:161], v[222:225], v[72:75]
	v_mfma_f32_16x16x32_bf16 v[124:127], v[154:157], v[186:189], v[124:127]
	v_mfma_f32_16x16x32_bf16 v[120:123], v[162:165], v[186:189], v[120:123]
	v_mfma_f32_16x16x32_bf16 v[108:111], v[154:157], v[194:197], v[108:111]
	v_mfma_f32_16x16x32_bf16 v[104:107], v[162:165], v[194:197], v[104:107]
	v_mfma_f32_16x16x32_bf16 v[92:95], v[154:157], v[218:221], v[92:95]
	v_mfma_f32_16x16x32_bf16 v[88:91], v[162:165], v[218:221], v[88:91]
	v_mfma_f32_16x16x32_bf16 v[76:79], v[154:157], v[226:229], v[76:79]
	v_mfma_f32_16x16x32_bf16 v[72:75], v[162:165], v[226:229], v[72:75]
	s_setprio 0
	s_setprio 1
	v_mfma_f32_16x16x32_bf16 v[116:119], v[166:169], v[182:185], v[116:119]
	v_mfma_f32_16x16x32_bf16 v[112:115], v[174:177], v[182:185], v[112:115]
	v_mfma_f32_16x16x32_bf16 v[100:103], v[166:169], v[190:193], v[100:103]
	v_mfma_f32_16x16x32_bf16 v[96:99], v[174:177], v[190:193], v[96:99]
	v_mfma_f32_16x16x32_bf16 v[84:87], v[166:169], v[214:217], v[84:87]
	v_mfma_f32_16x16x32_bf16 v[80:83], v[174:177], v[214:217], v[80:83]
	v_mfma_f32_16x16x32_bf16 v[68:71], v[166:169], v[222:225], v[68:71]
	v_mfma_f32_16x16x32_bf16 v[64:67], v[174:177], v[222:225], v[64:67]
	v_mfma_f32_16x16x32_bf16 v[116:119], v[170:173], v[186:189], v[116:119]
	v_mfma_f32_16x16x32_bf16 v[112:115], v[178:181], v[186:189], v[112:115]
	v_mfma_f32_16x16x32_bf16 v[100:103], v[170:173], v[194:197], v[100:103]
	v_mfma_f32_16x16x32_bf16 v[96:99], v[178:181], v[194:197], v[96:99]
	v_mfma_f32_16x16x32_bf16 v[84:87], v[170:173], v[218:221], v[84:87]
	v_mfma_f32_16x16x32_bf16 v[80:83], v[178:181], v[218:221], v[80:83]
	v_mfma_f32_16x16x32_bf16 v[68:71], v[170:173], v[226:229], v[68:71]
	v_mfma_f32_16x16x32_bf16 v[64:67], v[178:181], v[226:229], v[64:67]
	s_setprio 0
	s_barrier
; #define PG8_STAGE(bufoff, gbase, voff) do { _Pragma("unroll") for (int _i = 0; _i < 2; ++_i) \
;         __builtin_amdgcn_global_load_lds((const unsigned*)((const char*)(gbase) + (voff)[_i]), (LAS unsigned*)(lds + (bufoff) + ldsw + _i * 8192), 16, 0, 0); } while (0)
; #define PG8_LDA(dst, b, h) do { _Pragma("unroll") for (int m = 0; m < 4; ++m) _Pragma("unroll") for (int k = 0; k < 2; ++k) dst[m][k] = *(const LAS bf16x8*)(lds + PG8_SA(b, h) + aoff + m * 2048 + k * 1024); } while (0)
; #define PG8_MMA(ai, bj, At, Bt) do { __builtin_amdgcn_s_setprio(1); _Pragma("unroll") for (int m = 0; m < 4; ++m) _Pragma("unroll") for (int n = 0; n < 2; ++n) _Pragma("unroll") for (int k = 0; k < 2; ++k) \
;         acc[ai][bj][m][n] = __builtin_amdgcn_mfma_f32_16x16x32_bf16(Bt[n][k], At[m][k], acc[ai][bj][m][n], 0, 0, 0); __builtin_amdgcn_s_setprio(0); } while (0)
; #define PG8_WAIT_V(n) asm volatile("s_waitcnt vmcnt(" #n ")" ::: "memory")
; #define PG8_WAIT_L(n) asm volatile("s_waitcnt lgkmcnt(" #n ")" ::: "memory")
; #define PG8_BAR __builtin_amdgcn_s_barrier()
; #define PG8_SCHED __builtin_amdgcn_sched_barrier(0)
; template <class Epi, bool ALIGN_EPI>
; DI void gemm_phase(lptr lds, const Gemm g, const StaticOrder& S, const Epi& E) {
;     ...
;         for (int t = 0; t < nt; t += 2) {
;             const bool last = (t == nt - 2);
;     ...
;             PG8_LDA(At, 1, 1); PG8_STAGE(PG8_SB(1, 0), b3, voffB); PG8_STAGE(PG8_SB(1, 1), b3 + hstepB, voffB); PG8_STAGE(PG8_SA(1, 0), a3, voffA);
;             PG8_WAIT_V(8); PG8_WAIT_L(0); PG8_BAR; PG8_MMA(1, 0, At, B0); PG8_MMA(1, 1, At, B1); PG8_BAR; PG8_SCHED;
;         }
	s_add_i32 s28, s38, s41
	v_lshl_add_u64 v[198:199], v[198:199], 0, s[12:13]
	s_mov_b32 m0, s28
	ds_read_b128 v[182:185], v213 offset:49152
	ds_read_b128 v[186:189], v213 offset:50176
	ds_read_b128 v[190:193], v213 offset:51200
	ds_read_b128 v[194:197], v213 offset:52224
	ds_read_b128 v[214:217], v213 offset:53248
	ds_read_b128 v[218:221], v213 offset:54272
	ds_read_b128 v[222:225], v213 offset:55296
	ds_read_b128 v[226:229], v213 offset:56320
	global_load_lds_dwordx4 v[198:199], off
	s_add_i32 m0, s28, 0x2000
	s_add_u32 s6, s6, 0x40080
	v_lshl_add_u64 v[198:199], v[230:231], 0, s[12:13]
	s_addc_u32 s7, s7, 0
	s_add_i32 s28, s39, s41
	global_load_lds_dwordx4 v[198:199], off
	v_lshl_add_u64 v[198:199], s[6:7], 0, v[130:131]
	s_mov_b32 m0, s28
	s_nop 0
	global_load_lds_dwordx4 v[198:199], off
	v_lshl_add_u64 v[198:199], s[6:7], 0, v[134:135]
	s_add_i32 m0, s28, 0x2000
	s_nop 0
	global_load_lds_dwordx4 v[198:199], off
	v_lshl_add_u64 v[198:199], v[232:233], 0, s[12:13]
	s_mov_b32 m0, s49
	s_nop 0
	global_load_lds_dwordx4 v[198:199], off
	v_lshl_add_u64 v[198:199], v[234:235], 0, s[12:13]
	s_mov_b32 m0, s50
	s_nop 0
	global_load_lds_dwordx4 v[198:199], off
	s_waitcnt vmcnt(8)
	s_waitcnt lgkmcnt(0)
	s_barrier
	s_setprio 1
	s_waitcnt lgkmcnt(0)
	v_mfma_f32_16x16x32_bf16 v[60:63], v[148:151], v[182:185], v[60:63]
	v_mfma_f32_16x16x32_bf16 v[56:59], v[158:161], v[182:185], v[56:59]
	v_mfma_f32_16x16x32_bf16 v[44:47], v[148:151], v[190:193], v[44:47]
	v_mfma_f32_16x16x32_bf16 v[40:43], v[158:161], v[190:193], v[40:43]
	v_mfma_f32_16x16x32_bf16 v[28:31], v[148:151], v[214:217], v[28:31]
	v_mfma_f32_16x16x32_bf16 v[24:27], v[158:161], v[214:217], v[24:27]
	v_mfma_f32_16x16x32_bf16 v[12:15], v[148:151], v[222:225], v[12:15]
	v_mfma_f32_16x16x32_bf16 v[8:11], v[158:161], v[222:225], v[8:11]
	v_mfma_f32_16x16x32_bf16 v[60:63], v[154:157], v[186:189], v[60:63]
	v_mfma_f32_16x16x32_bf16 v[56:59], v[162:165], v[186:189], v[56:59]
	v_mfma_f32_16x16x32_bf16 v[44:47], v[154:157], v[194:197], v[44:47]
	v_mfma_f32_16x16x32_bf16 v[40:43], v[162:165], v[194:197], v[40:43]
	v_mfma_f32_16x16x32_bf16 v[28:31], v[154:157], v[218:221], v[28:31]
	v_mfma_f32_16x16x32_bf16 v[24:27], v[162:165], v[218:221], v[24:27]
	v_mfma_f32_16x16x32_bf16 v[12:15], v[154:157], v[226:229], v[12:15]
	v_mfma_f32_16x16x32_bf16 v[8:11], v[162:165], v[226:229], v[8:11]
	s_setprio 0
	s_setprio 1
	v_mfma_f32_16x16x32_bf16 v[52:55], v[166:169], v[182:185], v[52:55]
	v_mfma_f32_16x16x32_bf16 v[48:51], v[174:177], v[182:185], v[48:51]
	v_mfma_f32_16x16x32_bf16 v[36:39], v[166:169], v[190:193], v[36:39]
	v_mfma_f32_16x16x32_bf16 v[32:35], v[174:177], v[190:193], v[32:35]
	v_mfma_f32_16x16x32_bf16 v[20:23], v[166:169], v[214:217], v[20:23]
	v_mfma_f32_16x16x32_bf16 v[16:19], v[174:177], v[214:217], v[16:19]
	v_mfma_f32_16x16x32_bf16 v[4:7], v[166:169], v[222:225], v[4:7]
	v_mfma_f32_16x16x32_bf16 v[0:3], v[174:177], v[222:225], v[0:3]
	v_mfma_f32_16x16x32_bf16 v[52:55], v[170:173], v[186:189], v[52:55]
	v_mfma_f32_16x16x32_bf16 v[48:51], v[178:181], v[186:189], v[48:51]
	v_mfma_f32_16x16x32_bf16 v[36:39], v[170:173], v[194:197], v[36:39]
	v_mfma_f32_16x16x32_bf16 v[32:35], v[178:181], v[194:197], v[32:35]
	v_mfma_f32_16x16x32_bf16 v[20:23], v[170:173], v[218:221], v[20:23]
	v_mfma_f32_16x16x32_bf16 v[16:19], v[178:181], v[218:221], v[16:19]
	v_mfma_f32_16x16x32_bf16 v[4:7], v[170:173], v[226:229], v[4:7]
	v_mfma_f32_16x16x32_bf16 v[0:3], v[178:181], v[226:229], v[0:3]
	s_setprio 0
	s_add_i32 s37, s37, 2
	s_add_u32 s4, s4, 0x100
	s_addc_u32 s5, s5, 0
	s_add_u32 s35, s35, 0x100
	s_addc_u32 s36, s36, 0
	s_cmp_gt_u32 s37, 13
	s_barrier
	s_cbranch_scc0 .LBB0_225
	s_and_b64 vcc, exec, s[14:15]
	s_cbranch_vccnz .LBB0_276
	s_cmp_gt_i32 s34, 19
	s_mov_b64 s[4:5], -1
	s_cbranch_scc1 .LBB0_277

; #define PG8_STAGE(bufoff, gbase, voff) do { _Pragma("unroll") for (int _i = 0; _i < 2; ++_i) \
;         __builtin_amdgcn_global_load_lds((const unsigned*)((const char*)(gbase) + (voff)[_i]), (LAS unsigned*)(lds + (bufoff) + ldsw + _i * 8192), 16, 0, 0); } while (0)
; #define PG8_LDA(dst, b, h) do { _Pragma("unroll") for (int m = 0; m < 4; ++m) _Pragma("unroll") for (int k = 0; k < 2; ++k) dst[m][k] = *(const LAS bf16x8*)(lds + PG8_SA(b, h) + aoff + m * 2048 + k * 1024); } while (0)
; #define PG8_LDB(dst, b, h) do { _Pragma("unroll") for (int n = 0; n < 2; ++n) _Pragma("unroll") for (int k = 0; k < 2; ++k) dst[n][k] = *(const LAS bf16x8*)(lds + PG8_SB(b, h) + boff + n * 2048 + k * 1024); } while (0)
; #define PG8_MMA(ai, bj, At, Bt) do { __builtin_amdgcn_s_setprio(1); _Pragma("unroll") for (int m = 0; m < 4; ++m) _Pragma("unroll") for (int n = 0; n < 2; ++n) _Pragma("unroll") for (int k = 0; k < 2; ++k) \
;         acc[ai][bj][m][n] = __builtin_amdgcn_mfma_f32_16x16x32_bf16(Bt[n][k], At[m][k], acc[ai][bj][m][n], 0, 0, 0); __builtin_amdgcn_s_setprio(0); } while (0)
; #define PG8_WAIT_V(n) asm volatile("s_waitcnt vmcnt(" #n ")" ::: "memory")
; #define PG8_WAIT_L(n) asm volatile("s_waitcnt lgkmcnt(" #n ")" ::: "memory")
; #define PG8_BAR __builtin_amdgcn_s_barrier()
; #define PG8_SCHED __builtin_amdgcn_sched_barrier(0)
; template <class Epi, bool ALIGN_EPI>
; DI void gemm_phase(lptr lds, const Gemm g, const StaticOrder& S, const Epi& E) {
;     ...
;             const char* a1 = cA + (size_t)(t + 1) * kstep;
;             const char* a2 = last ? nA : cA + (size_t)(t + 2) * kstep; const char* b2 = last ? nB : cB + (size_t)(t + 2) * kstep;
;             const char* a3 = a2 + kstep; const char* b3 = b2 + kstep;
;             PG8_LDB(B0, 0, 0); PG8_LDB(B1, 0, 1); PG8_SCHED; PG8_LDA(At, 0, 0); PG8_STAGE(PG8_SA(1, 1), a1 + hstepA, voffA);
;             PG8_WAIT_V(8); PG8_WAIT_L(0); PG8_BAR; PG8_MMA(0, 0, At, B0); PG8_MMA(0, 1, At, B1); PG8_BAR; PG8_SCHED;
;             PG8_LDA(At, 0, 1); PG8_STAGE(PG8_SB(0, 0), b2, voffB); PG8_STAGE(PG8_SB(0, 1), b2 + hstepB, voffB); PG8_STAGE(PG8_SA(0, 0), a2, voffA);
;             PG8_WAIT_V(8); PG8_WAIT_L(0); PG8_BAR; PG8_MMA(1, 0, At, B0); PG8_MMA(1, 1, At, B1); PG8_BAR; PG8_SCHED;
.LBB0_455:
	ds_read_b128 v[158:161], v157
	ds_read_b128 v[168:171], v157 offset:1024
	ds_read_b128 v[172:175], v157 offset:2048
	ds_read_b128 v[176:179], v157 offset:3072
	ds_read_b128 v[180:183], v163
	ds_read_b128 v[184:187], v163 offset:1024
	ds_read_b128 v[188:191], v163 offset:2048
	ds_read_b128 v[192:195], v163 offset:3072
	s_add_u32 s24, s22, 0xfffc0080
	s_addc_u32 s25, s23, -1
	s_cmp_eq_u32 s55, 12
	s_cselect_b32 s27, s17, s25
	s_cselect_b32 s26, s51, s24
	s_cselect_b32 s25, s15, s54
	s_cselect_b32 s24, s52, s53
	v_lshl_add_u64 v[148:149], s[22:23], 0, v[140:141]
	s_add_i32 m0, s36, 0xc000
	ds_read_b128 v[196:199], v167
	ds_read_b128 v[200:203], v167 offset:1024
	ds_read_b128 v[204:207], v167 offset:2048
	ds_read_b128 v[208:211], v167 offset:3072
	ds_read_b128 v[212:215], v167 offset:4096
	ds_read_b128 v[216:219], v167 offset:5120
	ds_read_b128 v[220:223], v167 offset:6144
	ds_read_b128 v[224:227], v167 offset:7168
	global_load_lds_dwordx4 v[148:149], off
	v_lshl_add_u64 v[148:149], s[22:23], 0, v[142:143]
	s_add_i32 m0, s36, 0xe000
	s_nop 0
	global_load_lds_dwordx4 v[148:149], off
	s_waitcnt vmcnt(8)
	s_waitcnt lgkmcnt(0)
	s_barrier
	s_setprio 1
	s_waitcnt lgkmcnt(0)
	v_mfma_f32_16x16x32_bf16 v[124:127], v[158:161], v[196:199], v[124:127]
	v_mfma_f32_16x16x32_bf16 v[120:123], v[172:175], v[196:199], v[120:123]
	v_mfma_f32_16x16x32_bf16 v[116:119], v[158:161], v[204:207], v[116:119]
	v_mfma_f32_16x16x32_bf16 v[112:115], v[172:175], v[204:207], v[112:115]
	v_mfma_f32_16x16x32_bf16 v[96:99], v[158:161], v[212:215], v[96:99]
	v_mfma_f32_16x16x32_bf16 v[88:91], v[172:175], v[212:215], v[88:91]
	v_mfma_f32_16x16x32_bf16 v[80:83], v[158:161], v[220:223], v[80:83]
	v_mfma_f32_16x16x32_bf16 v[72:75], v[172:175], v[220:223], v[72:75]
	v_mfma_f32_16x16x32_bf16 v[124:127], v[168:171], v[200:203], v[124:127]
	v_mfma_f32_16x16x32_bf16 v[120:123], v[176:179], v[200:203], v[120:123]
	v_mfma_f32_16x16x32_bf16 v[116:119], v[168:171], v[208:211], v[116:119]
	v_mfma_f32_16x16x32_bf16 v[112:115], v[176:179], v[208:211], v[112:115]
	v_mfma_f32_16x16x32_bf16 v[96:99], v[168:171], v[216:219], v[96:99]
	v_mfma_f32_16x16x32_bf16 v[88:91], v[176:179], v[216:219], v[88:91]
	v_mfma_f32_16x16x32_bf16 v[80:83], v[168:171], v[224:227], v[80:83]
	v_mfma_f32_16x16x32_bf16 v[72:75], v[176:179], v[224:227], v[72:75]
	s_setprio 0
	s_setprio 1
	v_mfma_f32_16x16x32_bf16 v[108:111], v[180:183], v[196:199], v[108:111]
	v_mfma_f32_16x16x32_bf16 v[104:107], v[188:191], v[196:199], v[104:107]
	v_mfma_f32_16x16x32_bf16 v[100:103], v[180:183], v[204:207], v[100:103]
	v_mfma_f32_16x16x32_bf16 v[92:95], v[188:191], v[204:207], v[92:95]
	v_mfma_f32_16x16x32_bf16 v[84:87], v[180:183], v[212:215], v[84:87]
	v_mfma_f32_16x16x32_bf16 v[76:79], v[188:191], v[212:215], v[76:79]
	v_mfma_f32_16x16x32_bf16 v[68:71], v[180:183], v[220:223], v[68:71]
	v_mfma_f32_16x16x32_bf16 v[64:67], v[188:191], v[220:223], v[64:67]
	v_mfma_f32_16x16x32_bf16 v[108:111], v[184:187], v[200:203], v[108:111]
	v_mfma_f32_16x16x32_bf16 v[104:107], v[192:195], v[200:203], v[104:107]
	v_mfma_f32_16x16x32_bf16 v[100:103], v[184:187], v[208:211], v[100:103]
	v_mfma_f32_16x16x32_bf16 v[92:95], v[192:195], v[208:211], v[92:95]
	v_mfma_f32_16x16x32_bf16 v[84:87], v[184:187], v[216:219], v[84:87]
	v_mfma_f32_16x16x32_bf16 v[76:79], v[192:195], v[216:219], v[76:79]
	v_mfma_f32_16x16x32_bf16 v[68:71], v[184:187], v[224:227], v[68:71]
	v_mfma_f32_16x16x32_bf16 v[64:67], v[192:195], v[224:227], v[64:67]
	s_setprio 0
	s_barrier
	s_add_i32 s56, s44, s35
	v_lshl_add_u64 v[148:149], s[24:25], 0, v[130:131]
	s_mov_b32 m0, s56
	ds_read_b128 v[196:199], v167 offset:16384
	ds_read_b128 v[200:203], v167 offset:17408
	ds_read_b128 v[204:207], v167 offset:18432
	ds_read_b128 v[208:211], v167 offset:19456
	ds_read_b128 v[212:215], v167 offset:20480
	ds_read_b128 v[216:219], v167 offset:21504
	ds_read_b128 v[220:223], v167 offset:22528
	ds_read_b128 v[224:227], v167 offset:23552
	global_load_lds_dwordx4 v[148:149], off
	s_add_i32 m0, s56, 0x2000
	s_add_u32 s56, s24, 0x40000
	v_lshl_add_u64 v[154:155], s[24:25], 0, v[134:135]
	s_addc_u32 s57, s25, 0
	s_add_i32 s58, s45, s35
	global_load_lds_dwordx4 v[154:155], off
	v_lshl_add_u64 v[164:165], s[56:57], 0, v[130:131]
	s_mov_b32 m0, s58
	v_lshl_add_u64 v[228:229], s[26:27], 0, v[132:133]
	global_load_lds_dwordx4 v[164:165], off
	v_lshl_add_u64 v[164:165], s[56:57], 0, v[134:135]
	s_add_i32 m0, s58, 0x2000
	s_nop 0
	global_load_lds_dwordx4 v[164:165], off
	v_lshl_add_u64 v[164:165], s[26:27], 0, v[128:129]
	s_mov_b32 m0, s36
	s_nop 0
	global_load_lds_dwordx4 v[164:165], off
	s_mov_b32 m0, s37
	s_nop 0
	global_load_lds_dwordx4 v[228:229], off
	s_waitcnt vmcnt(8)
	s_waitcnt lgkmcnt(0)
	s_barrier
; #define PG8_STAGE(bufoff, gbase, voff) do { _Pragma("unroll") for (int _i = 0; _i < 2; ++_i) \
;         __builtin_amdgcn_global_load_lds((const unsigned*)((const char*)(gbase) + (voff)[_i]), (LAS unsigned*)(lds + (bufoff) + ldsw + _i * 8192), 16, 0, 0); } while (0)
; #define PG8_LDA(dst, b, h) do { _Pragma("unroll") for (int m = 0; m < 4; ++m) _Pragma("unroll") for (int k = 0; k < 2; ++k) dst[m][k] = *(const LAS bf16x8*)(lds + PG8_SA(b, h) + aoff + m * 2048 + k * 1024); } while (0)
; #define PG8_LDB(dst, b, h) do { _Pragma("unroll") for (int n = 0; n < 2; ++n) _Pragma("unroll") for (int k = 0; k < 2; ++k) dst[n][k] = *(const LAS bf16x8*)(lds + PG8_SB(b, h) + boff + n * 2048 + k * 1024); } while (0)
; #define PG8_MMA(ai, bj, At, Bt) do { __builtin_amdgcn_s_setprio(1); _Pragma("unroll") for (int m = 0; m < 4; ++m) _Pragma("unroll") for (int n = 0; n < 2; ++n) _Pragma("unroll") for (int k = 0; k < 2; ++k) \
;         acc[ai][bj][m][n] = __builtin_amdgcn_mfma_f32_16x16x32_bf16(Bt[n][k], At[m][k], acc[ai][bj][m][n], 0, 0, 0); __builtin_amdgcn_s_setprio(0); } while (0)
; #define PG8_WAIT_V(n) asm volatile("s_waitcnt vmcnt(" #n ")" ::: "memory")
; #define PG8_WAIT_L(n) asm volatile("s_waitcnt lgkmcnt(" #n ")" ::: "memory")
; #define PG8_BAR __builtin_amdgcn_s_barrier()
; #define PG8_SCHED __builtin_amdgcn_sched_barrier(0)
; template <class Epi, bool ALIGN_EPI>
; DI void gemm_phase(lptr lds, const Gemm g, const StaticOrder& S, const Epi& E) {
;     ...
;             PG8_WAIT_V(8); PG8_WAIT_L(0); PG8_BAR; PG8_MMA(1, 0, At, B0); PG8_MMA(1, 1, At, B1); PG8_BAR; PG8_SCHED;
;             PG8_LDB(B0, 1, 0); PG8_LDB(B1, 1, 1); PG8_SCHED; PG8_LDA(At, 1, 0); PG8_STAGE(PG8_SA(0, 1), a2 + hstepA, voffA);
;             PG8_WAIT_V(8); PG8_WAIT_L(0); PG8_BAR; PG8_MMA(0, 0, At, B0); PG8_MMA(0, 1, At, B1); PG8_BAR; PG8_SCHED;
;             PG8_LDA(At, 1, 1); PG8_STAGE(PG8_SB(1, 0), b3, voffB); PG8_STAGE(PG8_SB(1, 1), b3 + hstepB, voffB); PG8_STAGE(PG8_SA(1, 0), a3, voffA);
	s_setprio 1
	s_waitcnt lgkmcnt(0)
	v_mfma_f32_16x16x32_bf16 v[60:63], v[158:161], v[196:199], v[60:63]
	v_mfma_f32_16x16x32_bf16 v[56:59], v[172:175], v[196:199], v[56:59]
	v_mfma_f32_16x16x32_bf16 v[48:51], v[158:161], v[204:207], v[48:51]
	v_mfma_f32_16x16x32_bf16 v[40:43], v[172:175], v[204:207], v[40:43]
	v_mfma_f32_16x16x32_bf16 v[32:35], v[158:161], v[212:215], v[32:35]
	v_mfma_f32_16x16x32_bf16 v[24:27], v[172:175], v[212:215], v[24:27]
	v_mfma_f32_16x16x32_bf16 v[16:19], v[158:161], v[220:223], v[16:19]
	v_mfma_f32_16x16x32_bf16 v[8:11], v[172:175], v[220:223], v[8:11]
	v_mfma_f32_16x16x32_bf16 v[60:63], v[168:171], v[200:203], v[60:63]
	v_mfma_f32_16x16x32_bf16 v[56:59], v[176:179], v[200:203], v[56:59]
	v_mfma_f32_16x16x32_bf16 v[48:51], v[168:171], v[208:211], v[48:51]
	v_mfma_f32_16x16x32_bf16 v[40:43], v[176:179], v[208:211], v[40:43]
	v_mfma_f32_16x16x32_bf16 v[32:35], v[168:171], v[216:219], v[32:35]
	v_mfma_f32_16x16x32_bf16 v[24:27], v[176:179], v[216:219], v[24:27]
	v_mfma_f32_16x16x32_bf16 v[16:19], v[168:171], v[224:227], v[16:19]
	v_mfma_f32_16x16x32_bf16 v[8:11], v[176:179], v[224:227], v[8:11]
	s_setprio 0
	s_setprio 1
	v_mfma_f32_16x16x32_bf16 v[52:55], v[180:183], v[196:199], v[52:55]
	v_mfma_f32_16x16x32_bf16 v[44:47], v[188:191], v[196:199], v[44:47]
	v_mfma_f32_16x16x32_bf16 v[36:39], v[180:183], v[204:207], v[36:39]
	v_mfma_f32_16x16x32_bf16 v[28:31], v[188:191], v[204:207], v[28:31]
	v_mfma_f32_16x16x32_bf16 v[20:23], v[180:183], v[212:215], v[20:23]
	v_mfma_f32_16x16x32_bf16 v[12:15], v[188:191], v[212:215], v[12:15]
	v_mfma_f32_16x16x32_bf16 v[4:7], v[180:183], v[220:223], v[4:7]
	v_mfma_f32_16x16x32_bf16 v[0:3], v[188:191], v[220:223], v[0:3]
	v_mfma_f32_16x16x32_bf16 v[52:55], v[184:187], v[200:203], v[52:55]
	v_mfma_f32_16x16x32_bf16 v[44:47], v[192:195], v[200:203], v[44:47]
	v_mfma_f32_16x16x32_bf16 v[36:39], v[184:187], v[208:211], v[36:39]
	v_mfma_f32_16x16x32_bf16 v[28:31], v[192:195], v[208:211], v[28:31]
	v_mfma_f32_16x16x32_bf16 v[20:23], v[184:187], v[216:219], v[20:23]
	v_mfma_f32_16x16x32_bf16 v[12:15], v[192:195], v[216:219], v[12:15]
	v_mfma_f32_16x16x32_bf16 v[4:7], v[184:187], v[224:227], v[4:7]
	v_mfma_f32_16x16x32_bf16 v[0:3], v[192:195], v[224:227], v[0:3]
	s_setprio 0
	s_barrier
	s_add_i32 s56, 0, 0x18000
	v_add_u32_e32 v136, s56, v151
	s_add_i32 s57, 0, 0x1c000
	ds_read_b128 v[158:161], v136
	ds_read_b128 v[168:171], v136 offset:1024
	ds_read_b128 v[172:175], v136 offset:2048
	ds_read_b128 v[176:179], v136 offset:3072
	v_add_u32_e32 v136, s57, v151
	ds_read_b128 v[180:183], v136
	ds_read_b128 v[184:187], v136 offset:1024
	ds_read_b128 v[188:191], v136 offset:2048
	ds_read_b128 v[192:195], v136 offset:3072
	s_add_u32 s26, s26, 0x40000
	s_addc_u32 s27, s27, 0
	s_mov_b32 m0, s38
	v_lshl_add_u64 v[230:231], s[26:27], 0, v[128:129]
	ds_read_b128 v[196:199], v167 offset:32768
	ds_read_b128 v[200:203], v167 offset:33792
	ds_read_b128 v[204:207], v167 offset:34816
	ds_read_b128 v[208:211], v167 offset:35840
	ds_read_b128 v[212:215], v167 offset:36864
	ds_read_b128 v[216:219], v167 offset:37888
	ds_read_b128 v[220:223], v167 offset:38912
	ds_read_b128 v[224:227], v167 offset:39936
	global_load_lds_dwordx4 v[230:231], off
	v_lshl_add_u64 v[230:231], s[26:27], 0, v[132:133]
	s_mov_b32 m0, s39
	s_nop 0
	global_load_lds_dwordx4 v[230:231], off
	s_waitcnt vmcnt(8)
	s_waitcnt lgkmcnt(0)
	s_barrier
	s_setprio 1
	s_waitcnt lgkmcnt(0)
	v_mfma_f32_16x16x32_bf16 v[124:127], v[158:161], v[196:199], v[124:127]
	v_mfma_f32_16x16x32_bf16 v[120:123], v[172:175], v[196:199], v[120:123]
	v_mfma_f32_16x16x32_bf16 v[116:119], v[158:161], v[204:207], v[116:119]
	v_mfma_f32_16x16x32_bf16 v[112:115], v[172:175], v[204:207], v[112:115]
	v_mfma_f32_16x16x32_bf16 v[96:99], v[158:161], v[212:215], v[96:99]
	v_mfma_f32_16x16x32_bf16 v[88:91], v[172:175], v[212:215], v[88:91]
	v_mfma_f32_16x16x32_bf16 v[80:83], v[158:161], v[220:223], v[80:83]
	v_mfma_f32_16x16x32_bf16 v[72:75], v[172:175], v[220:223], v[72:75]
	v_mfma_f32_16x16x32_bf16 v[124:127], v[168:171], v[200:203], v[124:127]
	v_mfma_f32_16x16x32_bf16 v[120:123], v[176:179], v[200:203], v[120:123]
	v_mfma_f32_16x16x32_bf16 v[116:119], v[168:171], v[208:211], v[116:119]
	v_mfma_f32_16x16x32_bf16 v[112:115], v[176:179], v[208:211], v[112:115]
	v_mfma_f32_16x16x32_bf16 v[96:99], v[168:171], v[216:219], v[96:99]
	v_mfma_f32_16x16x32_bf16 v[88:91], v[176:179], v[216:219], v[88:91]
	v_mfma_f32_16x16x32_bf16 v[80:83], v[168:171], v[224:227], v[80:83]
	v_mfma_f32_16x16x32_bf16 v[72:75], v[176:179], v[224:227], v[72:75]
	s_setprio 0
	s_setprio 1
	v_mfma_f32_16x16x32_bf16 v[108:111], v[180:183], v[196:199], v[108:111]
	v_mfma_f32_16x16x32_bf16 v[104:107], v[188:191], v[196:199], v[104:107]
	v_mfma_f32_16x16x32_bf16 v[100:103], v[180:183], v[204:207], v[100:103]
	v_mfma_f32_16x16x32_bf16 v[92:95], v[188:191], v[204:207], v[92:95]
	v_mfma_f32_16x16x32_bf16 v[84:87], v[180:183], v[212:215], v[84:87]
	v_mfma_f32_16x16x32_bf16 v[76:79], v[188:191], v[212:215], v[76:79]
	v_mfma_f32_16x16x32_bf16 v[68:71], v[180:183], v[220:223], v[68:71]
	v_mfma_f32_16x16x32_bf16 v[64:67], v[188:191], v[220:223], v[64:67]
	v_mfma_f32_16x16x32_bf16 v[108:111], v[184:187], v[200:203], v[108:111]
	v_mfma_f32_16x16x32_bf16 v[104:107], v[192:195], v[200:203], v[104:107]
	v_mfma_f32_16x16x32_bf16 v[100:103], v[184:187], v[208:211], v[100:103]
	v_mfma_f32_16x16x32_bf16 v[92:95], v[192:195], v[208:211], v[92:95]
	v_mfma_f32_16x16x32_bf16 v[84:87], v[184:187], v[216:219], v[84:87]
	v_mfma_f32_16x16x32_bf16 v[76:79], v[192:195], v[216:219], v[76:79]
	v_mfma_f32_16x16x32_bf16 v[68:71], v[184:187], v[224:227], v[68:71]
	v_mfma_f32_16x16x32_bf16 v[64:67], v[192:195], v[224:227], v[64:67]
	s_setprio 0
	s_barrier
; #define PG8_STAGE(bufoff, gbase, voff) do { _Pragma("unroll") for (int _i = 0; _i < 2; ++_i) \
;         __builtin_amdgcn_global_load_lds((const unsigned*)((const char*)(gbase) + (voff)[_i]), (LAS unsigned*)(lds + (bufoff) + ldsw + _i * 8192), 16, 0, 0); } while (0)
; #define PG8_LDA(dst, b, h) do { _Pragma("unroll") for (int m = 0; m < 4; ++m) _Pragma("unroll") for (int k = 0; k < 2; ++k) dst[m][k] = *(const LAS bf16x8*)(lds + PG8_SA(b, h) + aoff + m * 2048 + k * 1024); } while (0)
; #define PG8_MMA(ai, bj, At, Bt) do { __builtin_amdgcn_s_setprio(1); _Pragma("unroll") for (int m = 0; m < 4; ++m) _Pragma("unroll") for (int n = 0; n < 2; ++n) _Pragma("unroll") for (int k = 0; k < 2; ++k) \
;         acc[ai][bj][m][n] = __builtin_amdgcn_mfma_f32_16x16x32_bf16(Bt[n][k], At[m][k], acc[ai][bj][m][n], 0, 0, 0); __builtin_amdgcn_s_setprio(0); } while (0)
; #define PG8_WAIT_V(n) asm volatile("s_waitcnt vmcnt(" #n ")" ::: "memory")
; #define PG8_WAIT_L(n) asm volatile("s_waitcnt lgkmcnt(" #n ")" ::: "memory")
; #define PG8_BAR __builtin_amdgcn_s_barrier()
; #define PG8_SCHED __builtin_amdgcn_sched_barrier(0)
; template <class Epi, bool ALIGN_EPI>
; DI void gemm_phase(lptr lds, const Gemm g, const StaticOrder& S, const Epi& E) {
;     ...
;         for (int t = 0; t < nt; t += 2) {
;             const bool last = (t == nt - 2);
;     ...
;             PG8_LDA(At, 1, 1); PG8_STAGE(PG8_SB(1, 0), b3, voffB); PG8_STAGE(PG8_SB(1, 1), b3 + hstepB, voffB); PG8_STAGE(PG8_SA(1, 0), a3, voffA);
;             PG8_WAIT_V(8); PG8_WAIT_L(0); PG8_BAR; PG8_MMA(1, 0, At, B0); PG8_MMA(1, 1, At, B1); PG8_BAR; PG8_SCHED;
;         }
	s_add_i32 s26, s56, s35
	v_lshl_add_u64 v[148:149], v[148:149], 0, s[10:11]
	s_mov_b32 m0, s26
	ds_read_b128 v[196:199], v167 offset:49152
	ds_read_b128 v[200:203], v167 offset:50176
	ds_read_b128 v[204:207], v167 offset:51200
	ds_read_b128 v[208:211], v167 offset:52224
	ds_read_b128 v[212:215], v167 offset:53248
	ds_read_b128 v[216:219], v167 offset:54272
	ds_read_b128 v[220:223], v167 offset:55296
	ds_read_b128 v[224:227], v167 offset:56320
	global_load_lds_dwordx4 v[148:149], off
	s_add_i32 m0, s26, 0x2000
	s_add_u32 s24, s24, 0x40080
	v_lshl_add_u64 v[148:149], v[154:155], 0, s[10:11]
	s_addc_u32 s25, s25, 0
	s_add_i32 s26, s57, s35
	global_load_lds_dwordx4 v[148:149], off
	v_lshl_add_u64 v[148:149], s[24:25], 0, v[130:131]
	s_mov_b32 m0, s26
	s_nop 0
	global_load_lds_dwordx4 v[148:149], off
	v_lshl_add_u64 v[148:149], s[24:25], 0, v[134:135]
	s_add_i32 m0, s26, 0x2000
	s_nop 0
	global_load_lds_dwordx4 v[148:149], off
	v_lshl_add_u64 v[148:149], v[164:165], 0, s[10:11]
	s_mov_b32 m0, s41
	s_nop 0
	global_load_lds_dwordx4 v[148:149], off
	v_lshl_add_u64 v[148:149], v[228:229], 0, s[10:11]
	s_mov_b32 m0, s42
	s_nop 0
	global_load_lds_dwordx4 v[148:149], off
	s_waitcnt vmcnt(8)
	s_waitcnt lgkmcnt(0)
	s_barrier
	s_setprio 1
	s_waitcnt lgkmcnt(0)
	v_mfma_f32_16x16x32_bf16 v[60:63], v[158:161], v[196:199], v[60:63]
	v_mfma_f32_16x16x32_bf16 v[56:59], v[172:175], v[196:199], v[56:59]
	v_mfma_f32_16x16x32_bf16 v[48:51], v[158:161], v[204:207], v[48:51]
	v_mfma_f32_16x16x32_bf16 v[40:43], v[172:175], v[204:207], v[40:43]
	v_mfma_f32_16x16x32_bf16 v[32:35], v[158:161], v[212:215], v[32:35]
	v_mfma_f32_16x16x32_bf16 v[24:27], v[172:175], v[212:215], v[24:27]
	v_mfma_f32_16x16x32_bf16 v[16:19], v[158:161], v[220:223], v[16:19]
	v_mfma_f32_16x16x32_bf16 v[8:11], v[172:175], v[220:223], v[8:11]
	v_mfma_f32_16x16x32_bf16 v[60:63], v[168:171], v[200:203], v[60:63]
	v_mfma_f32_16x16x32_bf16 v[56:59], v[176:179], v[200:203], v[56:59]
	v_mfma_f32_16x16x32_bf16 v[48:51], v[168:171], v[208:211], v[48:51]
	v_mfma_f32_16x16x32_bf16 v[40:43], v[176:179], v[208:211], v[40:43]
	v_mfma_f32_16x16x32_bf16 v[32:35], v[168:171], v[216:219], v[32:35]
	v_mfma_f32_16x16x32_bf16 v[24:27], v[176:179], v[216:219], v[24:27]
	v_mfma_f32_16x16x32_bf16 v[16:19], v[168:171], v[224:227], v[16:19]
	v_mfma_f32_16x16x32_bf16 v[8:11], v[176:179], v[224:227], v[8:11]
	s_setprio 0
	s_setprio 1
	v_mfma_f32_16x16x32_bf16 v[52:55], v[180:183], v[196:199], v[52:55]
	v_mfma_f32_16x16x32_bf16 v[44:47], v[188:191], v[196:199], v[44:47]
	v_mfma_f32_16x16x32_bf16 v[36:39], v[180:183], v[204:207], v[36:39]
	v_mfma_f32_16x16x32_bf16 v[28:31], v[188:191], v[204:207], v[28:31]
	v_mfma_f32_16x16x32_bf16 v[20:23], v[180:183], v[212:215], v[20:23]
	v_mfma_f32_16x16x32_bf16 v[12:15], v[188:191], v[212:215], v[12:15]
	v_mfma_f32_16x16x32_bf16 v[4:7], v[180:183], v[220:223], v[4:7]
	v_mfma_f32_16x16x32_bf16 v[0:3], v[188:191], v[220:223], v[0:3]
	v_mfma_f32_16x16x32_bf16 v[52:55], v[184:187], v[200:203], v[52:55]
	v_mfma_f32_16x16x32_bf16 v[44:47], v[192:195], v[200:203], v[44:47]
	v_mfma_f32_16x16x32_bf16 v[36:39], v[184:187], v[208:211], v[36:39]
	v_mfma_f32_16x16x32_bf16 v[28:31], v[192:195], v[208:211], v[28:31]
	v_mfma_f32_16x16x32_bf16 v[20:23], v[184:187], v[216:219], v[20:23]
	v_mfma_f32_16x16x32_bf16 v[12:15], v[192:195], v[216:219], v[12:15]
	v_mfma_f32_16x16x32_bf16 v[4:7], v[184:187], v[224:227], v[4:7]
	v_mfma_f32_16x16x32_bf16 v[0:3], v[192:195], v[224:227], v[0:3]
	s_setprio 0
	s_add_i32 s55, s55, 2
	s_add_u32 s22, s22, 0x100
	s_addc_u32 s23, s23, 0
	s_add_u32 s53, s53, 0x100
	s_addc_u32 s54, s54, 0
	s_cmp_gt_u32 s55, 13
	s_barrier
	s_cbranch_scc0 .LBB0_455
	s_and_b64 vcc, exec, s[12:13]
	s_cbranch_vccz .LBB0_458
	s_barrier

; #define PG8_STAGE(bufoff, gbase, voff) do { _Pragma("unroll") for (int _i = 0; _i < 2; ++_i) \
;         __builtin_amdgcn_global_load_lds((const unsigned*)((const char*)(gbase) + (voff)[_i]), (LAS unsigned*)(lds + (bufoff) + ldsw + _i * 8192), 16, 0, 0); } while (0)
; #define PG8_LDA(dst, b, h) do { _Pragma("unroll") for (int m = 0; m < 4; ++m) _Pragma("unroll") for (int k = 0; k < 2; ++k) dst[m][k] = *(const LAS bf16x8*)(lds + PG8_SA(b, h) + aoff + m * 2048 + k * 1024); } while (0)
; #define PG8_LDB(dst, b, h) do { _Pragma("unroll") for (int n = 0; n < 2; ++n) _Pragma("unroll") for (int k = 0; k < 2; ++k) dst[n][k] = *(const LAS bf16x8*)(lds + PG8_SB(b, h) + boff + n * 2048 + k * 1024); } while (0)
; #define PG8_MMA(ai, bj, At, Bt) do { __builtin_amdgcn_s_setprio(1); _Pragma("unroll") for (int m = 0; m < 4; ++m) _Pragma("unroll") for (int n = 0; n < 2; ++n) _Pragma("unroll") for (int k = 0; k < 2; ++k) \
;         acc[ai][bj][m][n] = __builtin_amdgcn_mfma_f32_16x16x32_bf16(Bt[n][k], At[m][k], acc[ai][bj][m][n], 0, 0, 0); __builtin_amdgcn_s_setprio(0); } while (0)
; #define PG8_WAIT_V(n) asm volatile("s_waitcnt vmcnt(" #n ")" ::: "memory")
; #define PG8_WAIT_L(n) asm volatile("s_waitcnt lgkmcnt(" #n ")" ::: "memory")
; #define PG8_BAR __builtin_amdgcn_s_barrier()
; #define PG8_SCHED __builtin_amdgcn_sched_barrier(0)
; template <class Epi, bool ALIGN_EPI>
; DI void gemm_phase(lptr lds, const Gemm g, const StaticOrder& S, const Epi& E) {
;     ...
;             const char* a1 = cA + (size_t)(t + 1) * kstep;
;             const char* a2 = last ? nA : cA + (size_t)(t + 2) * kstep; const char* b2 = last ? nB : cB + (size_t)(t + 2) * kstep;
;             const char* a3 = a2 + kstep; const char* b3 = b2 + kstep;
;             PG8_LDB(B0, 0, 0); PG8_LDB(B1, 0, 1); PG8_SCHED; PG8_LDA(At, 0, 0); PG8_STAGE(PG8_SA(1, 1), a1 + hstepA, voffA);
;             PG8_WAIT_V(8); PG8_WAIT_L(0); PG8_BAR; PG8_MMA(0, 0, At, B0); PG8_MMA(0, 1, At, B1); PG8_BAR; PG8_SCHED;
;             PG8_LDA(At, 0, 1); PG8_STAGE(PG8_SB(0, 0), b2, voffB); PG8_STAGE(PG8_SB(0, 1), b2 + hstepB, voffB); PG8_STAGE(PG8_SA(0, 0), a2, voffA);
;             PG8_WAIT_V(8); PG8_WAIT_L(0); PG8_BAR; PG8_MMA(1, 0, At, B0); PG8_MMA(1, 1, At, B1); PG8_BAR; PG8_SCHED;
.LBB0_705:
	ds_read_b128 v[128:131], v171
	ds_read_b128 v[132:135], v171 offset:1024
	ds_read_b128 v[136:139], v171 offset:2048
	ds_read_b128 v[148:151], v171 offset:3072
	ds_read_b128 v[162:165], v172
	ds_read_b128 v[188:191], v172 offset:1024
	ds_read_b128 v[192:195], v172 offset:2048
	ds_read_b128 v[196:199], v172 offset:3072
	s_add_u32 s26, s24, 0xfffc0080
	s_addc_u32 s27, s25, -1
	s_cmp_eq_u32 s53, 12
	s_cselect_b32 s29, s19, s27
	s_cselect_b32 s28, s49, s26
	s_cselect_b32 s27, s17, s52
	s_cselect_b32 s26, s50, s51
	v_lshl_add_u64 v[166:167], s[24:25], 0, v[140:141]
	s_add_i32 m0, s36, 0xc000
	ds_read_b128 v[200:203], v173
	ds_read_b128 v[204:207], v173 offset:1024
	ds_read_b128 v[208:211], v173 offset:2048
	ds_read_b128 v[212:215], v173 offset:3072
	ds_read_b128 v[216:219], v173 offset:4096
	ds_read_b128 v[220:223], v173 offset:5120
	ds_read_b128 v[224:227], v173 offset:6144
	ds_read_b128 v[228:231], v173 offset:7168
	global_load_lds_dwordx4 v[166:167], off
	v_lshl_add_u64 v[166:167], s[24:25], 0, v[142:143]
	s_add_i32 m0, s36, 0xe000
	s_nop 0
	global_load_lds_dwordx4 v[166:167], off
	s_waitcnt vmcnt(8)
	s_waitcnt lgkmcnt(0)
	s_barrier
	s_setprio 1
	s_waitcnt lgkmcnt(0)
	v_mfma_f32_16x16x32_bf16 v[124:127], v[128:131], v[200:203], v[124:127]
	v_mfma_f32_16x16x32_bf16 v[120:123], v[136:139], v[200:203], v[120:123]
	v_mfma_f32_16x16x32_bf16 v[116:119], v[128:131], v[208:211], v[116:119]
	v_mfma_f32_16x16x32_bf16 v[112:115], v[136:139], v[208:211], v[112:115]
	v_mfma_f32_16x16x32_bf16 v[92:95], v[128:131], v[216:219], v[92:95]
	v_mfma_f32_16x16x32_bf16 v[88:91], v[136:139], v[216:219], v[88:91]
	v_mfma_f32_16x16x32_bf16 v[84:87], v[128:131], v[224:227], v[84:87]
	v_mfma_f32_16x16x32_bf16 v[76:79], v[136:139], v[224:227], v[76:79]
	v_mfma_f32_16x16x32_bf16 v[124:127], v[132:135], v[204:207], v[124:127]
	v_mfma_f32_16x16x32_bf16 v[120:123], v[148:151], v[204:207], v[120:123]
	v_mfma_f32_16x16x32_bf16 v[116:119], v[132:135], v[212:215], v[116:119]
	v_mfma_f32_16x16x32_bf16 v[112:115], v[148:151], v[212:215], v[112:115]
	v_mfma_f32_16x16x32_bf16 v[92:95], v[132:135], v[220:223], v[92:95]
	v_mfma_f32_16x16x32_bf16 v[88:91], v[148:151], v[220:223], v[88:91]
	v_mfma_f32_16x16x32_bf16 v[84:87], v[132:135], v[228:231], v[84:87]
	v_mfma_f32_16x16x32_bf16 v[76:79], v[148:151], v[228:231], v[76:79]
	s_setprio 0
	s_setprio 1
	v_mfma_f32_16x16x32_bf16 v[108:111], v[162:165], v[200:203], v[108:111]
	v_mfma_f32_16x16x32_bf16 v[104:107], v[192:195], v[200:203], v[104:107]
	v_mfma_f32_16x16x32_bf16 v[100:103], v[162:165], v[208:211], v[100:103]
	v_mfma_f32_16x16x32_bf16 v[96:99], v[192:195], v[208:211], v[96:99]
	v_mfma_f32_16x16x32_bf16 v[80:83], v[162:165], v[216:219], v[80:83]
	v_mfma_f32_16x16x32_bf16 v[72:75], v[192:195], v[216:219], v[72:75]
	v_mfma_f32_16x16x32_bf16 v[68:71], v[162:165], v[224:227], v[68:71]
	v_mfma_f32_16x16x32_bf16 v[64:67], v[192:195], v[224:227], v[64:67]
	v_mfma_f32_16x16x32_bf16 v[108:111], v[188:191], v[204:207], v[108:111]
	v_mfma_f32_16x16x32_bf16 v[104:107], v[196:199], v[204:207], v[104:107]
	v_mfma_f32_16x16x32_bf16 v[100:103], v[188:191], v[212:215], v[100:103]
	v_mfma_f32_16x16x32_bf16 v[96:99], v[196:199], v[212:215], v[96:99]
	v_mfma_f32_16x16x32_bf16 v[80:83], v[188:191], v[220:223], v[80:83]
	v_mfma_f32_16x16x32_bf16 v[72:75], v[196:199], v[220:223], v[72:75]
	v_mfma_f32_16x16x32_bf16 v[68:71], v[188:191], v[228:231], v[68:71]
	v_mfma_f32_16x16x32_bf16 v[64:67], v[196:199], v[228:231], v[64:67]
	s_setprio 0
	s_barrier
	s_add_i32 s54, s43, s35
	v_lshl_add_u64 v[166:167], s[26:27], 0, v[156:157]
	s_mov_b32 m0, s54
	ds_read_b128 v[200:203], v173 offset:16384
	ds_read_b128 v[204:207], v173 offset:17408
	ds_read_b128 v[208:211], v173 offset:18432
	ds_read_b128 v[212:215], v173 offset:19456
	ds_read_b128 v[216:219], v173 offset:20480
	ds_read_b128 v[220:223], v173 offset:21504
	ds_read_b128 v[224:227], v173 offset:22528
	ds_read_b128 v[228:231], v173 offset:23552
	global_load_lds_dwordx4 v[166:167], off
	s_add_i32 m0, s54, 0x2000
	s_add_u32 s54, s26, 0x40000
	v_lshl_add_u64 v[174:175], s[26:27], 0, v[160:161]
	s_addc_u32 s55, s27, 0
	s_add_i32 s56, s44, s35
	global_load_lds_dwordx4 v[174:175], off
	v_lshl_add_u64 v[232:233], s[54:55], 0, v[156:157]
	s_mov_b32 m0, s56
	v_lshl_add_u64 v[234:235], s[28:29], 0, v[158:159]
	global_load_lds_dwordx4 v[232:233], off
	v_lshl_add_u64 v[232:233], s[54:55], 0, v[160:161]
	s_add_i32 m0, s56, 0x2000
	s_nop 0
	global_load_lds_dwordx4 v[232:233], off
	v_lshl_add_u64 v[232:233], s[28:29], 0, v[154:155]
	s_mov_b32 m0, s36
	s_nop 0
	global_load_lds_dwordx4 v[232:233], off
	s_mov_b32 m0, s33
	s_nop 0
	global_load_lds_dwordx4 v[234:235], off
	s_waitcnt vmcnt(8)
	s_waitcnt lgkmcnt(0)
	s_barrier
; #define PG8_STAGE(bufoff, gbase, voff) do { _Pragma("unroll") for (int _i = 0; _i < 2; ++_i) \
;         __builtin_amdgcn_global_load_lds((const unsigned*)((const char*)(gbase) + (voff)[_i]), (LAS unsigned*)(lds + (bufoff) + ldsw + _i * 8192), 16, 0, 0); } while (0)
; #define PG8_LDA(dst, b, h) do { _Pragma("unroll") for (int m = 0; m < 4; ++m) _Pragma("unroll") for (int k = 0; k < 2; ++k) dst[m][k] = *(const LAS bf16x8*)(lds + PG8_SA(b, h) + aoff + m * 2048 + k * 1024); } while (0)
; #define PG8_LDB(dst, b, h) do { _Pragma("unroll") for (int n = 0; n < 2; ++n) _Pragma("unroll") for (int k = 0; k < 2; ++k) dst[n][k] = *(const LAS bf16x8*)(lds + PG8_SB(b, h) + boff + n * 2048 + k * 1024); } while (0)
; #define PG8_MMA(ai, bj, At, Bt) do { __builtin_amdgcn_s_setprio(1); _Pragma("unroll") for (int m = 0; m < 4; ++m) _Pragma("unroll") for (int n = 0; n < 2; ++n) _Pragma("unroll") for (int k = 0; k < 2; ++k) \
;         acc[ai][bj][m][n] = __builtin_amdgcn_mfma_f32_16x16x32_bf16(Bt[n][k], At[m][k], acc[ai][bj][m][n], 0, 0, 0); __builtin_amdgcn_s_setprio(0); } while (0)
; #define PG8_WAIT_V(n) asm volatile("s_waitcnt vmcnt(" #n ")" ::: "memory")
; #define PG8_WAIT_L(n) asm volatile("s_waitcnt lgkmcnt(" #n ")" ::: "memory")
; #define PG8_BAR __builtin_amdgcn_s_barrier()
; #define PG8_SCHED __builtin_amdgcn_sched_barrier(0)
; template <class Epi, bool ALIGN_EPI>
; DI void gemm_phase(lptr lds, const Gemm g, const StaticOrder& S, const Epi& E) {
;     ...
;             PG8_WAIT_V(8); PG8_WAIT_L(0); PG8_BAR; PG8_MMA(1, 0, At, B0); PG8_MMA(1, 1, At, B1); PG8_BAR; PG8_SCHED;
;             PG8_LDB(B0, 1, 0); PG8_LDB(B1, 1, 1); PG8_SCHED; PG8_LDA(At, 1, 0); PG8_STAGE(PG8_SA(0, 1), a2 + hstepA, voffA);
;             PG8_WAIT_V(8); PG8_WAIT_L(0); PG8_BAR; PG8_MMA(0, 0, At, B0); PG8_MMA(0, 1, At, B1); PG8_BAR; PG8_SCHED;
;             PG8_LDA(At, 1, 1); PG8_STAGE(PG8_SB(1, 0), b3, voffB); PG8_STAGE(PG8_SB(1, 1), b3 + hstepB, voffB); PG8_STAGE(PG8_SA(1, 0), a3, voffA);
	s_setprio 1
	s_waitcnt lgkmcnt(0)
	v_mfma_f32_16x16x32_bf16 v[60:63], v[128:131], v[200:203], v[60:63]
	v_mfma_f32_16x16x32_bf16 v[56:59], v[136:139], v[200:203], v[56:59]
	v_mfma_f32_16x16x32_bf16 v[44:47], v[128:131], v[208:211], v[44:47]
	v_mfma_f32_16x16x32_bf16 v[40:43], v[136:139], v[208:211], v[40:43]
	v_mfma_f32_16x16x32_bf16 v[28:31], v[128:131], v[216:219], v[28:31]
	v_mfma_f32_16x16x32_bf16 v[24:27], v[136:139], v[216:219], v[24:27]
	v_mfma_f32_16x16x32_bf16 v[12:15], v[128:131], v[224:227], v[12:15]
	v_mfma_f32_16x16x32_bf16 v[8:11], v[136:139], v[224:227], v[8:11]
	v_mfma_f32_16x16x32_bf16 v[60:63], v[132:135], v[204:207], v[60:63]
	v_mfma_f32_16x16x32_bf16 v[56:59], v[148:151], v[204:207], v[56:59]
	v_mfma_f32_16x16x32_bf16 v[44:47], v[132:135], v[212:215], v[44:47]
	v_mfma_f32_16x16x32_bf16 v[40:43], v[148:151], v[212:215], v[40:43]
	v_mfma_f32_16x16x32_bf16 v[28:31], v[132:135], v[220:223], v[28:31]
	v_mfma_f32_16x16x32_bf16 v[24:27], v[148:151], v[220:223], v[24:27]
	v_mfma_f32_16x16x32_bf16 v[12:15], v[132:135], v[228:231], v[12:15]
	v_mfma_f32_16x16x32_bf16 v[8:11], v[148:151], v[228:231], v[8:11]
	s_setprio 0
	s_setprio 1
	v_mfma_f32_16x16x32_bf16 v[52:55], v[162:165], v[200:203], v[52:55]
	v_mfma_f32_16x16x32_bf16 v[48:51], v[192:195], v[200:203], v[48:51]
	v_mfma_f32_16x16x32_bf16 v[36:39], v[162:165], v[208:211], v[36:39]
	v_mfma_f32_16x16x32_bf16 v[32:35], v[192:195], v[208:211], v[32:35]
	v_mfma_f32_16x16x32_bf16 v[20:23], v[162:165], v[216:219], v[20:23]
	v_mfma_f32_16x16x32_bf16 v[16:19], v[192:195], v[216:219], v[16:19]
	v_mfma_f32_16x16x32_bf16 v[4:7], v[162:165], v[224:227], v[4:7]
	v_mfma_f32_16x16x32_bf16 v[0:3], v[192:195], v[224:227], v[0:3]
	v_mfma_f32_16x16x32_bf16 v[52:55], v[188:191], v[204:207], v[52:55]
	v_mfma_f32_16x16x32_bf16 v[48:51], v[196:199], v[204:207], v[48:51]
	v_mfma_f32_16x16x32_bf16 v[36:39], v[188:191], v[212:215], v[36:39]
	v_mfma_f32_16x16x32_bf16 v[32:35], v[196:199], v[212:215], v[32:35]
	v_mfma_f32_16x16x32_bf16 v[20:23], v[188:191], v[220:223], v[20:23]
	v_mfma_f32_16x16x32_bf16 v[16:19], v[196:199], v[220:223], v[16:19]
	v_mfma_f32_16x16x32_bf16 v[4:7], v[188:191], v[228:231], v[4:7]
	v_mfma_f32_16x16x32_bf16 v[0:3], v[196:199], v[228:231], v[0:3]
	s_setprio 0
	s_barrier
	s_add_i32 s54, 0, 0x18000
	s_add_i32 s55, 0, 0x1c000
	v_add_u32_e32 v148, s54, v169
	v_add_u32_e32 v185, s55, v169
	ds_read_b128 v[128:131], v148
	ds_read_b128 v[132:135], v148 offset:1024
	ds_read_b128 v[136:139], v148 offset:2048
	ds_read_b128 v[148:151], v148 offset:3072
	ds_read_b128 v[162:165], v185
	ds_read_b128 v[188:191], v185 offset:1024
	ds_read_b128 v[192:195], v185 offset:2048
	ds_read_b128 v[196:199], v185 offset:3072
	s_add_u32 s28, s28, 0x40000
	s_addc_u32 s29, s29, 0
	s_mov_b32 m0, s37
	v_lshl_add_u64 v[236:237], s[28:29], 0, v[154:155]
	ds_read_b128 v[200:203], v173 offset:32768
	ds_read_b128 v[204:207], v173 offset:33792
	ds_read_b128 v[208:211], v173 offset:34816
	ds_read_b128 v[212:215], v173 offset:35840
	ds_read_b128 v[216:219], v173 offset:36864
	ds_read_b128 v[220:223], v173 offset:37888
	ds_read_b128 v[224:227], v173 offset:38912
	ds_read_b128 v[228:231], v173 offset:39936
	global_load_lds_dwordx4 v[236:237], off
	v_lshl_add_u64 v[236:237], s[28:29], 0, v[158:159]
	s_mov_b32 m0, s38
	s_nop 0
	global_load_lds_dwordx4 v[236:237], off
	s_waitcnt vmcnt(8)
	s_waitcnt lgkmcnt(0)
	s_barrier
	s_setprio 1
	s_waitcnt lgkmcnt(0)
	v_mfma_f32_16x16x32_bf16 v[124:127], v[128:131], v[200:203], v[124:127]
	v_mfma_f32_16x16x32_bf16 v[120:123], v[136:139], v[200:203], v[120:123]
	v_mfma_f32_16x16x32_bf16 v[116:119], v[128:131], v[208:211], v[116:119]
	v_mfma_f32_16x16x32_bf16 v[112:115], v[136:139], v[208:211], v[112:115]
	v_mfma_f32_16x16x32_bf16 v[92:95], v[128:131], v[216:219], v[92:95]
	v_mfma_f32_16x16x32_bf16 v[88:91], v[136:139], v[216:219], v[88:91]
	v_mfma_f32_16x16x32_bf16 v[84:87], v[128:131], v[224:227], v[84:87]
	v_mfma_f32_16x16x32_bf16 v[76:79], v[136:139], v[224:227], v[76:79]
	v_mfma_f32_16x16x32_bf16 v[124:127], v[132:135], v[204:207], v[124:127]
	v_mfma_f32_16x16x32_bf16 v[120:123], v[148:151], v[204:207], v[120:123]
	v_mfma_f32_16x16x32_bf16 v[116:119], v[132:135], v[212:215], v[116:119]
	v_mfma_f32_16x16x32_bf16 v[112:115], v[148:151], v[212:215], v[112:115]
	v_mfma_f32_16x16x32_bf16 v[92:95], v[132:135], v[220:223], v[92:95]
	v_mfma_f32_16x16x32_bf16 v[88:91], v[148:151], v[220:223], v[88:91]
	v_mfma_f32_16x16x32_bf16 v[84:87], v[132:135], v[228:231], v[84:87]
	v_mfma_f32_16x16x32_bf16 v[76:79], v[148:151], v[228:231], v[76:79]
	s_setprio 0
	s_setprio 1
	v_mfma_f32_16x16x32_bf16 v[108:111], v[162:165], v[200:203], v[108:111]
	v_mfma_f32_16x16x32_bf16 v[104:107], v[192:195], v[200:203], v[104:107]
	v_mfma_f32_16x16x32_bf16 v[100:103], v[162:165], v[208:211], v[100:103]
	v_mfma_f32_16x16x32_bf16 v[96:99], v[192:195], v[208:211], v[96:99]
	v_mfma_f32_16x16x32_bf16 v[80:83], v[162:165], v[216:219], v[80:83]
	v_mfma_f32_16x16x32_bf16 v[72:75], v[192:195], v[216:219], v[72:75]
	v_mfma_f32_16x16x32_bf16 v[68:71], v[162:165], v[224:227], v[68:71]
	v_mfma_f32_16x16x32_bf16 v[64:67], v[192:195], v[224:227], v[64:67]
	v_mfma_f32_16x16x32_bf16 v[108:111], v[188:191], v[204:207], v[108:111]
	v_mfma_f32_16x16x32_bf16 v[104:107], v[196:199], v[204:207], v[104:107]
	v_mfma_f32_16x16x32_bf16 v[100:103], v[188:191], v[212:215], v[100:103]
	v_mfma_f32_16x16x32_bf16 v[96:99], v[196:199], v[212:215], v[96:99]
	v_mfma_f32_16x16x32_bf16 v[80:83], v[188:191], v[220:223], v[80:83]
	v_mfma_f32_16x16x32_bf16 v[72:75], v[196:199], v[220:223], v[72:75]
	v_mfma_f32_16x16x32_bf16 v[68:71], v[188:191], v[228:231], v[68:71]
	v_mfma_f32_16x16x32_bf16 v[64:67], v[196:199], v[228:231], v[64:67]
	s_setprio 0
	s_barrier
; #define PG8_STAGE(bufoff, gbase, voff) do { _Pragma("unroll") for (int _i = 0; _i < 2; ++_i) \
;         __builtin_amdgcn_global_load_lds((const unsigned*)((const char*)(gbase) + (voff)[_i]), (LAS unsigned*)(lds + (bufoff) + ldsw + _i * 8192), 16, 0, 0); } while (0)
; #define PG8_LDA(dst, b, h) do { _Pragma("unroll") for (int m = 0; m < 4; ++m) _Pragma("unroll") for (int k = 0; k < 2; ++k) dst[m][k] = *(const LAS bf16x8*)(lds + PG8_SA(b, h) + aoff + m * 2048 + k * 1024); } while (0)
; #define PG8_MMA(ai, bj, At, Bt) do { __builtin_amdgcn_s_setprio(1); _Pragma("unroll") for (int m = 0; m < 4; ++m) _Pragma("unroll") for (int n = 0; n < 2; ++n) _Pragma("unroll") for (int k = 0; k < 2; ++k) \
;         acc[ai][bj][m][n] = __builtin_amdgcn_mfma_f32_16x16x32_bf16(Bt[n][k], At[m][k], acc[ai][bj][m][n], 0, 0, 0); __builtin_amdgcn_s_setprio(0); } while (0)
; #define PG8_WAIT_V(n) asm volatile("s_waitcnt vmcnt(" #n ")" ::: "memory")
; #define PG8_WAIT_L(n) asm volatile("s_waitcnt lgkmcnt(" #n ")" ::: "memory")
; #define PG8_BAR __builtin_amdgcn_s_barrier()
; #define PG8_SCHED __builtin_amdgcn_sched_barrier(0)
; template <class Epi, bool ALIGN_EPI>
; DI void gemm_phase(lptr lds, const Gemm g, const StaticOrder& S, const Epi& E) {
;     ...
;         for (int t = 0; t < nt; t += 2) {
;             const bool last = (t == nt - 2);
;     ...
;             PG8_LDA(At, 1, 1); PG8_STAGE(PG8_SB(1, 0), b3, voffB); PG8_STAGE(PG8_SB(1, 1), b3 + hstepB, voffB); PG8_STAGE(PG8_SA(1, 0), a3, voffA);
;             PG8_WAIT_V(8); PG8_WAIT_L(0); PG8_BAR; PG8_MMA(1, 0, At, B0); PG8_MMA(1, 1, At, B1); PG8_BAR; PG8_SCHED;
;         }
	s_add_i32 s28, s54, s35
	v_lshl_add_u64 v[166:167], v[166:167], 0, s[10:11]
	s_mov_b32 m0, s28
	ds_read_b128 v[200:203], v173 offset:49152
	ds_read_b128 v[204:207], v173 offset:50176
	ds_read_b128 v[208:211], v173 offset:51200
	ds_read_b128 v[212:215], v173 offset:52224
	ds_read_b128 v[216:219], v173 offset:53248
	ds_read_b128 v[220:223], v173 offset:54272
	ds_read_b128 v[224:227], v173 offset:55296
	ds_read_b128 v[228:231], v173 offset:56320
	global_load_lds_dwordx4 v[166:167], off
	s_add_i32 m0, s28, 0x2000
	s_add_u32 s26, s26, 0x40080
	v_lshl_add_u64 v[166:167], v[174:175], 0, s[10:11]
	s_addc_u32 s27, s27, 0
	s_add_i32 s28, s55, s35
	global_load_lds_dwordx4 v[166:167], off
	v_lshl_add_u64 v[166:167], s[26:27], 0, v[156:157]
	s_mov_b32 m0, s28
	s_nop 0
	global_load_lds_dwordx4 v[166:167], off
	v_lshl_add_u64 v[166:167], s[26:27], 0, v[160:161]
	s_add_i32 m0, s28, 0x2000
	s_nop 0
	global_load_lds_dwordx4 v[166:167], off
	v_lshl_add_u64 v[166:167], v[232:233], 0, s[10:11]
	s_mov_b32 m0, s40
	s_nop 0
	global_load_lds_dwordx4 v[166:167], off
	v_lshl_add_u64 v[166:167], v[234:235], 0, s[10:11]
	s_mov_b32 m0, s41
	s_nop 0
	global_load_lds_dwordx4 v[166:167], off
	s_waitcnt vmcnt(8)
	s_waitcnt lgkmcnt(0)
	s_barrier
	s_setprio 1
	s_waitcnt lgkmcnt(0)
	v_mfma_f32_16x16x32_bf16 v[60:63], v[128:131], v[200:203], v[60:63]
	v_mfma_f32_16x16x32_bf16 v[56:59], v[136:139], v[200:203], v[56:59]
	v_mfma_f32_16x16x32_bf16 v[44:47], v[128:131], v[208:211], v[44:47]
	v_mfma_f32_16x16x32_bf16 v[40:43], v[136:139], v[208:211], v[40:43]
	v_mfma_f32_16x16x32_bf16 v[28:31], v[128:131], v[216:219], v[28:31]
	v_mfma_f32_16x16x32_bf16 v[24:27], v[136:139], v[216:219], v[24:27]
	v_mfma_f32_16x16x32_bf16 v[12:15], v[128:131], v[224:227], v[12:15]
	v_mfma_f32_16x16x32_bf16 v[8:11], v[136:139], v[224:227], v[8:11]
	v_mfma_f32_16x16x32_bf16 v[60:63], v[132:135], v[204:207], v[60:63]
	v_mfma_f32_16x16x32_bf16 v[56:59], v[148:151], v[204:207], v[56:59]
	v_mfma_f32_16x16x32_bf16 v[44:47], v[132:135], v[212:215], v[44:47]
	v_mfma_f32_16x16x32_bf16 v[40:43], v[148:151], v[212:215], v[40:43]
	v_mfma_f32_16x16x32_bf16 v[28:31], v[132:135], v[220:223], v[28:31]
	v_mfma_f32_16x16x32_bf16 v[24:27], v[148:151], v[220:223], v[24:27]
	v_mfma_f32_16x16x32_bf16 v[12:15], v[132:135], v[228:231], v[12:15]
	v_mfma_f32_16x16x32_bf16 v[8:11], v[148:151], v[228:231], v[8:11]
	s_setprio 0
	s_setprio 1
	v_mfma_f32_16x16x32_bf16 v[52:55], v[162:165], v[200:203], v[52:55]
	v_mfma_f32_16x16x32_bf16 v[48:51], v[192:195], v[200:203], v[48:51]
	v_mfma_f32_16x16x32_bf16 v[36:39], v[162:165], v[208:211], v[36:39]
	v_mfma_f32_16x16x32_bf16 v[32:35], v[192:195], v[208:211], v[32:35]
	v_mfma_f32_16x16x32_bf16 v[20:23], v[162:165], v[216:219], v[20:23]
	v_mfma_f32_16x16x32_bf16 v[16:19], v[192:195], v[216:219], v[16:19]
	v_mfma_f32_16x16x32_bf16 v[4:7], v[162:165], v[224:227], v[4:7]
	v_mfma_f32_16x16x32_bf16 v[0:3], v[192:195], v[224:227], v[0:3]
	v_mfma_f32_16x16x32_bf16 v[52:55], v[188:191], v[204:207], v[52:55]
	v_mfma_f32_16x16x32_bf16 v[48:51], v[196:199], v[204:207], v[48:51]
	v_mfma_f32_16x16x32_bf16 v[36:39], v[188:191], v[212:215], v[36:39]
	v_mfma_f32_16x16x32_bf16 v[32:35], v[196:199], v[212:215], v[32:35]
	v_mfma_f32_16x16x32_bf16 v[20:23], v[188:191], v[220:223], v[20:23]
	v_mfma_f32_16x16x32_bf16 v[16:19], v[196:199], v[220:223], v[16:19]
	v_mfma_f32_16x16x32_bf16 v[4:7], v[188:191], v[228:231], v[4:7]
	v_mfma_f32_16x16x32_bf16 v[0:3], v[196:199], v[228:231], v[0:3]
	s_setprio 0
	s_add_i32 s53, s53, 2
	s_add_u32 s24, s24, 0x100
	s_addc_u32 s25, s25, 0
	s_add_u32 s51, s51, 0x100
	s_addc_u32 s52, s52, 0
	s_cmp_gt_u32 s53, 13
	s_barrier
	s_cbranch_scc0 .LBB0_705
	s_and_b64 vcc, exec, s[12:13]
	s_cbranch_vccz .LBB0_708
	s_barrier

; #define PG8_STAGE(bufoff, gbase, voff) do { _Pragma("unroll") for (int _i = 0; _i < 2; ++_i) \
;         __builtin_amdgcn_global_load_lds((const unsigned*)((const char*)(gbase) + (voff)[_i]), (LAS unsigned*)(lds + (bufoff) + ldsw + _i * 8192), 16, 0, 0); } while (0)
; #define PG8_LDA(dst, b, h) do { _Pragma("unroll") for (int m = 0; m < 4; ++m) _Pragma("unroll") for (int k = 0; k < 2; ++k) dst[m][k] = *(const LAS bf16x8*)(lds + PG8_SA(b, h) + aoff + m * 2048 + k * 1024); } while (0)
; #define PG8_LDB(dst, b, h) do { _Pragma("unroll") for (int n = 0; n < 2; ++n) _Pragma("unroll") for (int k = 0; k < 2; ++k) dst[n][k] = *(const LAS bf16x8*)(lds + PG8_SB(b, h) + boff + n * 2048 + k * 1024); } while (0)
; #define PG8_MMA(ai, bj, At, Bt) do { __builtin_amdgcn_s_setprio(1); _Pragma("unroll") for (int m = 0; m < 4; ++m) _Pragma("unroll") for (int n = 0; n < 2; ++n) _Pragma("unroll") for (int k = 0; k < 2; ++k) \
;         acc[ai][bj][m][n] = __builtin_amdgcn_mfma_f32_16x16x32_bf16(Bt[n][k], At[m][k], acc[ai][bj][m][n], 0, 0, 0); __builtin_amdgcn_s_setprio(0); } while (0)
; #define PG8_WAIT_V(n) asm volatile("s_waitcnt vmcnt(" #n ")" ::: "memory")
; #define PG8_WAIT_L(n) asm volatile("s_waitcnt lgkmcnt(" #n ")" ::: "memory")
; #define PG8_BAR __builtin_amdgcn_s_barrier()
; #define PG8_SCHED __builtin_amdgcn_sched_barrier(0)
; template <class Epi, bool ALIGN_EPI>
; DI void gemm_phase(lptr lds, const Gemm g, const StaticOrder& S, const Epi& E) {
;     ...
;             const char* a1 = cA + (size_t)(t + 1) * kstep;
;             const char* a2 = last ? nA : cA + (size_t)(t + 2) * kstep; const char* b2 = last ? nB : cB + (size_t)(t + 2) * kstep;
;             const char* a3 = a2 + kstep; const char* b3 = b2 + kstep;
;             PG8_LDB(B0, 0, 0); PG8_LDB(B1, 0, 1); PG8_SCHED; PG8_LDA(At, 0, 0); PG8_STAGE(PG8_SA(1, 1), a1 + hstepA, voffA);
;             PG8_WAIT_V(8); PG8_WAIT_L(0); PG8_BAR; PG8_MMA(0, 0, At, B0); PG8_MMA(0, 1, At, B1); PG8_BAR; PG8_SCHED;
;             PG8_LDA(At, 0, 1); PG8_STAGE(PG8_SB(0, 0), b2, voffB); PG8_STAGE(PG8_SB(0, 1), b2 + hstepB, voffB); PG8_STAGE(PG8_SA(0, 0), a2, voffA);
;             PG8_WAIT_V(8); PG8_WAIT_L(0); PG8_BAR; PG8_MMA(1, 0, At, B0); PG8_MMA(1, 1, At, B1); PG8_BAR; PG8_SCHED;
.LBB0_853:
	ds_read_b128 v[128:131], v175
	ds_read_b128 v[132:135], v175 offset:1024
	ds_read_b128 v[136:139], v175 offset:2048
	ds_read_b128 v[140:143], v175 offset:3072
	ds_read_b128 v[162:165], v176
	ds_read_b128 v[166:169], v176 offset:1024
	ds_read_b128 v[180:183], v176 offset:2048
	ds_read_b128 v[184:187], v176 offset:3072
	s_add_u32 s28, s26, 0xfffc0080
	s_addc_u32 s29, s27, -1
	s_cmp_eq_u32 s53, 12
	s_cselect_b32 s31, s19, s29
	s_cselect_b32 s30, s25, s28
	s_cselect_b32 s29, s17, s52
	s_cselect_b32 s28, s50, s51
	v_lshl_add_u64 v[220:221], s[26:27], 0, v[154:155]
	s_add_i32 m0, s37, 0xc000
	ds_read_b128 v[188:191], v177
	ds_read_b128 v[192:195], v177 offset:1024
	ds_read_b128 v[196:199], v177 offset:2048
	ds_read_b128 v[200:203], v177 offset:3072
	ds_read_b128 v[204:207], v177 offset:4096
	ds_read_b128 v[208:211], v177 offset:5120
	ds_read_b128 v[212:215], v177 offset:6144
	ds_read_b128 v[216:219], v177 offset:7168
	global_load_lds_dwordx4 v[220:221], off
	v_lshl_add_u64 v[220:221], s[26:27], 0, v[156:157]
	s_add_i32 m0, s37, 0xe000
	s_nop 0
	global_load_lds_dwordx4 v[220:221], off
	s_waitcnt vmcnt(8)
	s_waitcnt lgkmcnt(0)
	s_barrier
	s_setprio 1
	s_waitcnt lgkmcnt(0)
	v_mfma_f32_16x16x32_bf16 v[124:127], v[128:131], v[188:191], v[124:127]
	v_mfma_f32_16x16x32_bf16 v[120:123], v[136:139], v[188:191], v[120:123]
	v_mfma_f32_16x16x32_bf16 v[108:111], v[128:131], v[196:199], v[108:111]
	v_mfma_f32_16x16x32_bf16 v[104:107], v[136:139], v[196:199], v[104:107]
	v_mfma_f32_16x16x32_bf16 v[92:95], v[128:131], v[204:207], v[92:95]
	v_mfma_f32_16x16x32_bf16 v[88:91], v[136:139], v[204:207], v[88:91]
	v_mfma_f32_16x16x32_bf16 v[76:79], v[128:131], v[212:215], v[76:79]
	v_mfma_f32_16x16x32_bf16 v[72:75], v[136:139], v[212:215], v[72:75]
	v_mfma_f32_16x16x32_bf16 v[124:127], v[132:135], v[192:195], v[124:127]
	v_mfma_f32_16x16x32_bf16 v[120:123], v[140:143], v[192:195], v[120:123]
	v_mfma_f32_16x16x32_bf16 v[108:111], v[132:135], v[200:203], v[108:111]
	v_mfma_f32_16x16x32_bf16 v[104:107], v[140:143], v[200:203], v[104:107]
	v_mfma_f32_16x16x32_bf16 v[92:95], v[132:135], v[208:211], v[92:95]
	v_mfma_f32_16x16x32_bf16 v[88:91], v[140:143], v[208:211], v[88:91]
	v_mfma_f32_16x16x32_bf16 v[76:79], v[132:135], v[216:219], v[76:79]
	v_mfma_f32_16x16x32_bf16 v[72:75], v[140:143], v[216:219], v[72:75]
	s_setprio 0
	s_setprio 1
	v_mfma_f32_16x16x32_bf16 v[116:119], v[162:165], v[188:191], v[116:119]
	v_mfma_f32_16x16x32_bf16 v[112:115], v[180:183], v[188:191], v[112:115]
	v_mfma_f32_16x16x32_bf16 v[100:103], v[162:165], v[196:199], v[100:103]
	v_mfma_f32_16x16x32_bf16 v[96:99], v[180:183], v[196:199], v[96:99]
	v_mfma_f32_16x16x32_bf16 v[84:87], v[162:165], v[204:207], v[84:87]
	v_mfma_f32_16x16x32_bf16 v[80:83], v[180:183], v[204:207], v[80:83]
	v_mfma_f32_16x16x32_bf16 v[68:71], v[162:165], v[212:215], v[68:71]
	v_mfma_f32_16x16x32_bf16 v[64:67], v[180:183], v[212:215], v[64:67]
	v_mfma_f32_16x16x32_bf16 v[116:119], v[166:169], v[192:195], v[116:119]
	v_mfma_f32_16x16x32_bf16 v[112:115], v[184:187], v[192:195], v[112:115]
	v_mfma_f32_16x16x32_bf16 v[100:103], v[166:169], v[200:203], v[100:103]
	v_mfma_f32_16x16x32_bf16 v[96:99], v[184:187], v[200:203], v[96:99]
	v_mfma_f32_16x16x32_bf16 v[84:87], v[166:169], v[208:211], v[84:87]
	v_mfma_f32_16x16x32_bf16 v[80:83], v[184:187], v[208:211], v[80:83]
	v_mfma_f32_16x16x32_bf16 v[68:71], v[166:169], v[216:219], v[68:71]
	v_mfma_f32_16x16x32_bf16 v[64:67], v[184:187], v[216:219], v[64:67]
	s_setprio 0
	s_barrier
	s_add_i32 s54, s47, s36
	v_lshl_add_u64 v[220:221], s[28:29], 0, v[146:147]
	s_mov_b32 m0, s54
	ds_read_b128 v[188:191], v177 offset:16384
	ds_read_b128 v[192:195], v177 offset:17408
	ds_read_b128 v[196:199], v177 offset:18432
	ds_read_b128 v[200:203], v177 offset:19456
	ds_read_b128 v[204:207], v177 offset:20480
	ds_read_b128 v[208:211], v177 offset:21504
	ds_read_b128 v[212:215], v177 offset:22528
	ds_read_b128 v[216:219], v177 offset:23552
	global_load_lds_dwordx4 v[220:221], off
	s_add_i32 m0, s54, 0x2000
	s_add_u32 s54, s28, 0x40000
	v_lshl_add_u64 v[222:223], s[28:29], 0, v[150:151]
	s_addc_u32 s55, s29, 0
	s_add_i32 s56, s48, s36
	global_load_lds_dwordx4 v[222:223], off
	v_lshl_add_u64 v[224:225], s[54:55], 0, v[146:147]
	s_mov_b32 m0, s56
	v_lshl_add_u64 v[226:227], s[30:31], 0, v[148:149]
	global_load_lds_dwordx4 v[224:225], off
	v_lshl_add_u64 v[224:225], s[54:55], 0, v[150:151]
	s_add_i32 m0, s56, 0x2000
	s_nop 0
	global_load_lds_dwordx4 v[224:225], off
	v_lshl_add_u64 v[224:225], s[30:31], 0, v[144:145]
	s_mov_b32 m0, s37
	s_nop 0
	global_load_lds_dwordx4 v[224:225], off
	s_mov_b32 m0, s38
	s_nop 0
	global_load_lds_dwordx4 v[226:227], off
	s_waitcnt vmcnt(8)
	s_waitcnt lgkmcnt(0)
	s_barrier
; #define PG8_STAGE(bufoff, gbase, voff) do { _Pragma("unroll") for (int _i = 0; _i < 2; ++_i) \
;         __builtin_amdgcn_global_load_lds((const unsigned*)((const char*)(gbase) + (voff)[_i]), (LAS unsigned*)(lds + (bufoff) + ldsw + _i * 8192), 16, 0, 0); } while (0)
; #define PG8_LDA(dst, b, h) do { _Pragma("unroll") for (int m = 0; m < 4; ++m) _Pragma("unroll") for (int k = 0; k < 2; ++k) dst[m][k] = *(const LAS bf16x8*)(lds + PG8_SA(b, h) + aoff + m * 2048 + k * 1024); } while (0)
; #define PG8_LDB(dst, b, h) do { _Pragma("unroll") for (int n = 0; n < 2; ++n) _Pragma("unroll") for (int k = 0; k < 2; ++k) dst[n][k] = *(const LAS bf16x8*)(lds + PG8_SB(b, h) + boff + n * 2048 + k * 1024); } while (0)
; #define PG8_MMA(ai, bj, At, Bt) do { __builtin_amdgcn_s_setprio(1); _Pragma("unroll") for (int m = 0; m < 4; ++m) _Pragma("unroll") for (int n = 0; n < 2; ++n) _Pragma("unroll") for (int k = 0; k < 2; ++k) \
;         acc[ai][bj][m][n] = __builtin_amdgcn_mfma_f32_16x16x32_bf16(Bt[n][k], At[m][k], acc[ai][bj][m][n], 0, 0, 0); __builtin_amdgcn_s_setprio(0); } while (0)
; #define PG8_WAIT_V(n) asm volatile("s_waitcnt vmcnt(" #n ")" ::: "memory")
; #define PG8_WAIT_L(n) asm volatile("s_waitcnt lgkmcnt(" #n ")" ::: "memory")
; #define PG8_BAR __builtin_amdgcn_s_barrier()
; #define PG8_SCHED __builtin_amdgcn_sched_barrier(0)
; template <class Epi, bool ALIGN_EPI>
; DI void gemm_phase(lptr lds, const Gemm g, const StaticOrder& S, const Epi& E) {
;     ...
;             PG8_WAIT_V(8); PG8_WAIT_L(0); PG8_BAR; PG8_MMA(1, 0, At, B0); PG8_MMA(1, 1, At, B1); PG8_BAR; PG8_SCHED;
;             PG8_LDB(B0, 1, 0); PG8_LDB(B1, 1, 1); PG8_SCHED; PG8_LDA(At, 1, 0); PG8_STAGE(PG8_SA(0, 1), a2 + hstepA, voffA);
;             PG8_WAIT_V(8); PG8_WAIT_L(0); PG8_BAR; PG8_MMA(0, 0, At, B0); PG8_MMA(0, 1, At, B1); PG8_BAR; PG8_SCHED;
;             PG8_LDA(At, 1, 1); PG8_STAGE(PG8_SB(1, 0), b3, voffB); PG8_STAGE(PG8_SB(1, 1), b3 + hstepB, voffB); PG8_STAGE(PG8_SA(1, 0), a3, voffA);
	s_setprio 1
	s_waitcnt lgkmcnt(0)
	v_mfma_f32_16x16x32_bf16 v[60:63], v[128:131], v[188:191], v[60:63]
	v_mfma_f32_16x16x32_bf16 v[56:59], v[136:139], v[188:191], v[56:59]
	v_mfma_f32_16x16x32_bf16 v[44:47], v[128:131], v[196:199], v[44:47]
	v_mfma_f32_16x16x32_bf16 v[40:43], v[136:139], v[196:199], v[40:43]
	v_mfma_f32_16x16x32_bf16 v[28:31], v[128:131], v[204:207], v[28:31]
	v_mfma_f32_16x16x32_bf16 v[24:27], v[136:139], v[204:207], v[24:27]
	v_mfma_f32_16x16x32_bf16 v[12:15], v[128:131], v[212:215], v[12:15]
	v_mfma_f32_16x16x32_bf16 v[8:11], v[136:139], v[212:215], v[8:11]
	v_mfma_f32_16x16x32_bf16 v[60:63], v[132:135], v[192:195], v[60:63]
	v_mfma_f32_16x16x32_bf16 v[56:59], v[140:143], v[192:195], v[56:59]
	v_mfma_f32_16x16x32_bf16 v[44:47], v[132:135], v[200:203], v[44:47]
	v_mfma_f32_16x16x32_bf16 v[40:43], v[140:143], v[200:203], v[40:43]
	v_mfma_f32_16x16x32_bf16 v[28:31], v[132:135], v[208:211], v[28:31]
	v_mfma_f32_16x16x32_bf16 v[24:27], v[140:143], v[208:211], v[24:27]
	v_mfma_f32_16x16x32_bf16 v[12:15], v[132:135], v[216:219], v[12:15]
	v_mfma_f32_16x16x32_bf16 v[8:11], v[140:143], v[216:219], v[8:11]
	s_setprio 0
	s_setprio 1
	v_mfma_f32_16x16x32_bf16 v[52:55], v[162:165], v[188:191], v[52:55]
	v_mfma_f32_16x16x32_bf16 v[48:51], v[180:183], v[188:191], v[48:51]
	v_mfma_f32_16x16x32_bf16 v[36:39], v[162:165], v[196:199], v[36:39]
	v_mfma_f32_16x16x32_bf16 v[32:35], v[180:183], v[196:199], v[32:35]
	v_mfma_f32_16x16x32_bf16 v[20:23], v[162:165], v[204:207], v[20:23]
	v_mfma_f32_16x16x32_bf16 v[16:19], v[180:183], v[204:207], v[16:19]
	v_mfma_f32_16x16x32_bf16 v[4:7], v[162:165], v[212:215], v[4:7]
	v_mfma_f32_16x16x32_bf16 v[0:3], v[180:183], v[212:215], v[0:3]
	v_mfma_f32_16x16x32_bf16 v[52:55], v[166:169], v[192:195], v[52:55]
	v_mfma_f32_16x16x32_bf16 v[48:51], v[184:187], v[192:195], v[48:51]
	v_mfma_f32_16x16x32_bf16 v[36:39], v[166:169], v[200:203], v[36:39]
	v_mfma_f32_16x16x32_bf16 v[32:35], v[184:187], v[200:203], v[32:35]
	v_mfma_f32_16x16x32_bf16 v[20:23], v[166:169], v[208:211], v[20:23]
	v_mfma_f32_16x16x32_bf16 v[16:19], v[184:187], v[208:211], v[16:19]
	v_mfma_f32_16x16x32_bf16 v[4:7], v[166:169], v[216:219], v[4:7]
	v_mfma_f32_16x16x32_bf16 v[0:3], v[184:187], v[216:219], v[0:3]
	s_setprio 0
	s_barrier
	s_add_i32 s54, 0, 0x18000
	s_add_i32 s55, 0, 0x1c000
	v_add_u32_e32 v140, s54, v173
	v_add_u32_e32 v179, s55, v173
	ds_read_b128 v[128:131], v140
	ds_read_b128 v[132:135], v140 offset:1024
	ds_read_b128 v[136:139], v140 offset:2048
	ds_read_b128 v[140:143], v140 offset:3072
	ds_read_b128 v[162:165], v179
	ds_read_b128 v[166:169], v179 offset:1024
	ds_read_b128 v[180:183], v179 offset:2048
	ds_read_b128 v[184:187], v179 offset:3072
	s_add_u32 s30, s30, 0x40000
	s_addc_u32 s31, s31, 0
	s_mov_b32 m0, s39
	v_lshl_add_u64 v[228:229], s[30:31], 0, v[144:145]
	ds_read_b128 v[188:191], v177 offset:32768
	ds_read_b128 v[192:195], v177 offset:33792
	ds_read_b128 v[196:199], v177 offset:34816
	ds_read_b128 v[200:203], v177 offset:35840
	ds_read_b128 v[204:207], v177 offset:36864
	ds_read_b128 v[208:211], v177 offset:37888
	ds_read_b128 v[212:215], v177 offset:38912
	ds_read_b128 v[216:219], v177 offset:39936
	global_load_lds_dwordx4 v[228:229], off
	v_lshl_add_u64 v[228:229], s[30:31], 0, v[148:149]
	s_mov_b32 m0, s40
	s_nop 0
	global_load_lds_dwordx4 v[228:229], off
	s_waitcnt vmcnt(8)
	s_waitcnt lgkmcnt(0)
	s_barrier
	s_setprio 1
	s_waitcnt lgkmcnt(0)
	v_mfma_f32_16x16x32_bf16 v[124:127], v[128:131], v[188:191], v[124:127]
	v_mfma_f32_16x16x32_bf16 v[120:123], v[136:139], v[188:191], v[120:123]
	v_mfma_f32_16x16x32_bf16 v[108:111], v[128:131], v[196:199], v[108:111]
	v_mfma_f32_16x16x32_bf16 v[104:107], v[136:139], v[196:199], v[104:107]
	v_mfma_f32_16x16x32_bf16 v[92:95], v[128:131], v[204:207], v[92:95]
	v_mfma_f32_16x16x32_bf16 v[88:91], v[136:139], v[204:207], v[88:91]
	v_mfma_f32_16x16x32_bf16 v[76:79], v[128:131], v[212:215], v[76:79]
	v_mfma_f32_16x16x32_bf16 v[72:75], v[136:139], v[212:215], v[72:75]
	v_mfma_f32_16x16x32_bf16 v[124:127], v[132:135], v[192:195], v[124:127]
	v_mfma_f32_16x16x32_bf16 v[120:123], v[140:143], v[192:195], v[120:123]
	v_mfma_f32_16x16x32_bf16 v[108:111], v[132:135], v[200:203], v[108:111]
	v_mfma_f32_16x16x32_bf16 v[104:107], v[140:143], v[200:203], v[104:107]
	v_mfma_f32_16x16x32_bf16 v[92:95], v[132:135], v[208:211], v[92:95]
	v_mfma_f32_16x16x32_bf16 v[88:91], v[140:143], v[208:211], v[88:91]
	v_mfma_f32_16x16x32_bf16 v[76:79], v[132:135], v[216:219], v[76:79]
	v_mfma_f32_16x16x32_bf16 v[72:75], v[140:143], v[216:219], v[72:75]
	s_setprio 0
	s_setprio 1
	v_mfma_f32_16x16x32_bf16 v[116:119], v[162:165], v[188:191], v[116:119]
	v_mfma_f32_16x16x32_bf16 v[112:115], v[180:183], v[188:191], v[112:115]
	v_mfma_f32_16x16x32_bf16 v[100:103], v[162:165], v[196:199], v[100:103]
	v_mfma_f32_16x16x32_bf16 v[96:99], v[180:183], v[196:199], v[96:99]
	v_mfma_f32_16x16x32_bf16 v[84:87], v[162:165], v[204:207], v[84:87]
	v_mfma_f32_16x16x32_bf16 v[80:83], v[180:183], v[204:207], v[80:83]
	v_mfma_f32_16x16x32_bf16 v[68:71], v[162:165], v[212:215], v[68:71]
	v_mfma_f32_16x16x32_bf16 v[64:67], v[180:183], v[212:215], v[64:67]
	v_mfma_f32_16x16x32_bf16 v[116:119], v[166:169], v[192:195], v[116:119]
	v_mfma_f32_16x16x32_bf16 v[112:115], v[184:187], v[192:195], v[112:115]
	v_mfma_f32_16x16x32_bf16 v[100:103], v[166:169], v[200:203], v[100:103]
	v_mfma_f32_16x16x32_bf16 v[96:99], v[184:187], v[200:203], v[96:99]
	v_mfma_f32_16x16x32_bf16 v[84:87], v[166:169], v[208:211], v[84:87]
	v_mfma_f32_16x16x32_bf16 v[80:83], v[184:187], v[208:211], v[80:83]
	v_mfma_f32_16x16x32_bf16 v[68:71], v[166:169], v[216:219], v[68:71]
	v_mfma_f32_16x16x32_bf16 v[64:67], v[184:187], v[216:219], v[64:67]
	s_setprio 0
	s_barrier
; #define PG8_STAGE(bufoff, gbase, voff) do { _Pragma("unroll") for (int _i = 0; _i < 2; ++_i) \
;         __builtin_amdgcn_global_load_lds((const unsigned*)((const char*)(gbase) + (voff)[_i]), (LAS unsigned*)(lds + (bufoff) + ldsw + _i * 8192), 16, 0, 0); } while (0)
; #define PG8_LDA(dst, b, h) do { _Pragma("unroll") for (int m = 0; m < 4; ++m) _Pragma("unroll") for (int k = 0; k < 2; ++k) dst[m][k] = *(const LAS bf16x8*)(lds + PG8_SA(b, h) + aoff + m * 2048 + k * 1024); } while (0)
; #define PG8_MMA(ai, bj, At, Bt) do { __builtin_amdgcn_s_setprio(1); _Pragma("unroll") for (int m = 0; m < 4; ++m) _Pragma("unroll") for (int n = 0; n < 2; ++n) _Pragma("unroll") for (int k = 0; k < 2; ++k) \
;         acc[ai][bj][m][n] = __builtin_amdgcn_mfma_f32_16x16x32_bf16(Bt[n][k], At[m][k], acc[ai][bj][m][n], 0, 0, 0); __builtin_amdgcn_s_setprio(0); } while (0)
; #define PG8_WAIT_V(n) asm volatile("s_waitcnt vmcnt(" #n ")" ::: "memory")
; #define PG8_WAIT_L(n) asm volatile("s_waitcnt lgkmcnt(" #n ")" ::: "memory")
; #define PG8_BAR __builtin_amdgcn_s_barrier()
; #define PG8_SCHED __builtin_amdgcn_sched_barrier(0)
; template <class Epi, bool ALIGN_EPI>
; DI void gemm_phase(lptr lds, const Gemm g, const StaticOrder& S, const Epi& E) {
;     ...
;         for (int t = 0; t < nt; t += 2) {
;             const bool last = (t == nt - 2);
;     ...
;             PG8_LDA(At, 1, 1); PG8_STAGE(PG8_SB(1, 0), b3, voffB); PG8_STAGE(PG8_SB(1, 1), b3 + hstepB, voffB); PG8_STAGE(PG8_SA(1, 0), a3, voffA);
;             PG8_WAIT_V(8); PG8_WAIT_L(0); PG8_BAR; PG8_MMA(1, 0, At, B0); PG8_MMA(1, 1, At, B1); PG8_BAR; PG8_SCHED;
;         }
	s_add_i32 s30, s54, s36
	v_lshl_add_u64 v[220:221], v[220:221], 0, s[12:13]
	s_mov_b32 m0, s30
	ds_read_b128 v[188:191], v177 offset:49152
	ds_read_b128 v[192:195], v177 offset:50176
	ds_read_b128 v[196:199], v177 offset:51200
	ds_read_b128 v[200:203], v177 offset:52224
	ds_read_b128 v[204:207], v177 offset:53248
	ds_read_b128 v[208:211], v177 offset:54272
	ds_read_b128 v[212:215], v177 offset:55296
	ds_read_b128 v[216:219], v177 offset:56320
	global_load_lds_dwordx4 v[220:221], off
	s_add_i32 m0, s30, 0x2000
	s_add_u32 s28, s28, 0x40080
	v_lshl_add_u64 v[220:221], v[222:223], 0, s[12:13]
	s_addc_u32 s29, s29, 0
	s_add_i32 s30, s55, s36
	global_load_lds_dwordx4 v[220:221], off
	v_lshl_add_u64 v[220:221], s[28:29], 0, v[146:147]
	s_mov_b32 m0, s30
	s_nop 0
	global_load_lds_dwordx4 v[220:221], off
	v_lshl_add_u64 v[220:221], s[28:29], 0, v[150:151]
	s_add_i32 m0, s30, 0x2000
	s_nop 0
	global_load_lds_dwordx4 v[220:221], off
	v_lshl_add_u64 v[220:221], v[224:225], 0, s[12:13]
	s_mov_b32 m0, s43
	s_nop 0
	global_load_lds_dwordx4 v[220:221], off
	v_lshl_add_u64 v[220:221], v[226:227], 0, s[12:13]
	s_mov_b32 m0, s44
	s_nop 0
	global_load_lds_dwordx4 v[220:221], off
	s_waitcnt vmcnt(8)
	s_waitcnt lgkmcnt(0)
	s_barrier
	s_setprio 1
	s_waitcnt lgkmcnt(0)
	v_mfma_f32_16x16x32_bf16 v[60:63], v[128:131], v[188:191], v[60:63]
	v_mfma_f32_16x16x32_bf16 v[56:59], v[136:139], v[188:191], v[56:59]
	v_mfma_f32_16x16x32_bf16 v[44:47], v[128:131], v[196:199], v[44:47]
	v_mfma_f32_16x16x32_bf16 v[40:43], v[136:139], v[196:199], v[40:43]
	v_mfma_f32_16x16x32_bf16 v[28:31], v[128:131], v[204:207], v[28:31]
	v_mfma_f32_16x16x32_bf16 v[24:27], v[136:139], v[204:207], v[24:27]
	v_mfma_f32_16x16x32_bf16 v[12:15], v[128:131], v[212:215], v[12:15]
	v_mfma_f32_16x16x32_bf16 v[8:11], v[136:139], v[212:215], v[8:11]
	v_mfma_f32_16x16x32_bf16 v[60:63], v[132:135], v[192:195], v[60:63]
	v_mfma_f32_16x16x32_bf16 v[56:59], v[140:143], v[192:195], v[56:59]
	v_mfma_f32_16x16x32_bf16 v[44:47], v[132:135], v[200:203], v[44:47]
	v_mfma_f32_16x16x32_bf16 v[40:43], v[140:143], v[200:203], v[40:43]
	v_mfma_f32_16x16x32_bf16 v[28:31], v[132:135], v[208:211], v[28:31]
	v_mfma_f32_16x16x32_bf16 v[24:27], v[140:143], v[208:211], v[24:27]
	v_mfma_f32_16x16x32_bf16 v[12:15], v[132:135], v[216:219], v[12:15]
	v_mfma_f32_16x16x32_bf16 v[8:11], v[140:143], v[216:219], v[8:11]
	s_setprio 0
	s_setprio 1
	v_mfma_f32_16x16x32_bf16 v[52:55], v[162:165], v[188:191], v[52:55]
	v_mfma_f32_16x16x32_bf16 v[48:51], v[180:183], v[188:191], v[48:51]
	v_mfma_f32_16x16x32_bf16 v[36:39], v[162:165], v[196:199], v[36:39]
	v_mfma_f32_16x16x32_bf16 v[32:35], v[180:183], v[196:199], v[32:35]
	v_mfma_f32_16x16x32_bf16 v[20:23], v[162:165], v[204:207], v[20:23]
	v_mfma_f32_16x16x32_bf16 v[16:19], v[180:183], v[204:207], v[16:19]
	v_mfma_f32_16x16x32_bf16 v[4:7], v[162:165], v[212:215], v[4:7]
	v_mfma_f32_16x16x32_bf16 v[0:3], v[180:183], v[212:215], v[0:3]
	v_mfma_f32_16x16x32_bf16 v[52:55], v[166:169], v[192:195], v[52:55]
	v_mfma_f32_16x16x32_bf16 v[48:51], v[184:187], v[192:195], v[48:51]
	v_mfma_f32_16x16x32_bf16 v[36:39], v[166:169], v[200:203], v[36:39]
	v_mfma_f32_16x16x32_bf16 v[32:35], v[184:187], v[200:203], v[32:35]
	v_mfma_f32_16x16x32_bf16 v[20:23], v[166:169], v[208:211], v[20:23]
	v_mfma_f32_16x16x32_bf16 v[16:19], v[184:187], v[208:211], v[16:19]
	v_mfma_f32_16x16x32_bf16 v[4:7], v[166:169], v[216:219], v[4:7]
	v_mfma_f32_16x16x32_bf16 v[0:3], v[184:187], v[216:219], v[0:3]
	s_setprio 0
	s_add_i32 s53, s53, 2
	s_add_u32 s26, s26, 0x100
	s_addc_u32 s27, s27, 0
	s_add_u32 s51, s51, 0x100
	s_addc_u32 s52, s52, 0
	s_cmp_gt_u32 s53, 13
	s_barrier
	s_cbranch_scc0 .LBB0_853
	s_and_b64 vcc, exec, s[14:15]
	s_cbranch_vccz .LBB0_856
	s_barrier

; #define PG8_STAGE(bufoff, gbase, voff) do { _Pragma("unroll") for (int _i = 0; _i < 2; ++_i) \
;         __builtin_amdgcn_global_load_lds((const unsigned*)((const char*)(gbase) + (voff)[_i]), (LAS unsigned*)(lds + (bufoff) + ldsw + _i * 8192), 16, 0, 0); } while (0)
; #define PG8_LDA(dst, b, h) do { _Pragma("unroll") for (int m = 0; m < 4; ++m) _Pragma("unroll") for (int k = 0; k < 2; ++k) dst[m][k] = *(const LAS bf16x8*)(lds + PG8_SA(b, h) + aoff + m * 2048 + k * 1024); } while (0)
; #define PG8_LDB(dst, b, h) do { _Pragma("unroll") for (int n = 0; n < 2; ++n) _Pragma("unroll") for (int k = 0; k < 2; ++k) dst[n][k] = *(const LAS bf16x8*)(lds + PG8_SB(b, h) + boff + n * 2048 + k * 1024); } while (0)
; #define PG8_MMA(ai, bj, At, Bt) do { __builtin_amdgcn_s_setprio(1); _Pragma("unroll") for (int m = 0; m < 4; ++m) _Pragma("unroll") for (int n = 0; n < 2; ++n) _Pragma("unroll") for (int k = 0; k < 2; ++k) \
;         acc[ai][bj][m][n] = __builtin_amdgcn_mfma_f32_16x16x32_bf16(Bt[n][k], At[m][k], acc[ai][bj][m][n], 0, 0, 0); __builtin_amdgcn_s_setprio(0); } while (0)
; #define PG8_WAIT_V(n) asm volatile("s_waitcnt vmcnt(" #n ")" ::: "memory")
; #define PG8_WAIT_L(n) asm volatile("s_waitcnt lgkmcnt(" #n ")" ::: "memory")
; #define PG8_BAR __builtin_amdgcn_s_barrier()
; #define PG8_SCHED __builtin_amdgcn_sched_barrier(0)
; template <class Epi, bool ALIGN_EPI>
; DI void gemm_phase(lptr lds, const Gemm g, const StaticOrder& S, const Epi& E) {
;     ...
;             const char* a1 = cA + (size_t)(t + 1) * kstep;
;             const char* a2 = last ? nA : cA + (size_t)(t + 2) * kstep; const char* b2 = last ? nB : cB + (size_t)(t + 2) * kstep;
;             const char* a3 = a2 + kstep; const char* b3 = b2 + kstep;
;             PG8_LDB(B0, 0, 0); PG8_LDB(B1, 0, 1); PG8_SCHED; PG8_LDA(At, 0, 0); PG8_STAGE(PG8_SA(1, 1), a1 + hstepA, voffA);
;             PG8_WAIT_V(8); PG8_WAIT_L(0); PG8_BAR; PG8_MMA(0, 0, At, B0); PG8_MMA(0, 1, At, B1); PG8_BAR; PG8_SCHED;
;             PG8_LDA(At, 0, 1); PG8_STAGE(PG8_SB(0, 0), b2, voffB); PG8_STAGE(PG8_SB(0, 1), b2 + hstepB, voffB); PG8_STAGE(PG8_SA(0, 0), a2, voffA);
;             PG8_WAIT_V(8); PG8_WAIT_L(0); PG8_BAR; PG8_MMA(1, 0, At, B0); PG8_MMA(1, 1, At, B1); PG8_BAR; PG8_SCHED;
.LBB0_973:
	ds_read_b128 v[144:147], v159
	ds_read_b128 v[148:151], v159 offset:1024
	ds_read_b128 v[170:173], v159 offset:2048
	ds_read_b128 v[174:177], v159 offset:3072
	ds_read_b128 v[178:181], v163
	ds_read_b128 v[182:185], v163 offset:1024
	ds_read_b128 v[186:189], v163 offset:2048
	ds_read_b128 v[190:193], v163 offset:3072
	s_add_u32 s26, s24, 0xfffc0080
	s_addc_u32 s27, s25, -1
	s_cmp_eq_u32 s51, 12
	s_cselect_b32 s29, s19, s27
	s_cselect_b32 s28, s47, s26
	s_cselect_b32 s27, s17, s50
	s_cselect_b32 s26, s48, s49
	v_lshl_add_u64 v[154:155], s[24:25], 0, v[136:137]
	s_add_i32 m0, s33, 0xc000
	ds_read_b128 v[194:197], v164
	ds_read_b128 v[198:201], v164 offset:1024
	ds_read_b128 v[202:205], v164 offset:2048
	ds_read_b128 v[206:209], v164 offset:3072
	ds_read_b128 v[210:213], v164 offset:4096
	ds_read_b128 v[214:217], v164 offset:5120
	ds_read_b128 v[218:221], v164 offset:6144
	ds_read_b128 v[222:225], v164 offset:7168
	global_load_lds_dwordx4 v[154:155], off
	v_lshl_add_u64 v[154:155], s[24:25], 0, v[138:139]
	s_add_i32 m0, s33, 0xe000
	s_nop 0
	global_load_lds_dwordx4 v[154:155], off
	s_waitcnt vmcnt(8)
	s_waitcnt lgkmcnt(0)
	s_barrier
	s_setprio 1
	s_waitcnt lgkmcnt(0)
	v_mfma_f32_16x16x32_bf16 v[124:127], v[144:147], v[194:197], v[124:127]
	v_mfma_f32_16x16x32_bf16 v[120:123], v[170:173], v[194:197], v[120:123]
	v_mfma_f32_16x16x32_bf16 v[116:119], v[144:147], v[202:205], v[116:119]
	v_mfma_f32_16x16x32_bf16 v[112:115], v[170:173], v[202:205], v[112:115]
	v_mfma_f32_16x16x32_bf16 v[96:99], v[144:147], v[210:213], v[96:99]
	v_mfma_f32_16x16x32_bf16 v[88:91], v[170:173], v[210:213], v[88:91]
	v_mfma_f32_16x16x32_bf16 v[80:83], v[144:147], v[218:221], v[80:83]
	v_mfma_f32_16x16x32_bf16 v[72:75], v[170:173], v[218:221], v[72:75]
	v_mfma_f32_16x16x32_bf16 v[124:127], v[148:151], v[198:201], v[124:127]
	v_mfma_f32_16x16x32_bf16 v[120:123], v[174:177], v[198:201], v[120:123]
	v_mfma_f32_16x16x32_bf16 v[116:119], v[148:151], v[206:209], v[116:119]
	v_mfma_f32_16x16x32_bf16 v[112:115], v[174:177], v[206:209], v[112:115]
	v_mfma_f32_16x16x32_bf16 v[96:99], v[148:151], v[214:217], v[96:99]
	v_mfma_f32_16x16x32_bf16 v[88:91], v[174:177], v[214:217], v[88:91]
	v_mfma_f32_16x16x32_bf16 v[80:83], v[148:151], v[222:225], v[80:83]
	v_mfma_f32_16x16x32_bf16 v[72:75], v[174:177], v[222:225], v[72:75]
	s_setprio 0
	s_setprio 1
	v_mfma_f32_16x16x32_bf16 v[108:111], v[178:181], v[194:197], v[108:111]
	v_mfma_f32_16x16x32_bf16 v[104:107], v[186:189], v[194:197], v[104:107]
	v_mfma_f32_16x16x32_bf16 v[100:103], v[178:181], v[202:205], v[100:103]
	v_mfma_f32_16x16x32_bf16 v[92:95], v[186:189], v[202:205], v[92:95]
	v_mfma_f32_16x16x32_bf16 v[84:87], v[178:181], v[210:213], v[84:87]
	v_mfma_f32_16x16x32_bf16 v[76:79], v[186:189], v[210:213], v[76:79]
	v_mfma_f32_16x16x32_bf16 v[68:71], v[178:181], v[218:221], v[68:71]
	v_mfma_f32_16x16x32_bf16 v[64:67], v[186:189], v[218:221], v[64:67]
	v_mfma_f32_16x16x32_bf16 v[108:111], v[182:185], v[198:201], v[108:111]
	v_mfma_f32_16x16x32_bf16 v[104:107], v[190:193], v[198:201], v[104:107]
	v_mfma_f32_16x16x32_bf16 v[100:103], v[182:185], v[206:209], v[100:103]
	v_mfma_f32_16x16x32_bf16 v[92:95], v[190:193], v[206:209], v[92:95]
	v_mfma_f32_16x16x32_bf16 v[84:87], v[182:185], v[214:217], v[84:87]
	v_mfma_f32_16x16x32_bf16 v[76:79], v[190:193], v[214:217], v[76:79]
	v_mfma_f32_16x16x32_bf16 v[68:71], v[182:185], v[222:225], v[68:71]
	v_mfma_f32_16x16x32_bf16 v[64:67], v[190:193], v[222:225], v[64:67]
	s_setprio 0
	s_barrier
	s_add_i32 s52, s41, s31
	v_lshl_add_u64 v[154:155], s[26:27], 0, v[130:131]
	s_mov_b32 m0, s52
	ds_read_b128 v[194:197], v164 offset:16384
	ds_read_b128 v[198:201], v164 offset:17408
	ds_read_b128 v[202:205], v164 offset:18432
	ds_read_b128 v[206:209], v164 offset:19456
	ds_read_b128 v[210:213], v164 offset:20480
	ds_read_b128 v[214:217], v164 offset:21504
	ds_read_b128 v[218:221], v164 offset:22528
	ds_read_b128 v[222:225], v164 offset:23552
	global_load_lds_dwordx4 v[154:155], off
	s_add_i32 m0, s52, 0x2000
	s_add_u32 s52, s26, 0x40000
	v_lshl_add_u64 v[166:167], s[26:27], 0, v[134:135]
	s_addc_u32 s53, s27, 0
	s_add_i32 s54, s42, s31
	global_load_lds_dwordx4 v[166:167], off
	v_lshl_add_u64 v[226:227], s[52:53], 0, v[130:131]
	s_mov_b32 m0, s54
	v_lshl_add_u64 v[228:229], s[28:29], 0, v[132:133]
	global_load_lds_dwordx4 v[226:227], off
	v_lshl_add_u64 v[226:227], s[52:53], 0, v[134:135]
	s_add_i32 m0, s54, 0x2000
	s_nop 0
	global_load_lds_dwordx4 v[226:227], off
	v_lshl_add_u64 v[226:227], s[28:29], 0, v[128:129]
	s_mov_b32 m0, s33
	s_nop 0
	global_load_lds_dwordx4 v[226:227], off
	s_mov_b32 m0, s34
	s_nop 0
	global_load_lds_dwordx4 v[228:229], off
	s_waitcnt vmcnt(8)
	s_waitcnt lgkmcnt(0)
	s_barrier
; #define PG8_STAGE(bufoff, gbase, voff) do { _Pragma("unroll") for (int _i = 0; _i < 2; ++_i) \
;         __builtin_amdgcn_global_load_lds((const unsigned*)((const char*)(gbase) + (voff)[_i]), (LAS unsigned*)(lds + (bufoff) + ldsw + _i * 8192), 16, 0, 0); } while (0)
; #define PG8_LDA(dst, b, h) do { _Pragma("unroll") for (int m = 0; m < 4; ++m) _Pragma("unroll") for (int k = 0; k < 2; ++k) dst[m][k] = *(const LAS bf16x8*)(lds + PG8_SA(b, h) + aoff + m * 2048 + k * 1024); } while (0)
; #define PG8_LDB(dst, b, h) do { _Pragma("unroll") for (int n = 0; n < 2; ++n) _Pragma("unroll") for (int k = 0; k < 2; ++k) dst[n][k] = *(const LAS bf16x8*)(lds + PG8_SB(b, h) + boff + n * 2048 + k * 1024); } while (0)
; #define PG8_MMA(ai, bj, At, Bt) do { __builtin_amdgcn_s_setprio(1); _Pragma("unroll") for (int m = 0; m < 4; ++m) _Pragma("unroll") for (int n = 0; n < 2; ++n) _Pragma("unroll") for (int k = 0; k < 2; ++k) \
;         acc[ai][bj][m][n] = __builtin_amdgcn_mfma_f32_16x16x32_bf16(Bt[n][k], At[m][k], acc[ai][bj][m][n], 0, 0, 0); __builtin_amdgcn_s_setprio(0); } while (0)
; #define PG8_WAIT_V(n) asm volatile("s_waitcnt vmcnt(" #n ")" ::: "memory")
; #define PG8_WAIT_L(n) asm volatile("s_waitcnt lgkmcnt(" #n ")" ::: "memory")
; #define PG8_BAR __builtin_amdgcn_s_barrier()
; #define PG8_SCHED __builtin_amdgcn_sched_barrier(0)
; template <class Epi, bool ALIGN_EPI>
; DI void gemm_phase(lptr lds, const Gemm g, const StaticOrder& S, const Epi& E) {
;     ...
;             PG8_WAIT_V(8); PG8_WAIT_L(0); PG8_BAR; PG8_MMA(1, 0, At, B0); PG8_MMA(1, 1, At, B1); PG8_BAR; PG8_SCHED;
;             PG8_LDB(B0, 1, 0); PG8_LDB(B1, 1, 1); PG8_SCHED; PG8_LDA(At, 1, 0); PG8_STAGE(PG8_SA(0, 1), a2 + hstepA, voffA);
;             PG8_WAIT_V(8); PG8_WAIT_L(0); PG8_BAR; PG8_MMA(0, 0, At, B0); PG8_MMA(0, 1, At, B1); PG8_BAR; PG8_SCHED;
;             PG8_LDA(At, 1, 1); PG8_STAGE(PG8_SB(1, 0), b3, voffB); PG8_STAGE(PG8_SB(1, 1), b3 + hstepB, voffB); PG8_STAGE(PG8_SA(1, 0), a3, voffA);
	s_setprio 1
	s_waitcnt lgkmcnt(0)
	v_mfma_f32_16x16x32_bf16 v[60:63], v[144:147], v[194:197], v[60:63]
	v_mfma_f32_16x16x32_bf16 v[56:59], v[170:173], v[194:197], v[56:59]
	v_mfma_f32_16x16x32_bf16 v[48:51], v[144:147], v[202:205], v[48:51]
	v_mfma_f32_16x16x32_bf16 v[40:43], v[170:173], v[202:205], v[40:43]
	v_mfma_f32_16x16x32_bf16 v[32:35], v[144:147], v[210:213], v[32:35]
	v_mfma_f32_16x16x32_bf16 v[24:27], v[170:173], v[210:213], v[24:27]
	v_mfma_f32_16x16x32_bf16 v[16:19], v[144:147], v[218:221], v[16:19]
	v_mfma_f32_16x16x32_bf16 v[8:11], v[170:173], v[218:221], v[8:11]
	v_mfma_f32_16x16x32_bf16 v[60:63], v[148:151], v[198:201], v[60:63]
	v_mfma_f32_16x16x32_bf16 v[56:59], v[174:177], v[198:201], v[56:59]
	v_mfma_f32_16x16x32_bf16 v[48:51], v[148:151], v[206:209], v[48:51]
	v_mfma_f32_16x16x32_bf16 v[40:43], v[174:177], v[206:209], v[40:43]
	v_mfma_f32_16x16x32_bf16 v[32:35], v[148:151], v[214:217], v[32:35]
	v_mfma_f32_16x16x32_bf16 v[24:27], v[174:177], v[214:217], v[24:27]
	v_mfma_f32_16x16x32_bf16 v[16:19], v[148:151], v[222:225], v[16:19]
	v_mfma_f32_16x16x32_bf16 v[8:11], v[174:177], v[222:225], v[8:11]
	s_setprio 0
	s_setprio 1
	v_mfma_f32_16x16x32_bf16 v[52:55], v[178:181], v[194:197], v[52:55]
	v_mfma_f32_16x16x32_bf16 v[44:47], v[186:189], v[194:197], v[44:47]
	v_mfma_f32_16x16x32_bf16 v[36:39], v[178:181], v[202:205], v[36:39]
	v_mfma_f32_16x16x32_bf16 v[28:31], v[186:189], v[202:205], v[28:31]
	v_mfma_f32_16x16x32_bf16 v[20:23], v[178:181], v[210:213], v[20:23]
	v_mfma_f32_16x16x32_bf16 v[12:15], v[186:189], v[210:213], v[12:15]
	v_mfma_f32_16x16x32_bf16 v[4:7], v[178:181], v[218:221], v[4:7]
	v_mfma_f32_16x16x32_bf16 v[0:3], v[186:189], v[218:221], v[0:3]
	v_mfma_f32_16x16x32_bf16 v[52:55], v[182:185], v[198:201], v[52:55]
	v_mfma_f32_16x16x32_bf16 v[44:47], v[190:193], v[198:201], v[44:47]
	v_mfma_f32_16x16x32_bf16 v[36:39], v[182:185], v[206:209], v[36:39]
	v_mfma_f32_16x16x32_bf16 v[28:31], v[190:193], v[206:209], v[28:31]
	v_mfma_f32_16x16x32_bf16 v[20:23], v[182:185], v[214:217], v[20:23]
	v_mfma_f32_16x16x32_bf16 v[12:15], v[190:193], v[214:217], v[12:15]
	v_mfma_f32_16x16x32_bf16 v[4:7], v[182:185], v[222:225], v[4:7]
	v_mfma_f32_16x16x32_bf16 v[0:3], v[190:193], v[222:225], v[0:3]
	s_setprio 0
	s_barrier
	s_add_i32 s52, 0, 0x18000
	v_add_u32_e32 v169, s52, v157
	s_add_i32 s53, 0, 0x1c000
	ds_read_b128 v[144:147], v169
	ds_read_b128 v[148:151], v169 offset:1024
	ds_read_b128 v[170:173], v169 offset:2048
	ds_read_b128 v[174:177], v169 offset:3072
	v_add_u32_e32 v169, s53, v157
	ds_read_b128 v[178:181], v169
	ds_read_b128 v[182:185], v169 offset:1024
	ds_read_b128 v[186:189], v169 offset:2048
	ds_read_b128 v[190:193], v169 offset:3072
	s_add_u32 s28, s28, 0x40000
	s_addc_u32 s29, s29, 0
	s_mov_b32 m0, s35
	v_lshl_add_u64 v[230:231], s[28:29], 0, v[128:129]
	ds_read_b128 v[194:197], v164 offset:32768
	ds_read_b128 v[198:201], v164 offset:33792
	ds_read_b128 v[202:205], v164 offset:34816
	ds_read_b128 v[206:209], v164 offset:35840
	ds_read_b128 v[210:213], v164 offset:36864
	ds_read_b128 v[214:217], v164 offset:37888
	ds_read_b128 v[218:221], v164 offset:38912
	ds_read_b128 v[222:225], v164 offset:39936
	global_load_lds_dwordx4 v[230:231], off
	v_lshl_add_u64 v[230:231], s[28:29], 0, v[132:133]
	s_mov_b32 m0, s36
	s_nop 0
	global_load_lds_dwordx4 v[230:231], off
	s_waitcnt vmcnt(8)
	s_waitcnt lgkmcnt(0)
	s_barrier
	s_setprio 1
	s_waitcnt lgkmcnt(0)
	v_mfma_f32_16x16x32_bf16 v[124:127], v[144:147], v[194:197], v[124:127]
	v_mfma_f32_16x16x32_bf16 v[120:123], v[170:173], v[194:197], v[120:123]
	v_mfma_f32_16x16x32_bf16 v[116:119], v[144:147], v[202:205], v[116:119]
	v_mfma_f32_16x16x32_bf16 v[112:115], v[170:173], v[202:205], v[112:115]
	v_mfma_f32_16x16x32_bf16 v[96:99], v[144:147], v[210:213], v[96:99]
	v_mfma_f32_16x16x32_bf16 v[88:91], v[170:173], v[210:213], v[88:91]
	v_mfma_f32_16x16x32_bf16 v[80:83], v[144:147], v[218:221], v[80:83]
	v_mfma_f32_16x16x32_bf16 v[72:75], v[170:173], v[218:221], v[72:75]
	v_mfma_f32_16x16x32_bf16 v[124:127], v[148:151], v[198:201], v[124:127]
	v_mfma_f32_16x16x32_bf16 v[120:123], v[174:177], v[198:201], v[120:123]
	v_mfma_f32_16x16x32_bf16 v[116:119], v[148:151], v[206:209], v[116:119]
	v_mfma_f32_16x16x32_bf16 v[112:115], v[174:177], v[206:209], v[112:115]
	v_mfma_f32_16x16x32_bf16 v[96:99], v[148:151], v[214:217], v[96:99]
	v_mfma_f32_16x16x32_bf16 v[88:91], v[174:177], v[214:217], v[88:91]
	v_mfma_f32_16x16x32_bf16 v[80:83], v[148:151], v[222:225], v[80:83]
	v_mfma_f32_16x16x32_bf16 v[72:75], v[174:177], v[222:225], v[72:75]
	s_setprio 0
	s_setprio 1
	v_mfma_f32_16x16x32_bf16 v[108:111], v[178:181], v[194:197], v[108:111]
	v_mfma_f32_16x16x32_bf16 v[104:107], v[186:189], v[194:197], v[104:107]
	v_mfma_f32_16x16x32_bf16 v[100:103], v[178:181], v[202:205], v[100:103]
	v_mfma_f32_16x16x32_bf16 v[92:95], v[186:189], v[202:205], v[92:95]
	v_mfma_f32_16x16x32_bf16 v[84:87], v[178:181], v[210:213], v[84:87]
	v_mfma_f32_16x16x32_bf16 v[76:79], v[186:189], v[210:213], v[76:79]
	v_mfma_f32_16x16x32_bf16 v[68:71], v[178:181], v[218:221], v[68:71]
	v_mfma_f32_16x16x32_bf16 v[64:67], v[186:189], v[218:221], v[64:67]
	v_mfma_f32_16x16x32_bf16 v[108:111], v[182:185], v[198:201], v[108:111]
	v_mfma_f32_16x16x32_bf16 v[104:107], v[190:193], v[198:201], v[104:107]
	v_mfma_f32_16x16x32_bf16 v[100:103], v[182:185], v[206:209], v[100:103]
	v_mfma_f32_16x16x32_bf16 v[92:95], v[190:193], v[206:209], v[92:95]
	v_mfma_f32_16x16x32_bf16 v[84:87], v[182:185], v[214:217], v[84:87]
	v_mfma_f32_16x16x32_bf16 v[76:79], v[190:193], v[214:217], v[76:79]
	v_mfma_f32_16x16x32_bf16 v[68:71], v[182:185], v[222:225], v[68:71]
	v_mfma_f32_16x16x32_bf16 v[64:67], v[190:193], v[222:225], v[64:67]
	s_setprio 0
	s_barrier
; #define PG8_STAGE(bufoff, gbase, voff) do { _Pragma("unroll") for (int _i = 0; _i < 2; ++_i) \
;         __builtin_amdgcn_global_load_lds((const unsigned*)((const char*)(gbase) + (voff)[_i]), (LAS unsigned*)(lds + (bufoff) + ldsw + _i * 8192), 16, 0, 0); } while (0)
; #define PG8_LDA(dst, b, h) do { _Pragma("unroll") for (int m = 0; m < 4; ++m) _Pragma("unroll") for (int k = 0; k < 2; ++k) dst[m][k] = *(const LAS bf16x8*)(lds + PG8_SA(b, h) + aoff + m * 2048 + k * 1024); } while (0)
; #define PG8_MMA(ai, bj, At, Bt) do { __builtin_amdgcn_s_setprio(1); _Pragma("unroll") for (int m = 0; m < 4; ++m) _Pragma("unroll") for (int n = 0; n < 2; ++n) _Pragma("unroll") for (int k = 0; k < 2; ++k) \
;         acc[ai][bj][m][n] = __builtin_amdgcn_mfma_f32_16x16x32_bf16(Bt[n][k], At[m][k], acc[ai][bj][m][n], 0, 0, 0); __builtin_amdgcn_s_setprio(0); } while (0)
; #define PG8_WAIT_V(n) asm volatile("s_waitcnt vmcnt(" #n ")" ::: "memory")
; #define PG8_WAIT_L(n) asm volatile("s_waitcnt lgkmcnt(" #n ")" ::: "memory")
; #define PG8_BAR __builtin_amdgcn_s_barrier()
; #define PG8_SCHED __builtin_amdgcn_sched_barrier(0)
; template <class Epi, bool ALIGN_EPI>
; DI void gemm_phase(lptr lds, const Gemm g, const StaticOrder& S, const Epi& E) {
;     ...
;         for (int t = 0; t < nt; t += 2) {
;             const bool last = (t == nt - 2);
;     ...
;             PG8_LDA(At, 1, 1); PG8_STAGE(PG8_SB(1, 0), b3, voffB); PG8_STAGE(PG8_SB(1, 1), b3 + hstepB, voffB); PG8_STAGE(PG8_SA(1, 0), a3, voffA);
;             PG8_WAIT_V(8); PG8_WAIT_L(0); PG8_BAR; PG8_MMA(1, 0, At, B0); PG8_MMA(1, 1, At, B1); PG8_BAR; PG8_SCHED;
;         }
	s_add_i32 s28, s52, s31
	v_lshl_add_u64 v[154:155], v[154:155], 0, s[10:11]
	s_mov_b32 m0, s28
	ds_read_b128 v[194:197], v164 offset:49152
	ds_read_b128 v[198:201], v164 offset:50176
	ds_read_b128 v[202:205], v164 offset:51200
	ds_read_b128 v[206:209], v164 offset:52224
	ds_read_b128 v[210:213], v164 offset:53248
	ds_read_b128 v[214:217], v164 offset:54272
	ds_read_b128 v[218:221], v164 offset:55296
	ds_read_b128 v[222:225], v164 offset:56320
	global_load_lds_dwordx4 v[154:155], off
	s_add_i32 m0, s28, 0x2000
	s_add_u32 s26, s26, 0x40080
	v_lshl_add_u64 v[154:155], v[166:167], 0, s[10:11]
	s_addc_u32 s27, s27, 0
	s_add_i32 s28, s53, s31
	global_load_lds_dwordx4 v[154:155], off
	v_lshl_add_u64 v[154:155], s[26:27], 0, v[130:131]
	s_mov_b32 m0, s28
	s_nop 0
	global_load_lds_dwordx4 v[154:155], off
	v_lshl_add_u64 v[154:155], s[26:27], 0, v[134:135]
	s_add_i32 m0, s28, 0x2000
	s_nop 0
	global_load_lds_dwordx4 v[154:155], off
	v_lshl_add_u64 v[154:155], v[226:227], 0, s[10:11]
	s_mov_b32 m0, s38
	s_nop 0
	global_load_lds_dwordx4 v[154:155], off
	v_lshl_add_u64 v[154:155], v[228:229], 0, s[10:11]
	s_mov_b32 m0, s39
	s_nop 0
	global_load_lds_dwordx4 v[154:155], off
	s_waitcnt vmcnt(8)
	s_waitcnt lgkmcnt(0)
	s_barrier
	s_setprio 1
	s_waitcnt lgkmcnt(0)
	v_mfma_f32_16x16x32_bf16 v[60:63], v[144:147], v[194:197], v[60:63]
	v_mfma_f32_16x16x32_bf16 v[56:59], v[170:173], v[194:197], v[56:59]
	v_mfma_f32_16x16x32_bf16 v[48:51], v[144:147], v[202:205], v[48:51]
	v_mfma_f32_16x16x32_bf16 v[40:43], v[170:173], v[202:205], v[40:43]
	v_mfma_f32_16x16x32_bf16 v[32:35], v[144:147], v[210:213], v[32:35]
	v_mfma_f32_16x16x32_bf16 v[24:27], v[170:173], v[210:213], v[24:27]
	v_mfma_f32_16x16x32_bf16 v[16:19], v[144:147], v[218:221], v[16:19]
	v_mfma_f32_16x16x32_bf16 v[8:11], v[170:173], v[218:221], v[8:11]
	v_mfma_f32_16x16x32_bf16 v[60:63], v[148:151], v[198:201], v[60:63]
	v_mfma_f32_16x16x32_bf16 v[56:59], v[174:177], v[198:201], v[56:59]
	v_mfma_f32_16x16x32_bf16 v[48:51], v[148:151], v[206:209], v[48:51]
	v_mfma_f32_16x16x32_bf16 v[40:43], v[174:177], v[206:209], v[40:43]
	v_mfma_f32_16x16x32_bf16 v[32:35], v[148:151], v[214:217], v[32:35]
	v_mfma_f32_16x16x32_bf16 v[24:27], v[174:177], v[214:217], v[24:27]
	v_mfma_f32_16x16x32_bf16 v[16:19], v[148:151], v[222:225], v[16:19]
	v_mfma_f32_16x16x32_bf16 v[8:11], v[174:177], v[222:225], v[8:11]
	s_setprio 0
	s_setprio 1
	v_mfma_f32_16x16x32_bf16 v[52:55], v[178:181], v[194:197], v[52:55]
	v_mfma_f32_16x16x32_bf16 v[44:47], v[186:189], v[194:197], v[44:47]
	v_mfma_f32_16x16x32_bf16 v[36:39], v[178:181], v[202:205], v[36:39]
	v_mfma_f32_16x16x32_bf16 v[28:31], v[186:189], v[202:205], v[28:31]
	v_mfma_f32_16x16x32_bf16 v[20:23], v[178:181], v[210:213], v[20:23]
	v_mfma_f32_16x16x32_bf16 v[12:15], v[186:189], v[210:213], v[12:15]
	v_mfma_f32_16x16x32_bf16 v[4:7], v[178:181], v[218:221], v[4:7]
	v_mfma_f32_16x16x32_bf16 v[0:3], v[186:189], v[218:221], v[0:3]
	v_mfma_f32_16x16x32_bf16 v[52:55], v[182:185], v[198:201], v[52:55]
	v_mfma_f32_16x16x32_bf16 v[44:47], v[190:193], v[198:201], v[44:47]
	v_mfma_f32_16x16x32_bf16 v[36:39], v[182:185], v[206:209], v[36:39]
	v_mfma_f32_16x16x32_bf16 v[28:31], v[190:193], v[206:209], v[28:31]
	v_mfma_f32_16x16x32_bf16 v[20:23], v[182:185], v[214:217], v[20:23]
	v_mfma_f32_16x16x32_bf16 v[12:15], v[190:193], v[214:217], v[12:15]
	v_mfma_f32_16x16x32_bf16 v[4:7], v[182:185], v[222:225], v[4:7]
	v_mfma_f32_16x16x32_bf16 v[0:3], v[190:193], v[222:225], v[0:3]
	s_setprio 0
	s_add_i32 s51, s51, 2
	s_add_u32 s24, s24, 0x100
	s_addc_u32 s25, s25, 0
	s_add_u32 s49, s49, 0x100
	s_addc_u32 s50, s50, 0
	s_cmp_gt_u32 s51, 13
	s_barrier
	s_cbranch_scc0 .LBB0_973
	s_and_b64 vcc, exec, s[12:13]
	s_cbranch_vccz .LBB0_976
	s_barrier

; #define PG8_STAGE(bufoff, gbase, voff) do { _Pragma("unroll") for (int _i = 0; _i < 2; ++_i) \
;         __builtin_amdgcn_global_load_lds((const unsigned*)((const char*)(gbase) + (voff)[_i]), (LAS unsigned*)(lds + (bufoff) + ldsw + _i * 8192), 16, 0, 0); } while (0)
; #define PG8_LDA(dst, b, h) do { _Pragma("unroll") for (int m = 0; m < 4; ++m) _Pragma("unroll") for (int k = 0; k < 2; ++k) dst[m][k] = *(const LAS bf16x8*)(lds + PG8_SA(b, h) + aoff + m * 2048 + k * 1024); } while (0)
; #define PG8_LDB(dst, b, h) do { _Pragma("unroll") for (int n = 0; n < 2; ++n) _Pragma("unroll") for (int k = 0; k < 2; ++k) dst[n][k] = *(const LAS bf16x8*)(lds + PG8_SB(b, h) + boff + n * 2048 + k * 1024); } while (0)
; #define PG8_MMA(ai, bj, At, Bt) do { __builtin_amdgcn_s_setprio(1); _Pragma("unroll") for (int m = 0; m < 4; ++m) _Pragma("unroll") for (int n = 0; n < 2; ++n) _Pragma("unroll") for (int k = 0; k < 2; ++k) \
;         acc[ai][bj][m][n] = __builtin_amdgcn_mfma_f32_16x16x32_bf16(Bt[n][k], At[m][k], acc[ai][bj][m][n], 0, 0, 0); __builtin_amdgcn_s_setprio(0); } while (0)
; #define PG8_WAIT_V(n) asm volatile("s_waitcnt vmcnt(" #n ")" ::: "memory")
; #define PG8_WAIT_L(n) asm volatile("s_waitcnt lgkmcnt(" #n ")" ::: "memory")
; #define PG8_BAR __builtin_amdgcn_s_barrier()
; #define PG8_SCHED __builtin_amdgcn_sched_barrier(0)
; template <class Epi, bool ALIGN_EPI>
; DI void gemm_phase(lptr lds, const Gemm g, const StaticOrder& S, const Epi& E) {
;     ...
;             const char* a1 = cA + (size_t)(t + 1) * kstep;
;             const char* a2 = last ? nA : cA + (size_t)(t + 2) * kstep; const char* b2 = last ? nB : cB + (size_t)(t + 2) * kstep;
;             const char* a3 = a2 + kstep; const char* b3 = b2 + kstep;
;             PG8_LDB(B0, 0, 0); PG8_LDB(B1, 0, 1); PG8_SCHED; PG8_LDA(At, 0, 0); PG8_STAGE(PG8_SA(1, 1), a1 + hstepA, voffA);
;             PG8_WAIT_V(8); PG8_WAIT_L(0); PG8_BAR; PG8_MMA(0, 0, At, B0); PG8_MMA(0, 1, At, B1); PG8_BAR; PG8_SCHED;
;             PG8_LDA(At, 0, 1); PG8_STAGE(PG8_SB(0, 0), b2, voffB); PG8_STAGE(PG8_SB(0, 1), b2 + hstepB, voffB); PG8_STAGE(PG8_SA(0, 0), a2, voffA);
;             PG8_WAIT_V(8); PG8_WAIT_L(0); PG8_BAR; PG8_MMA(1, 0, At, B0); PG8_MMA(1, 1, At, B1); PG8_BAR; PG8_SCHED;
.LBB0_1169:
	ds_read_b128 v[128:131], v177
	ds_read_b128 v[132:135], v177 offset:1024
	ds_read_b128 v[136:139], v177 offset:2048
	ds_read_b128 v[140:143], v177 offset:3072
	ds_read_b128 v[162:165], v178
	ds_read_b128 v[166:169], v178 offset:1024
	ds_read_b128 v[182:185], v178 offset:2048
	ds_read_b128 v[186:189], v178 offset:3072
	s_add_u32 s28, s26, 0xfffc0080
	s_addc_u32 s29, s27, -1
	s_cmp_eq_u32 s52, 12
	s_cselect_b32 s31, s19, s29
	s_cselect_b32 s30, s25, s28
	s_cselect_b32 s29, s17, s51
	s_cselect_b32 s28, s49, s50
	v_lshl_add_u64 v[170:171], s[26:27], 0, v[154:155]
	s_add_i32 m0, s37, 0xc000
	ds_read_b128 v[190:193], v179
	ds_read_b128 v[194:197], v179 offset:1024
	ds_read_b128 v[198:201], v179 offset:2048
	ds_read_b128 v[202:205], v179 offset:3072
	ds_read_b128 v[206:209], v179 offset:4096
	ds_read_b128 v[210:213], v179 offset:5120
	ds_read_b128 v[214:217], v179 offset:6144
	ds_read_b128 v[218:221], v179 offset:7168
	global_load_lds_dwordx4 v[170:171], off
	v_lshl_add_u64 v[170:171], s[26:27], 0, v[156:157]
	s_add_i32 m0, s37, 0xe000
	s_nop 0
	global_load_lds_dwordx4 v[170:171], off
	s_waitcnt vmcnt(8)
	s_waitcnt lgkmcnt(0)
	s_barrier
	s_setprio 1
	s_waitcnt lgkmcnt(0)
	v_mfma_f32_16x16x32_bf16 v[124:127], v[128:131], v[190:193], v[124:127]
	v_mfma_f32_16x16x32_bf16 v[120:123], v[136:139], v[190:193], v[120:123]
	v_mfma_f32_16x16x32_bf16 v[108:111], v[128:131], v[198:201], v[108:111]
	v_mfma_f32_16x16x32_bf16 v[104:107], v[136:139], v[198:201], v[104:107]
	v_mfma_f32_16x16x32_bf16 v[92:95], v[128:131], v[206:209], v[92:95]
	v_mfma_f32_16x16x32_bf16 v[88:91], v[136:139], v[206:209], v[88:91]
	v_mfma_f32_16x16x32_bf16 v[76:79], v[128:131], v[214:217], v[76:79]
	v_mfma_f32_16x16x32_bf16 v[72:75], v[136:139], v[214:217], v[72:75]
	v_mfma_f32_16x16x32_bf16 v[124:127], v[132:135], v[194:197], v[124:127]
	v_mfma_f32_16x16x32_bf16 v[120:123], v[140:143], v[194:197], v[120:123]
	v_mfma_f32_16x16x32_bf16 v[108:111], v[132:135], v[202:205], v[108:111]
	v_mfma_f32_16x16x32_bf16 v[104:107], v[140:143], v[202:205], v[104:107]
	v_mfma_f32_16x16x32_bf16 v[92:95], v[132:135], v[210:213], v[92:95]
	v_mfma_f32_16x16x32_bf16 v[88:91], v[140:143], v[210:213], v[88:91]
	v_mfma_f32_16x16x32_bf16 v[76:79], v[132:135], v[218:221], v[76:79]
	v_mfma_f32_16x16x32_bf16 v[72:75], v[140:143], v[218:221], v[72:75]
	s_setprio 0
	s_setprio 1
	v_mfma_f32_16x16x32_bf16 v[116:119], v[162:165], v[190:193], v[116:119]
	v_mfma_f32_16x16x32_bf16 v[112:115], v[182:185], v[190:193], v[112:115]
	v_mfma_f32_16x16x32_bf16 v[100:103], v[162:165], v[198:201], v[100:103]
	v_mfma_f32_16x16x32_bf16 v[96:99], v[182:185], v[198:201], v[96:99]
	v_mfma_f32_16x16x32_bf16 v[84:87], v[162:165], v[206:209], v[84:87]
	v_mfma_f32_16x16x32_bf16 v[80:83], v[182:185], v[206:209], v[80:83]
	v_mfma_f32_16x16x32_bf16 v[68:71], v[162:165], v[214:217], v[68:71]
	v_mfma_f32_16x16x32_bf16 v[64:67], v[182:185], v[214:217], v[64:67]
	v_mfma_f32_16x16x32_bf16 v[116:119], v[166:169], v[194:197], v[116:119]
	v_mfma_f32_16x16x32_bf16 v[112:115], v[186:189], v[194:197], v[112:115]
	v_mfma_f32_16x16x32_bf16 v[100:103], v[166:169], v[202:205], v[100:103]
	v_mfma_f32_16x16x32_bf16 v[96:99], v[186:189], v[202:205], v[96:99]
	v_mfma_f32_16x16x32_bf16 v[84:87], v[166:169], v[210:213], v[84:87]
	v_mfma_f32_16x16x32_bf16 v[80:83], v[186:189], v[210:213], v[80:83]
	v_mfma_f32_16x16x32_bf16 v[68:71], v[166:169], v[218:221], v[68:71]
	v_mfma_f32_16x16x32_bf16 v[64:67], v[186:189], v[218:221], v[64:67]
	s_setprio 0
	s_barrier
	s_add_i32 s53, s46, s36
	v_lshl_add_u64 v[170:171], s[28:29], 0, v[146:147]
	s_mov_b32 m0, s53
	ds_read_b128 v[190:193], v179 offset:16384
	ds_read_b128 v[194:197], v179 offset:17408
	ds_read_b128 v[198:201], v179 offset:18432
	ds_read_b128 v[202:205], v179 offset:19456
	ds_read_b128 v[206:209], v179 offset:20480
	ds_read_b128 v[210:213], v179 offset:21504
	ds_read_b128 v[214:217], v179 offset:22528
	ds_read_b128 v[218:221], v179 offset:23552
	global_load_lds_dwordx4 v[170:171], off
	s_add_i32 m0, s53, 0x2000
	s_add_u32 s54, s28, 0x40000
	v_lshl_add_u64 v[222:223], s[28:29], 0, v[150:151]
	s_addc_u32 s55, s29, 0
	s_add_i32 s53, s47, s36
	global_load_lds_dwordx4 v[222:223], off
	v_lshl_add_u64 v[224:225], s[54:55], 0, v[146:147]
	s_mov_b32 m0, s53
	v_lshl_add_u64 v[226:227], s[30:31], 0, v[148:149]
	global_load_lds_dwordx4 v[224:225], off
	v_lshl_add_u64 v[224:225], s[54:55], 0, v[150:151]
	s_add_i32 m0, s53, 0x2000
	s_nop 0
	global_load_lds_dwordx4 v[224:225], off
	v_lshl_add_u64 v[224:225], s[30:31], 0, v[144:145]
	s_mov_b32 m0, s37
	s_nop 0
	global_load_lds_dwordx4 v[224:225], off
	s_mov_b32 m0, s38
	s_nop 0
	global_load_lds_dwordx4 v[226:227], off
	s_waitcnt vmcnt(8)
	s_waitcnt lgkmcnt(0)
	s_barrier
; #define PG8_STAGE(bufoff, gbase, voff) do { _Pragma("unroll") for (int _i = 0; _i < 2; ++_i) \
;         __builtin_amdgcn_global_load_lds((const unsigned*)((const char*)(gbase) + (voff)[_i]), (LAS unsigned*)(lds + (bufoff) + ldsw + _i * 8192), 16, 0, 0); } while (0)
; #define PG8_LDA(dst, b, h) do { _Pragma("unroll") for (int m = 0; m < 4; ++m) _Pragma("unroll") for (int k = 0; k < 2; ++k) dst[m][k] = *(const LAS bf16x8*)(lds + PG8_SA(b, h) + aoff + m * 2048 + k * 1024); } while (0)
; #define PG8_LDB(dst, b, h) do { _Pragma("unroll") for (int n = 0; n < 2; ++n) _Pragma("unroll") for (int k = 0; k < 2; ++k) dst[n][k] = *(const LAS bf16x8*)(lds + PG8_SB(b, h) + boff + n * 2048 + k * 1024); } while (0)
; #define PG8_MMA(ai, bj, At, Bt) do { __builtin_amdgcn_s_setprio(1); _Pragma("unroll") for (int m = 0; m < 4; ++m) _Pragma("unroll") for (int n = 0; n < 2; ++n) _Pragma("unroll") for (int k = 0; k < 2; ++k) \
;         acc[ai][bj][m][n] = __builtin_amdgcn_mfma_f32_16x16x32_bf16(Bt[n][k], At[m][k], acc[ai][bj][m][n], 0, 0, 0); __builtin_amdgcn_s_setprio(0); } while (0)
; #define PG8_WAIT_V(n) asm volatile("s_waitcnt vmcnt(" #n ")" ::: "memory")
; #define PG8_WAIT_L(n) asm volatile("s_waitcnt lgkmcnt(" #n ")" ::: "memory")
; #define PG8_BAR __builtin_amdgcn_s_barrier()
; #define PG8_SCHED __builtin_amdgcn_sched_barrier(0)
; template <class Epi, bool ALIGN_EPI>
; DI void gemm_phase(lptr lds, const Gemm g, const StaticOrder& S, const Epi& E) {
;     ...
;             PG8_WAIT_V(8); PG8_WAIT_L(0); PG8_BAR; PG8_MMA(1, 0, At, B0); PG8_MMA(1, 1, At, B1); PG8_BAR; PG8_SCHED;
;             PG8_LDB(B0, 1, 0); PG8_LDB(B1, 1, 1); PG8_SCHED; PG8_LDA(At, 1, 0); PG8_STAGE(PG8_SA(0, 1), a2 + hstepA, voffA);
;             PG8_WAIT_V(8); PG8_WAIT_L(0); PG8_BAR; PG8_MMA(0, 0, At, B0); PG8_MMA(0, 1, At, B1); PG8_BAR; PG8_SCHED;
;             PG8_LDA(At, 1, 1); PG8_STAGE(PG8_SB(1, 0), b3, voffB); PG8_STAGE(PG8_SB(1, 1), b3 + hstepB, voffB); PG8_STAGE(PG8_SA(1, 0), a3, voffA);
	s_setprio 1
	s_waitcnt lgkmcnt(0)
	v_mfma_f32_16x16x32_bf16 v[60:63], v[128:131], v[190:193], v[60:63]
	v_mfma_f32_16x16x32_bf16 v[56:59], v[136:139], v[190:193], v[56:59]
	v_mfma_f32_16x16x32_bf16 v[44:47], v[128:131], v[198:201], v[44:47]
	v_mfma_f32_16x16x32_bf16 v[40:43], v[136:139], v[198:201], v[40:43]
	v_mfma_f32_16x16x32_bf16 v[28:31], v[128:131], v[206:209], v[28:31]
	v_mfma_f32_16x16x32_bf16 v[24:27], v[136:139], v[206:209], v[24:27]
	v_mfma_f32_16x16x32_bf16 v[12:15], v[128:131], v[214:217], v[12:15]
	v_mfma_f32_16x16x32_bf16 v[8:11], v[136:139], v[214:217], v[8:11]
	v_mfma_f32_16x16x32_bf16 v[60:63], v[132:135], v[194:197], v[60:63]
	v_mfma_f32_16x16x32_bf16 v[56:59], v[140:143], v[194:197], v[56:59]
	v_mfma_f32_16x16x32_bf16 v[44:47], v[132:135], v[202:205], v[44:47]
	v_mfma_f32_16x16x32_bf16 v[40:43], v[140:143], v[202:205], v[40:43]
	v_mfma_f32_16x16x32_bf16 v[28:31], v[132:135], v[210:213], v[28:31]
	v_mfma_f32_16x16x32_bf16 v[24:27], v[140:143], v[210:213], v[24:27]
	v_mfma_f32_16x16x32_bf16 v[12:15], v[132:135], v[218:221], v[12:15]
	v_mfma_f32_16x16x32_bf16 v[8:11], v[140:143], v[218:221], v[8:11]
	s_setprio 0
	s_setprio 1
	v_mfma_f32_16x16x32_bf16 v[52:55], v[162:165], v[190:193], v[52:55]
	v_mfma_f32_16x16x32_bf16 v[48:51], v[182:185], v[190:193], v[48:51]
	v_mfma_f32_16x16x32_bf16 v[36:39], v[162:165], v[198:201], v[36:39]
	v_mfma_f32_16x16x32_bf16 v[32:35], v[182:185], v[198:201], v[32:35]
	v_mfma_f32_16x16x32_bf16 v[20:23], v[162:165], v[206:209], v[20:23]
	v_mfma_f32_16x16x32_bf16 v[16:19], v[182:185], v[206:209], v[16:19]
	v_mfma_f32_16x16x32_bf16 v[4:7], v[162:165], v[214:217], v[4:7]
	v_mfma_f32_16x16x32_bf16 v[0:3], v[182:185], v[214:217], v[0:3]
	v_mfma_f32_16x16x32_bf16 v[52:55], v[166:169], v[194:197], v[52:55]
	v_mfma_f32_16x16x32_bf16 v[48:51], v[186:189], v[194:197], v[48:51]
	v_mfma_f32_16x16x32_bf16 v[36:39], v[166:169], v[202:205], v[36:39]
	v_mfma_f32_16x16x32_bf16 v[32:35], v[186:189], v[202:205], v[32:35]
	v_mfma_f32_16x16x32_bf16 v[20:23], v[166:169], v[210:213], v[20:23]
	v_mfma_f32_16x16x32_bf16 v[16:19], v[186:189], v[210:213], v[16:19]
	v_mfma_f32_16x16x32_bf16 v[4:7], v[166:169], v[218:221], v[4:7]
	v_mfma_f32_16x16x32_bf16 v[0:3], v[186:189], v[218:221], v[0:3]
	s_setprio 0
	s_barrier
	s_add_i32 s53, 0, 0x18000
	s_add_i32 s54, 0, 0x1c000
	v_add_u32_e32 v140, s53, v175
	v_add_u32_e32 v181, s54, v175
	ds_read_b128 v[128:131], v140
	ds_read_b128 v[132:135], v140 offset:1024
	ds_read_b128 v[136:139], v140 offset:2048
	ds_read_b128 v[140:143], v140 offset:3072
	ds_read_b128 v[162:165], v181
	ds_read_b128 v[166:169], v181 offset:1024
	ds_read_b128 v[182:185], v181 offset:2048
	ds_read_b128 v[186:189], v181 offset:3072
	s_add_u32 s30, s30, 0x40000
	s_addc_u32 s31, s31, 0
	s_mov_b32 m0, s39
	v_lshl_add_u64 v[228:229], s[30:31], 0, v[144:145]
	ds_read_b128 v[190:193], v179 offset:32768
	ds_read_b128 v[194:197], v179 offset:33792
	ds_read_b128 v[198:201], v179 offset:34816
	ds_read_b128 v[202:205], v179 offset:35840
	ds_read_b128 v[206:209], v179 offset:36864
	ds_read_b128 v[210:213], v179 offset:37888
	ds_read_b128 v[214:217], v179 offset:38912
	ds_read_b128 v[218:221], v179 offset:39936
	global_load_lds_dwordx4 v[228:229], off
	v_lshl_add_u64 v[228:229], s[30:31], 0, v[148:149]
	s_mov_b32 m0, s40
	s_nop 0
	global_load_lds_dwordx4 v[228:229], off
	s_waitcnt vmcnt(8)
	s_waitcnt lgkmcnt(0)
	s_barrier
	s_setprio 1
	s_waitcnt lgkmcnt(0)
	v_mfma_f32_16x16x32_bf16 v[124:127], v[128:131], v[190:193], v[124:127]
	v_mfma_f32_16x16x32_bf16 v[120:123], v[136:139], v[190:193], v[120:123]
	v_mfma_f32_16x16x32_bf16 v[108:111], v[128:131], v[198:201], v[108:111]
	v_mfma_f32_16x16x32_bf16 v[104:107], v[136:139], v[198:201], v[104:107]
	v_mfma_f32_16x16x32_bf16 v[92:95], v[128:131], v[206:209], v[92:95]
	v_mfma_f32_16x16x32_bf16 v[88:91], v[136:139], v[206:209], v[88:91]
	v_mfma_f32_16x16x32_bf16 v[76:79], v[128:131], v[214:217], v[76:79]
	v_mfma_f32_16x16x32_bf16 v[72:75], v[136:139], v[214:217], v[72:75]
	v_mfma_f32_16x16x32_bf16 v[124:127], v[132:135], v[194:197], v[124:127]
	v_mfma_f32_16x16x32_bf16 v[120:123], v[140:143], v[194:197], v[120:123]
	v_mfma_f32_16x16x32_bf16 v[108:111], v[132:135], v[202:205], v[108:111]
	v_mfma_f32_16x16x32_bf16 v[104:107], v[140:143], v[202:205], v[104:107]
	v_mfma_f32_16x16x32_bf16 v[92:95], v[132:135], v[210:213], v[92:95]
	v_mfma_f32_16x16x32_bf16 v[88:91], v[140:143], v[210:213], v[88:91]
	v_mfma_f32_16x16x32_bf16 v[76:79], v[132:135], v[218:221], v[76:79]
	v_mfma_f32_16x16x32_bf16 v[72:75], v[140:143], v[218:221], v[72:75]
	s_setprio 0
	s_setprio 1
	v_mfma_f32_16x16x32_bf16 v[116:119], v[162:165], v[190:193], v[116:119]
	v_mfma_f32_16x16x32_bf16 v[112:115], v[182:185], v[190:193], v[112:115]
	v_mfma_f32_16x16x32_bf16 v[100:103], v[162:165], v[198:201], v[100:103]
	v_mfma_f32_16x16x32_bf16 v[96:99], v[182:185], v[198:201], v[96:99]
	v_mfma_f32_16x16x32_bf16 v[84:87], v[162:165], v[206:209], v[84:87]
	v_mfma_f32_16x16x32_bf16 v[80:83], v[182:185], v[206:209], v[80:83]
	v_mfma_f32_16x16x32_bf16 v[68:71], v[162:165], v[214:217], v[68:71]
	v_mfma_f32_16x16x32_bf16 v[64:67], v[182:185], v[214:217], v[64:67]
	v_mfma_f32_16x16x32_bf16 v[116:119], v[166:169], v[194:197], v[116:119]
	v_mfma_f32_16x16x32_bf16 v[112:115], v[186:189], v[194:197], v[112:115]
	v_mfma_f32_16x16x32_bf16 v[100:103], v[166:169], v[202:205], v[100:103]
	v_mfma_f32_16x16x32_bf16 v[96:99], v[186:189], v[202:205], v[96:99]
	v_mfma_f32_16x16x32_bf16 v[84:87], v[166:169], v[210:213], v[84:87]
	v_mfma_f32_16x16x32_bf16 v[80:83], v[186:189], v[210:213], v[80:83]
	v_mfma_f32_16x16x32_bf16 v[68:71], v[166:169], v[218:221], v[68:71]
	v_mfma_f32_16x16x32_bf16 v[64:67], v[186:189], v[218:221], v[64:67]
	s_setprio 0
	s_barrier
; #define PG8_STAGE(bufoff, gbase, voff) do { _Pragma("unroll") for (int _i = 0; _i < 2; ++_i) \
;         __builtin_amdgcn_global_load_lds((const unsigned*)((const char*)(gbase) + (voff)[_i]), (LAS unsigned*)(lds + (bufoff) + ldsw + _i * 8192), 16, 0, 0); } while (0)
; #define PG8_LDA(dst, b, h) do { _Pragma("unroll") for (int m = 0; m < 4; ++m) _Pragma("unroll") for (int k = 0; k < 2; ++k) dst[m][k] = *(const LAS bf16x8*)(lds + PG8_SA(b, h) + aoff + m * 2048 + k * 1024); } while (0)
; #define PG8_MMA(ai, bj, At, Bt) do { __builtin_amdgcn_s_setprio(1); _Pragma("unroll") for (int m = 0; m < 4; ++m) _Pragma("unroll") for (int n = 0; n < 2; ++n) _Pragma("unroll") for (int k = 0; k < 2; ++k) \
;         acc[ai][bj][m][n] = __builtin_amdgcn_mfma_f32_16x16x32_bf16(Bt[n][k], At[m][k], acc[ai][bj][m][n], 0, 0, 0); __builtin_amdgcn_s_setprio(0); } while (0)
; #define PG8_WAIT_V(n) asm volatile("s_waitcnt vmcnt(" #n ")" ::: "memory")
; #define PG8_WAIT_L(n) asm volatile("s_waitcnt lgkmcnt(" #n ")" ::: "memory")
; #define PG8_BAR __builtin_amdgcn_s_barrier()
; #define PG8_SCHED __builtin_amdgcn_sched_barrier(0)
; template <class Epi, bool ALIGN_EPI>
; DI void gemm_phase(lptr lds, const Gemm g, const StaticOrder& S, const Epi& E) {
;     ...
;         for (int t = 0; t < nt; t += 2) {
;             const bool last = (t == nt - 2);
;     ...
;             PG8_LDA(At, 1, 1); PG8_STAGE(PG8_SB(1, 0), b3, voffB); PG8_STAGE(PG8_SB(1, 1), b3 + hstepB, voffB); PG8_STAGE(PG8_SA(1, 0), a3, voffA);
;             PG8_WAIT_V(8); PG8_WAIT_L(0); PG8_BAR; PG8_MMA(1, 0, At, B0); PG8_MMA(1, 1, At, B1); PG8_BAR; PG8_SCHED;
;         }
	s_add_i32 s30, s53, s36
	v_lshl_add_u64 v[170:171], v[170:171], 0, s[12:13]
	s_mov_b32 m0, s30
	ds_read_b128 v[190:193], v179 offset:49152
	ds_read_b128 v[194:197], v179 offset:50176
	ds_read_b128 v[198:201], v179 offset:51200
	ds_read_b128 v[202:205], v179 offset:52224
	ds_read_b128 v[206:209], v179 offset:53248
	ds_read_b128 v[210:213], v179 offset:54272
	ds_read_b128 v[214:217], v179 offset:55296
	ds_read_b128 v[218:221], v179 offset:56320
	global_load_lds_dwordx4 v[170:171], off
	s_add_i32 m0, s30, 0x2000
	s_add_u32 s28, s28, 0x40080
	v_lshl_add_u64 v[170:171], v[222:223], 0, s[12:13]
	s_addc_u32 s29, s29, 0
	s_add_i32 s30, s54, s36
	global_load_lds_dwordx4 v[170:171], off
	v_lshl_add_u64 v[170:171], s[28:29], 0, v[146:147]
	s_mov_b32 m0, s30
	s_nop 0
	global_load_lds_dwordx4 v[170:171], off
	v_lshl_add_u64 v[170:171], s[28:29], 0, v[150:151]
	s_add_i32 m0, s30, 0x2000
	s_nop 0
	global_load_lds_dwordx4 v[170:171], off
	v_lshl_add_u64 v[170:171], v[224:225], 0, s[12:13]
	s_mov_b32 m0, s42
	s_nop 0
	global_load_lds_dwordx4 v[170:171], off
	v_lshl_add_u64 v[170:171], v[226:227], 0, s[12:13]
	s_mov_b32 m0, s43
	s_nop 0
	global_load_lds_dwordx4 v[170:171], off
	s_waitcnt vmcnt(8)
	s_waitcnt lgkmcnt(0)
	s_barrier
	s_setprio 1
	s_waitcnt lgkmcnt(0)
	v_mfma_f32_16x16x32_bf16 v[60:63], v[128:131], v[190:193], v[60:63]
	v_mfma_f32_16x16x32_bf16 v[56:59], v[136:139], v[190:193], v[56:59]
	v_mfma_f32_16x16x32_bf16 v[44:47], v[128:131], v[198:201], v[44:47]
	v_mfma_f32_16x16x32_bf16 v[40:43], v[136:139], v[198:201], v[40:43]
	v_mfma_f32_16x16x32_bf16 v[28:31], v[128:131], v[206:209], v[28:31]
	v_mfma_f32_16x16x32_bf16 v[24:27], v[136:139], v[206:209], v[24:27]
	v_mfma_f32_16x16x32_bf16 v[12:15], v[128:131], v[214:217], v[12:15]
	v_mfma_f32_16x16x32_bf16 v[8:11], v[136:139], v[214:217], v[8:11]
	v_mfma_f32_16x16x32_bf16 v[60:63], v[132:135], v[194:197], v[60:63]
	v_mfma_f32_16x16x32_bf16 v[56:59], v[140:143], v[194:197], v[56:59]
	v_mfma_f32_16x16x32_bf16 v[44:47], v[132:135], v[202:205], v[44:47]
	v_mfma_f32_16x16x32_bf16 v[40:43], v[140:143], v[202:205], v[40:43]
	v_mfma_f32_16x16x32_bf16 v[28:31], v[132:135], v[210:213], v[28:31]
	v_mfma_f32_16x16x32_bf16 v[24:27], v[140:143], v[210:213], v[24:27]
	v_mfma_f32_16x16x32_bf16 v[12:15], v[132:135], v[218:221], v[12:15]
	v_mfma_f32_16x16x32_bf16 v[8:11], v[140:143], v[218:221], v[8:11]
	s_setprio 0
	s_setprio 1
	v_mfma_f32_16x16x32_bf16 v[52:55], v[162:165], v[190:193], v[52:55]
	v_mfma_f32_16x16x32_bf16 v[48:51], v[182:185], v[190:193], v[48:51]
	v_mfma_f32_16x16x32_bf16 v[36:39], v[162:165], v[198:201], v[36:39]
	v_mfma_f32_16x16x32_bf16 v[32:35], v[182:185], v[198:201], v[32:35]
	v_mfma_f32_16x16x32_bf16 v[20:23], v[162:165], v[206:209], v[20:23]
	v_mfma_f32_16x16x32_bf16 v[16:19], v[182:185], v[206:209], v[16:19]
	v_mfma_f32_16x16x32_bf16 v[4:7], v[162:165], v[214:217], v[4:7]
	v_mfma_f32_16x16x32_bf16 v[0:3], v[182:185], v[214:217], v[0:3]
	v_mfma_f32_16x16x32_bf16 v[52:55], v[166:169], v[194:197], v[52:55]
	v_mfma_f32_16x16x32_bf16 v[48:51], v[186:189], v[194:197], v[48:51]
	v_mfma_f32_16x16x32_bf16 v[36:39], v[166:169], v[202:205], v[36:39]
	v_mfma_f32_16x16x32_bf16 v[32:35], v[186:189], v[202:205], v[32:35]
	v_mfma_f32_16x16x32_bf16 v[20:23], v[166:169], v[210:213], v[20:23]
	v_mfma_f32_16x16x32_bf16 v[16:19], v[186:189], v[210:213], v[16:19]
	v_mfma_f32_16x16x32_bf16 v[4:7], v[166:169], v[218:221], v[4:7]
	v_mfma_f32_16x16x32_bf16 v[0:3], v[186:189], v[218:221], v[0:3]
	s_setprio 0
	s_add_i32 s52, s52, 2
	s_add_u32 s26, s26, 0x100
	s_addc_u32 s27, s27, 0
	s_add_u32 s50, s50, 0x100
	s_addc_u32 s51, s51, 0
	s_cmp_gt_u32 s52, 13
	s_barrier
	s_cbranch_scc0 .LBB0_1169
	s_and_b64 vcc, exec, s[14:15]
	s_cbranch_vccz .LBB0_1172
	s_barrier

; #define PG8_STAGE(bufoff, gbase, voff) do { _Pragma("unroll") for (int _i = 0; _i < 2; ++_i) \
;         __builtin_amdgcn_global_load_lds((const unsigned*)((const char*)(gbase) + (voff)[_i]), (LAS unsigned*)(lds + (bufoff) + ldsw + _i * 8192), 16, 0, 0); } while (0)
; #define PG8_LDA(dst, b, h) do { _Pragma("unroll") for (int m = 0; m < 4; ++m) _Pragma("unroll") for (int k = 0; k < 2; ++k) dst[m][k] = *(const LAS bf16x8*)(lds + PG8_SA(b, h) + aoff + m * 2048 + k * 1024); } while (0)
; #define PG8_LDB(dst, b, h) do { _Pragma("unroll") for (int n = 0; n < 2; ++n) _Pragma("unroll") for (int k = 0; k < 2; ++k) dst[n][k] = *(const LAS bf16x8*)(lds + PG8_SB(b, h) + boff + n * 2048 + k * 1024); } while (0)
; #define PG8_MMA(ai, bj, At, Bt) do { __builtin_amdgcn_s_setprio(1); _Pragma("unroll") for (int m = 0; m < 4; ++m) _Pragma("unroll") for (int n = 0; n < 2; ++n) _Pragma("unroll") for (int k = 0; k < 2; ++k) \
;         acc[ai][bj][m][n] = __builtin_amdgcn_mfma_f32_16x16x32_bf16(Bt[n][k], At[m][k], acc[ai][bj][m][n], 0, 0, 0); __builtin_amdgcn_s_setprio(0); } while (0)
; #define PG8_WAIT_V(n) asm volatile("s_waitcnt vmcnt(" #n ")" ::: "memory")
; #define PG8_WAIT_L(n) asm volatile("s_waitcnt lgkmcnt(" #n ")" ::: "memory")
; #define PG8_BAR __builtin_amdgcn_s_barrier()
; #define PG8_SCHED __builtin_amdgcn_sched_barrier(0)
; template <class Epi, bool ALIGN_EPI>
; DI void gemm_phase(lptr lds, const Gemm g, const StaticOrder& S, const Epi& E) {
;     ...
;             const char* a1 = cA + (size_t)(t + 1) * kstep;
;             const char* a2 = last ? nA : cA + (size_t)(t + 2) * kstep; const char* b2 = last ? nB : cB + (size_t)(t + 2) * kstep;
;             const char* a3 = a2 + kstep; const char* b3 = b2 + kstep;
;             PG8_LDB(B0, 0, 0); PG8_LDB(B1, 0, 1); PG8_SCHED; PG8_LDA(At, 0, 0); PG8_STAGE(PG8_SA(1, 1), a1 + hstepA, voffA);
;             PG8_WAIT_V(8); PG8_WAIT_L(0); PG8_BAR; PG8_MMA(0, 0, At, B0); PG8_MMA(0, 1, At, B1); PG8_BAR; PG8_SCHED;
;             PG8_LDA(At, 0, 1); PG8_STAGE(PG8_SB(0, 0), b2, voffB); PG8_STAGE(PG8_SB(0, 1), b2 + hstepB, voffB); PG8_STAGE(PG8_SA(0, 0), a2, voffA);
;             PG8_WAIT_V(8); PG8_WAIT_L(0); PG8_BAR; PG8_MMA(1, 0, At, B0); PG8_MMA(1, 1, At, B1); PG8_BAR; PG8_SCHED;
.LBB0_1281:
	ds_read_b128 v[144:147], v166
	ds_read_b128 v[148:151], v166 offset:1024
	ds_read_b128 v[154:157], v166 offset:2048
	ds_read_b128 v[172:175], v166 offset:3072
	ds_read_b128 v[176:179], v167
	ds_read_b128 v[180:183], v167 offset:1024
	ds_read_b128 v[184:187], v167 offset:2048
	ds_read_b128 v[188:191], v167 offset:3072
	s_add_u32 s26, s24, 0xfffc0080
	s_addc_u32 s27, s25, -1
	s_cmp_eq_u32 s52, 12
	s_cselect_b32 s29, s19, s27
	s_cselect_b32 s28, s48, s26
	s_cselect_b32 s27, s17, s51
	s_cselect_b32 s26, s49, s50
	v_lshl_add_u64 v[158:159], s[24:25], 0, v[136:137]
	s_add_i32 m0, s35, 0xc000
	ds_read_b128 v[192:195], v169
	ds_read_b128 v[196:199], v169 offset:1024
	ds_read_b128 v[200:203], v169 offset:2048
	ds_read_b128 v[204:207], v169 offset:3072
	ds_read_b128 v[208:211], v169 offset:4096
	ds_read_b128 v[212:215], v169 offset:5120
	ds_read_b128 v[216:219], v169 offset:6144
	ds_read_b128 v[220:223], v169 offset:7168
	global_load_lds_dwordx4 v[158:159], off
	v_lshl_add_u64 v[158:159], s[24:25], 0, v[138:139]
	s_add_i32 m0, s35, 0xe000
	s_nop 0
	global_load_lds_dwordx4 v[158:159], off
	s_waitcnt vmcnt(8)
	s_waitcnt lgkmcnt(0)
	s_barrier
	s_setprio 1
	s_waitcnt lgkmcnt(0)
	v_mfma_f32_16x16x32_bf16 v[124:127], v[144:147], v[192:195], v[124:127]
	v_mfma_f32_16x16x32_bf16 v[120:123], v[154:157], v[192:195], v[120:123]
	v_mfma_f32_16x16x32_bf16 v[116:119], v[144:147], v[200:203], v[116:119]
	v_mfma_f32_16x16x32_bf16 v[112:115], v[154:157], v[200:203], v[112:115]
	v_mfma_f32_16x16x32_bf16 v[92:95], v[144:147], v[208:211], v[92:95]
	v_mfma_f32_16x16x32_bf16 v[88:91], v[154:157], v[208:211], v[88:91]
	v_mfma_f32_16x16x32_bf16 v[76:79], v[144:147], v[216:219], v[76:79]
	v_mfma_f32_16x16x32_bf16 v[72:75], v[154:157], v[216:219], v[72:75]
	v_mfma_f32_16x16x32_bf16 v[124:127], v[148:151], v[196:199], v[124:127]
	v_mfma_f32_16x16x32_bf16 v[120:123], v[172:175], v[196:199], v[120:123]
	v_mfma_f32_16x16x32_bf16 v[116:119], v[148:151], v[204:207], v[116:119]
	v_mfma_f32_16x16x32_bf16 v[112:115], v[172:175], v[204:207], v[112:115]
	v_mfma_f32_16x16x32_bf16 v[92:95], v[148:151], v[212:215], v[92:95]
	v_mfma_f32_16x16x32_bf16 v[88:91], v[172:175], v[212:215], v[88:91]
	v_mfma_f32_16x16x32_bf16 v[76:79], v[148:151], v[220:223], v[76:79]
	v_mfma_f32_16x16x32_bf16 v[72:75], v[172:175], v[220:223], v[72:75]
	s_setprio 0
	s_setprio 1
	v_mfma_f32_16x16x32_bf16 v[108:111], v[176:179], v[192:195], v[108:111]
	v_mfma_f32_16x16x32_bf16 v[104:107], v[184:187], v[192:195], v[104:107]
	v_mfma_f32_16x16x32_bf16 v[100:103], v[176:179], v[200:203], v[100:103]
	v_mfma_f32_16x16x32_bf16 v[96:99], v[184:187], v[200:203], v[96:99]
	v_mfma_f32_16x16x32_bf16 v[84:87], v[176:179], v[208:211], v[84:87]
	v_mfma_f32_16x16x32_bf16 v[80:83], v[184:187], v[208:211], v[80:83]
	v_mfma_f32_16x16x32_bf16 v[68:71], v[176:179], v[216:219], v[68:71]
	v_mfma_f32_16x16x32_bf16 v[64:67], v[184:187], v[216:219], v[64:67]
	v_mfma_f32_16x16x32_bf16 v[108:111], v[180:183], v[196:199], v[108:111]
	v_mfma_f32_16x16x32_bf16 v[104:107], v[188:191], v[196:199], v[104:107]
	v_mfma_f32_16x16x32_bf16 v[100:103], v[180:183], v[204:207], v[100:103]
	v_mfma_f32_16x16x32_bf16 v[96:99], v[188:191], v[204:207], v[96:99]
	v_mfma_f32_16x16x32_bf16 v[84:87], v[180:183], v[212:215], v[84:87]
	v_mfma_f32_16x16x32_bf16 v[80:83], v[188:191], v[212:215], v[80:83]
	v_mfma_f32_16x16x32_bf16 v[68:71], v[180:183], v[220:223], v[68:71]
	v_mfma_f32_16x16x32_bf16 v[64:67], v[188:191], v[220:223], v[64:67]
	s_setprio 0
	s_barrier
	s_add_i32 s53, s42, s30
	v_lshl_add_u64 v[158:159], s[26:27], 0, v[132:133]
	s_mov_b32 m0, s53
	ds_read_b128 v[192:195], v169 offset:16384
	ds_read_b128 v[196:199], v169 offset:17408
	ds_read_b128 v[200:203], v169 offset:18432
	ds_read_b128 v[204:207], v169 offset:19456
	ds_read_b128 v[208:211], v169 offset:20480
	ds_read_b128 v[212:215], v169 offset:21504
	ds_read_b128 v[216:219], v169 offset:22528
	ds_read_b128 v[220:223], v169 offset:23552
	global_load_lds_dwordx4 v[158:159], off
	s_add_i32 m0, s53, 0x2000
	s_add_u32 s54, s26, 0x40000
	v_lshl_add_u64 v[224:225], s[26:27], 0, v[128:129]
	s_addc_u32 s55, s27, 0
	s_add_i32 s53, s43, s30
	global_load_lds_dwordx4 v[224:225], off
	v_lshl_add_u64 v[226:227], s[54:55], 0, v[132:133]
	s_mov_b32 m0, s53
	v_lshl_add_u64 v[228:229], s[28:29], 0, v[130:131]
	global_load_lds_dwordx4 v[226:227], off
	v_lshl_add_u64 v[226:227], s[54:55], 0, v[128:129]
	s_add_i32 m0, s53, 0x2000
	s_nop 0
	global_load_lds_dwordx4 v[226:227], off
	v_lshl_add_u64 v[226:227], s[28:29], 0, v[134:135]
	s_mov_b32 m0, s35
	s_nop 0
	global_load_lds_dwordx4 v[226:227], off
	s_mov_b32 m0, s36
	s_nop 0
	global_load_lds_dwordx4 v[228:229], off
	s_waitcnt vmcnt(8)
	s_waitcnt lgkmcnt(0)
	s_barrier
; #define PG8_STAGE(bufoff, gbase, voff) do { _Pragma("unroll") for (int _i = 0; _i < 2; ++_i) \
;         __builtin_amdgcn_global_load_lds((const unsigned*)((const char*)(gbase) + (voff)[_i]), (LAS unsigned*)(lds + (bufoff) + ldsw + _i * 8192), 16, 0, 0); } while (0)
; #define PG8_LDA(dst, b, h) do { _Pragma("unroll") for (int m = 0; m < 4; ++m) _Pragma("unroll") for (int k = 0; k < 2; ++k) dst[m][k] = *(const LAS bf16x8*)(lds + PG8_SA(b, h) + aoff + m * 2048 + k * 1024); } while (0)
; #define PG8_LDB(dst, b, h) do { _Pragma("unroll") for (int n = 0; n < 2; ++n) _Pragma("unroll") for (int k = 0; k < 2; ++k) dst[n][k] = *(const LAS bf16x8*)(lds + PG8_SB(b, h) + boff + n * 2048 + k * 1024); } while (0)
; #define PG8_MMA(ai, bj, At, Bt) do { __builtin_amdgcn_s_setprio(1); _Pragma("unroll") for (int m = 0; m < 4; ++m) _Pragma("unroll") for (int n = 0; n < 2; ++n) _Pragma("unroll") for (int k = 0; k < 2; ++k) \
;         acc[ai][bj][m][n] = __builtin_amdgcn_mfma_f32_16x16x32_bf16(Bt[n][k], At[m][k], acc[ai][bj][m][n], 0, 0, 0); __builtin_amdgcn_s_setprio(0); } while (0)
; #define PG8_WAIT_V(n) asm volatile("s_waitcnt vmcnt(" #n ")" ::: "memory")
; #define PG8_WAIT_L(n) asm volatile("s_waitcnt lgkmcnt(" #n ")" ::: "memory")
; #define PG8_BAR __builtin_amdgcn_s_barrier()
; #define PG8_SCHED __builtin_amdgcn_sched_barrier(0)
; template <class Epi, bool ALIGN_EPI>
; DI void gemm_phase(lptr lds, const Gemm g, const StaticOrder& S, const Epi& E) {
;     ...
;             PG8_WAIT_V(8); PG8_WAIT_L(0); PG8_BAR; PG8_MMA(1, 0, At, B0); PG8_MMA(1, 1, At, B1); PG8_BAR; PG8_SCHED;
;             PG8_LDB(B0, 1, 0); PG8_LDB(B1, 1, 1); PG8_SCHED; PG8_LDA(At, 1, 0); PG8_STAGE(PG8_SA(0, 1), a2 + hstepA, voffA);
;             PG8_WAIT_V(8); PG8_WAIT_L(0); PG8_BAR; PG8_MMA(0, 0, At, B0); PG8_MMA(0, 1, At, B1); PG8_BAR; PG8_SCHED;
;             PG8_LDA(At, 1, 1); PG8_STAGE(PG8_SB(1, 0), b3, voffB); PG8_STAGE(PG8_SB(1, 1), b3 + hstepB, voffB); PG8_STAGE(PG8_SA(1, 0), a3, voffA);
	s_setprio 1
	s_waitcnt lgkmcnt(0)
	v_mfma_f32_16x16x32_bf16 v[60:63], v[144:147], v[192:195], v[60:63]
	v_mfma_f32_16x16x32_bf16 v[56:59], v[154:157], v[192:195], v[56:59]
	v_mfma_f32_16x16x32_bf16 v[44:47], v[144:147], v[200:203], v[44:47]
	v_mfma_f32_16x16x32_bf16 v[40:43], v[154:157], v[200:203], v[40:43]
	v_mfma_f32_16x16x32_bf16 v[28:31], v[144:147], v[208:211], v[28:31]
	v_mfma_f32_16x16x32_bf16 v[24:27], v[154:157], v[208:211], v[24:27]
	v_mfma_f32_16x16x32_bf16 v[12:15], v[144:147], v[216:219], v[12:15]
	v_mfma_f32_16x16x32_bf16 v[8:11], v[154:157], v[216:219], v[8:11]
	v_mfma_f32_16x16x32_bf16 v[60:63], v[148:151], v[196:199], v[60:63]
	v_mfma_f32_16x16x32_bf16 v[56:59], v[172:175], v[196:199], v[56:59]
	v_mfma_f32_16x16x32_bf16 v[44:47], v[148:151], v[204:207], v[44:47]
	v_mfma_f32_16x16x32_bf16 v[40:43], v[172:175], v[204:207], v[40:43]
	v_mfma_f32_16x16x32_bf16 v[28:31], v[148:151], v[212:215], v[28:31]
	v_mfma_f32_16x16x32_bf16 v[24:27], v[172:175], v[212:215], v[24:27]
	v_mfma_f32_16x16x32_bf16 v[12:15], v[148:151], v[220:223], v[12:15]
	v_mfma_f32_16x16x32_bf16 v[8:11], v[172:175], v[220:223], v[8:11]
	s_setprio 0
	s_setprio 1
	v_mfma_f32_16x16x32_bf16 v[52:55], v[176:179], v[192:195], v[52:55]
	v_mfma_f32_16x16x32_bf16 v[48:51], v[184:187], v[192:195], v[48:51]
	v_mfma_f32_16x16x32_bf16 v[36:39], v[176:179], v[200:203], v[36:39]
	v_mfma_f32_16x16x32_bf16 v[32:35], v[184:187], v[200:203], v[32:35]
	v_mfma_f32_16x16x32_bf16 v[20:23], v[176:179], v[208:211], v[20:23]
	v_mfma_f32_16x16x32_bf16 v[16:19], v[184:187], v[208:211], v[16:19]
	v_mfma_f32_16x16x32_bf16 v[4:7], v[176:179], v[216:219], v[4:7]
	v_mfma_f32_16x16x32_bf16 v[0:3], v[184:187], v[216:219], v[0:3]
	v_mfma_f32_16x16x32_bf16 v[52:55], v[180:183], v[196:199], v[52:55]
	v_mfma_f32_16x16x32_bf16 v[48:51], v[188:191], v[196:199], v[48:51]
	v_mfma_f32_16x16x32_bf16 v[36:39], v[180:183], v[204:207], v[36:39]
	v_mfma_f32_16x16x32_bf16 v[32:35], v[188:191], v[204:207], v[32:35]
	v_mfma_f32_16x16x32_bf16 v[20:23], v[180:183], v[212:215], v[20:23]
	v_mfma_f32_16x16x32_bf16 v[16:19], v[188:191], v[212:215], v[16:19]
	v_mfma_f32_16x16x32_bf16 v[4:7], v[180:183], v[220:223], v[4:7]
	v_mfma_f32_16x16x32_bf16 v[0:3], v[188:191], v[220:223], v[0:3]
	s_setprio 0
	s_barrier
	s_add_i32 s53, 0, 0x18000
	v_add_u32_e32 v171, s53, v164
	s_add_i32 s54, 0, 0x1c000
	ds_read_b128 v[144:147], v171
	ds_read_b128 v[148:151], v171 offset:1024
	ds_read_b128 v[154:157], v171 offset:2048
	ds_read_b128 v[172:175], v171 offset:3072
	v_add_u32_e32 v171, s54, v164
	ds_read_b128 v[176:179], v171
	ds_read_b128 v[180:183], v171 offset:1024
	ds_read_b128 v[184:187], v171 offset:2048
	ds_read_b128 v[188:191], v171 offset:3072
	s_add_u32 s28, s28, 0x40000
	s_addc_u32 s29, s29, 0
	s_mov_b32 m0, s37
	v_lshl_add_u64 v[230:231], s[28:29], 0, v[134:135]
	ds_read_b128 v[192:195], v169 offset:32768
	ds_read_b128 v[196:199], v169 offset:33792
	ds_read_b128 v[200:203], v169 offset:34816
	ds_read_b128 v[204:207], v169 offset:35840
	ds_read_b128 v[208:211], v169 offset:36864
	ds_read_b128 v[212:215], v169 offset:37888
	ds_read_b128 v[216:219], v169 offset:38912
	ds_read_b128 v[220:223], v169 offset:39936
	global_load_lds_dwordx4 v[230:231], off
	v_lshl_add_u64 v[230:231], s[28:29], 0, v[130:131]
	s_mov_b32 m0, s38
	s_nop 0
	global_load_lds_dwordx4 v[230:231], off
	s_waitcnt vmcnt(8)
	s_waitcnt lgkmcnt(0)
	s_barrier
	s_setprio 1
	s_waitcnt lgkmcnt(0)
	v_mfma_f32_16x16x32_bf16 v[124:127], v[144:147], v[192:195], v[124:127]
	v_mfma_f32_16x16x32_bf16 v[120:123], v[154:157], v[192:195], v[120:123]
	v_mfma_f32_16x16x32_bf16 v[116:119], v[144:147], v[200:203], v[116:119]
	v_mfma_f32_16x16x32_bf16 v[112:115], v[154:157], v[200:203], v[112:115]
	v_mfma_f32_16x16x32_bf16 v[92:95], v[144:147], v[208:211], v[92:95]
	v_mfma_f32_16x16x32_bf16 v[88:91], v[154:157], v[208:211], v[88:91]
	v_mfma_f32_16x16x32_bf16 v[76:79], v[144:147], v[216:219], v[76:79]
	v_mfma_f32_16x16x32_bf16 v[72:75], v[154:157], v[216:219], v[72:75]
	v_mfma_f32_16x16x32_bf16 v[124:127], v[148:151], v[196:199], v[124:127]
	v_mfma_f32_16x16x32_bf16 v[120:123], v[172:175], v[196:199], v[120:123]
	v_mfma_f32_16x16x32_bf16 v[116:119], v[148:151], v[204:207], v[116:119]
	v_mfma_f32_16x16x32_bf16 v[112:115], v[172:175], v[204:207], v[112:115]
	v_mfma_f32_16x16x32_bf16 v[92:95], v[148:151], v[212:215], v[92:95]
	v_mfma_f32_16x16x32_bf16 v[88:91], v[172:175], v[212:215], v[88:91]
	v_mfma_f32_16x16x32_bf16 v[76:79], v[148:151], v[220:223], v[76:79]
	v_mfma_f32_16x16x32_bf16 v[72:75], v[172:175], v[220:223], v[72:75]
	s_setprio 0
	s_setprio 1
	v_mfma_f32_16x16x32_bf16 v[108:111], v[176:179], v[192:195], v[108:111]
	v_mfma_f32_16x16x32_bf16 v[104:107], v[184:187], v[192:195], v[104:107]
	v_mfma_f32_16x16x32_bf16 v[100:103], v[176:179], v[200:203], v[100:103]
	v_mfma_f32_16x16x32_bf16 v[96:99], v[184:187], v[200:203], v[96:99]
	v_mfma_f32_16x16x32_bf16 v[84:87], v[176:179], v[208:211], v[84:87]
	v_mfma_f32_16x16x32_bf16 v[80:83], v[184:187], v[208:211], v[80:83]
	v_mfma_f32_16x16x32_bf16 v[68:71], v[176:179], v[216:219], v[68:71]
	v_mfma_f32_16x16x32_bf16 v[64:67], v[184:187], v[216:219], v[64:67]
	v_mfma_f32_16x16x32_bf16 v[108:111], v[180:183], v[196:199], v[108:111]
	v_mfma_f32_16x16x32_bf16 v[104:107], v[188:191], v[196:199], v[104:107]
	v_mfma_f32_16x16x32_bf16 v[100:103], v[180:183], v[204:207], v[100:103]
	v_mfma_f32_16x16x32_bf16 v[96:99], v[188:191], v[204:207], v[96:99]
	v_mfma_f32_16x16x32_bf16 v[84:87], v[180:183], v[212:215], v[84:87]
	v_mfma_f32_16x16x32_bf16 v[80:83], v[188:191], v[212:215], v[80:83]
	v_mfma_f32_16x16x32_bf16 v[68:71], v[180:183], v[220:223], v[68:71]
	v_mfma_f32_16x16x32_bf16 v[64:67], v[188:191], v[220:223], v[64:67]
	s_setprio 0
	s_barrier
; #define PG8_STAGE(bufoff, gbase, voff) do { _Pragma("unroll") for (int _i = 0; _i < 2; ++_i) \
;         __builtin_amdgcn_global_load_lds((const unsigned*)((const char*)(gbase) + (voff)[_i]), (LAS unsigned*)(lds + (bufoff) + ldsw + _i * 8192), 16, 0, 0); } while (0)
; #define PG8_LDA(dst, b, h) do { _Pragma("unroll") for (int m = 0; m < 4; ++m) _Pragma("unroll") for (int k = 0; k < 2; ++k) dst[m][k] = *(const LAS bf16x8*)(lds + PG8_SA(b, h) + aoff + m * 2048 + k * 1024); } while (0)
; #define PG8_MMA(ai, bj, At, Bt) do { __builtin_amdgcn_s_setprio(1); _Pragma("unroll") for (int m = 0; m < 4; ++m) _Pragma("unroll") for (int n = 0; n < 2; ++n) _Pragma("unroll") for (int k = 0; k < 2; ++k) \
;         acc[ai][bj][m][n] = __builtin_amdgcn_mfma_f32_16x16x32_bf16(Bt[n][k], At[m][k], acc[ai][bj][m][n], 0, 0, 0); __builtin_amdgcn_s_setprio(0); } while (0)
; #define PG8_WAIT_V(n) asm volatile("s_waitcnt vmcnt(" #n ")" ::: "memory")
; #define PG8_WAIT_L(n) asm volatile("s_waitcnt lgkmcnt(" #n ")" ::: "memory")
; #define PG8_BAR __builtin_amdgcn_s_barrier()
; #define PG8_SCHED __builtin_amdgcn_sched_barrier(0)
; template <class Epi, bool ALIGN_EPI>
; DI void gemm_phase(lptr lds, const Gemm g, const StaticOrder& S, const Epi& E) {
;     ...
;         for (int t = 0; t < nt; t += 2) {
;             const bool last = (t == nt - 2);
;     ...
;             PG8_LDA(At, 1, 1); PG8_STAGE(PG8_SB(1, 0), b3, voffB); PG8_STAGE(PG8_SB(1, 1), b3 + hstepB, voffB); PG8_STAGE(PG8_SA(1, 0), a3, voffA);
;             PG8_WAIT_V(8); PG8_WAIT_L(0); PG8_BAR; PG8_MMA(1, 0, At, B0); PG8_MMA(1, 1, At, B1); PG8_BAR; PG8_SCHED;
;         }
	s_add_i32 s28, s53, s30
	v_lshl_add_u64 v[158:159], v[158:159], 0, s[10:11]
	s_mov_b32 m0, s28
	ds_read_b128 v[192:195], v169 offset:49152
	ds_read_b128 v[196:199], v169 offset:50176
	ds_read_b128 v[200:203], v169 offset:51200
	ds_read_b128 v[204:207], v169 offset:52224
	ds_read_b128 v[208:211], v169 offset:53248
	ds_read_b128 v[212:215], v169 offset:54272
	ds_read_b128 v[216:219], v169 offset:55296
	ds_read_b128 v[220:223], v169 offset:56320
	global_load_lds_dwordx4 v[158:159], off
	s_add_i32 m0, s28, 0x2000
	s_add_u32 s26, s26, 0x40080
	v_lshl_add_u64 v[158:159], v[224:225], 0, s[10:11]
	s_addc_u32 s27, s27, 0
	s_add_i32 s28, s54, s30
	global_load_lds_dwordx4 v[158:159], off
	v_lshl_add_u64 v[158:159], s[26:27], 0, v[132:133]
	s_mov_b32 m0, s28
	s_nop 0
	global_load_lds_dwordx4 v[158:159], off
	v_lshl_add_u64 v[158:159], s[26:27], 0, v[128:129]
	s_add_i32 m0, s28, 0x2000
	s_nop 0
	global_load_lds_dwordx4 v[158:159], off
	v_lshl_add_u64 v[158:159], v[226:227], 0, s[10:11]
	s_mov_b32 m0, s33
	s_nop 0
	global_load_lds_dwordx4 v[158:159], off
	v_lshl_add_u64 v[158:159], v[228:229], 0, s[10:11]
	s_mov_b32 m0, s40
	s_nop 0
	global_load_lds_dwordx4 v[158:159], off
	s_waitcnt vmcnt(8)
	s_waitcnt lgkmcnt(0)
	s_barrier
	s_setprio 1
	s_waitcnt lgkmcnt(0)
	v_mfma_f32_16x16x32_bf16 v[60:63], v[144:147], v[192:195], v[60:63]
	v_mfma_f32_16x16x32_bf16 v[56:59], v[154:157], v[192:195], v[56:59]
	v_mfma_f32_16x16x32_bf16 v[44:47], v[144:147], v[200:203], v[44:47]
	v_mfma_f32_16x16x32_bf16 v[40:43], v[154:157], v[200:203], v[40:43]
	v_mfma_f32_16x16x32_bf16 v[28:31], v[144:147], v[208:211], v[28:31]
	v_mfma_f32_16x16x32_bf16 v[24:27], v[154:157], v[208:211], v[24:27]
	v_mfma_f32_16x16x32_bf16 v[12:15], v[144:147], v[216:219], v[12:15]
	v_mfma_f32_16x16x32_bf16 v[8:11], v[154:157], v[216:219], v[8:11]
	v_mfma_f32_16x16x32_bf16 v[60:63], v[148:151], v[196:199], v[60:63]
	v_mfma_f32_16x16x32_bf16 v[56:59], v[172:175], v[196:199], v[56:59]
	v_mfma_f32_16x16x32_bf16 v[44:47], v[148:151], v[204:207], v[44:47]
	v_mfma_f32_16x16x32_bf16 v[40:43], v[172:175], v[204:207], v[40:43]
	v_mfma_f32_16x16x32_bf16 v[28:31], v[148:151], v[212:215], v[28:31]
	v_mfma_f32_16x16x32_bf16 v[24:27], v[172:175], v[212:215], v[24:27]
	v_mfma_f32_16x16x32_bf16 v[12:15], v[148:151], v[220:223], v[12:15]
	v_mfma_f32_16x16x32_bf16 v[8:11], v[172:175], v[220:223], v[8:11]
	s_setprio 0
	s_setprio 1
	v_mfma_f32_16x16x32_bf16 v[52:55], v[176:179], v[192:195], v[52:55]
	v_mfma_f32_16x16x32_bf16 v[48:51], v[184:187], v[192:195], v[48:51]
	v_mfma_f32_16x16x32_bf16 v[36:39], v[176:179], v[200:203], v[36:39]
	v_mfma_f32_16x16x32_bf16 v[32:35], v[184:187], v[200:203], v[32:35]
	v_mfma_f32_16x16x32_bf16 v[20:23], v[176:179], v[208:211], v[20:23]
	v_mfma_f32_16x16x32_bf16 v[16:19], v[184:187], v[208:211], v[16:19]
	v_mfma_f32_16x16x32_bf16 v[4:7], v[176:179], v[216:219], v[4:7]
	v_mfma_f32_16x16x32_bf16 v[0:3], v[184:187], v[216:219], v[0:3]
	v_mfma_f32_16x16x32_bf16 v[52:55], v[180:183], v[196:199], v[52:55]
	v_mfma_f32_16x16x32_bf16 v[48:51], v[188:191], v[196:199], v[48:51]
	v_mfma_f32_16x16x32_bf16 v[36:39], v[180:183], v[204:207], v[36:39]
	v_mfma_f32_16x16x32_bf16 v[32:35], v[188:191], v[204:207], v[32:35]
	v_mfma_f32_16x16x32_bf16 v[20:23], v[180:183], v[212:215], v[20:23]
	v_mfma_f32_16x16x32_bf16 v[16:19], v[188:191], v[212:215], v[16:19]
	v_mfma_f32_16x16x32_bf16 v[4:7], v[180:183], v[220:223], v[4:7]
	v_mfma_f32_16x16x32_bf16 v[0:3], v[188:191], v[220:223], v[0:3]
	s_setprio 0
	s_add_i32 s52, s52, 2
	s_add_u32 s24, s24, 0x100
	s_addc_u32 s25, s25, 0
	s_add_u32 s50, s50, 0x100
	s_addc_u32 s51, s51, 0
	s_cmp_gt_u32 s52, 13
	s_barrier
	s_cbranch_scc0 .LBB0_1281
	s_and_b64 vcc, exec, s[12:13]
	s_cbranch_vccz .LBB0_1284
	s_barrier

; #define PG8_STAGE(bufoff, gbase, voff) do { _Pragma("unroll") for (int _i = 0; _i < 2; ++_i) \
;         __builtin_amdgcn_global_load_lds((const unsigned*)((const char*)(gbase) + (voff)[_i]), (LAS unsigned*)(lds + (bufoff) + ldsw + _i * 8192), 16, 0, 0); } while (0)
; #define PG8_LDA(dst, b, h) do { _Pragma("unroll") for (int m = 0; m < 4; ++m) _Pragma("unroll") for (int k = 0; k < 2; ++k) dst[m][k] = *(const LAS bf16x8*)(lds + PG8_SA(b, h) + aoff + m * 2048 + k * 1024); } while (0)
; #define PG8_LDB(dst, b, h) do { _Pragma("unroll") for (int n = 0; n < 2; ++n) _Pragma("unroll") for (int k = 0; k < 2; ++k) dst[n][k] = *(const LAS bf16x8*)(lds + PG8_SB(b, h) + boff + n * 2048 + k * 1024); } while (0)
; #define PG8_MMA(ai, bj, At, Bt) do { __builtin_amdgcn_s_setprio(1); _Pragma("unroll") for (int m = 0; m < 4; ++m) _Pragma("unroll") for (int n = 0; n < 2; ++n) _Pragma("unroll") for (int k = 0; k < 2; ++k) \
;         acc[ai][bj][m][n] = __builtin_amdgcn_mfma_f32_16x16x32_bf16(Bt[n][k], At[m][k], acc[ai][bj][m][n], 0, 0, 0); __builtin_amdgcn_s_setprio(0); } while (0)
; #define PG8_WAIT_V(n) asm volatile("s_waitcnt vmcnt(" #n ")" ::: "memory")
; #define PG8_WAIT_L(n) asm volatile("s_waitcnt lgkmcnt(" #n ")" ::: "memory")
; #define PG8_BAR __builtin_amdgcn_s_barrier()
; #define PG8_SCHED __builtin_amdgcn_sched_barrier(0)
; template <class Epi, bool ALIGN_EPI>
; DI void gemm_phase(lptr lds, const Gemm g, const StaticOrder& S, const Epi& E) {
;     ...
;             const char* a1 = cA + (size_t)(t + 1) * kstep;
;             const char* a2 = last ? nA : cA + (size_t)(t + 2) * kstep; const char* b2 = last ? nB : cB + (size_t)(t + 2) * kstep;
;             const char* a3 = a2 + kstep; const char* b3 = b2 + kstep;
;             PG8_LDB(B0, 0, 0); PG8_LDB(B1, 0, 1); PG8_SCHED; PG8_LDA(At, 0, 0); PG8_STAGE(PG8_SA(1, 1), a1 + hstepA, voffA);
;             PG8_WAIT_V(8); PG8_WAIT_L(0); PG8_BAR; PG8_MMA(0, 0, At, B0); PG8_MMA(0, 1, At, B1); PG8_BAR; PG8_SCHED;
;             PG8_LDA(At, 0, 1); PG8_STAGE(PG8_SB(0, 0), b2, voffB); PG8_STAGE(PG8_SB(0, 1), b2 + hstepB, voffB); PG8_STAGE(PG8_SA(0, 0), a2, voffA);
;             PG8_WAIT_V(8); PG8_WAIT_L(0); PG8_BAR; PG8_MMA(1, 0, At, B0); PG8_MMA(1, 1, At, B1); PG8_BAR; PG8_SCHED;
.LBB0_1385:
	ds_read_b128 v[128:131], v177
	ds_read_b128 v[132:135], v177 offset:1024
	ds_read_b128 v[136:139], v177 offset:2048
	ds_read_b128 v[140:143], v177 offset:3072
	ds_read_b128 v[162:165], v178
	ds_read_b128 v[166:169], v178 offset:1024
	ds_read_b128 v[182:185], v178 offset:2048
	ds_read_b128 v[186:189], v178 offset:3072
	s_add_u32 s22, s20, 0xfff50080
	s_addc_u32 s23, s21, -1
	s_cmp_eq_u32 s48, 40
	s_cselect_b32 s25, s1, s23
	s_cselect_b32 s24, s0, s22
	s_cselect_b32 s23, s19, s47
	s_cselect_b32 s22, s18, s46
	v_lshl_add_u64 v[170:171], s[20:21], 0, v[154:155]
	s_add_i32 m0, s27, 0xc000
	ds_read_b128 v[190:193], v179
	ds_read_b128 v[194:197], v179 offset:1024
	ds_read_b128 v[198:201], v179 offset:2048
	ds_read_b128 v[202:205], v179 offset:3072
	ds_read_b128 v[206:209], v179 offset:4096
	ds_read_b128 v[210:213], v179 offset:5120
	ds_read_b128 v[214:217], v179 offset:6144
	ds_read_b128 v[218:221], v179 offset:7168
	global_load_lds_dwordx4 v[170:171], off
	v_lshl_add_u64 v[170:171], s[20:21], 0, v[156:157]
	s_add_i32 m0, s27, 0xe000
	s_nop 0
	global_load_lds_dwordx4 v[170:171], off
	s_waitcnt vmcnt(8)
	s_waitcnt lgkmcnt(0)
	s_barrier
	s_setprio 1
	s_waitcnt lgkmcnt(0)
	v_mfma_f32_16x16x32_bf16 v[124:127], v[128:131], v[190:193], v[124:127]
	v_mfma_f32_16x16x32_bf16 v[120:123], v[136:139], v[190:193], v[120:123]
	v_mfma_f32_16x16x32_bf16 v[108:111], v[128:131], v[198:201], v[108:111]
	v_mfma_f32_16x16x32_bf16 v[104:107], v[136:139], v[198:201], v[104:107]
	v_mfma_f32_16x16x32_bf16 v[92:95], v[128:131], v[206:209], v[92:95]
	v_mfma_f32_16x16x32_bf16 v[88:91], v[136:139], v[206:209], v[88:91]
	v_mfma_f32_16x16x32_bf16 v[76:79], v[128:131], v[214:217], v[76:79]
	v_mfma_f32_16x16x32_bf16 v[72:75], v[136:139], v[214:217], v[72:75]
	v_mfma_f32_16x16x32_bf16 v[124:127], v[132:135], v[194:197], v[124:127]
	v_mfma_f32_16x16x32_bf16 v[120:123], v[140:143], v[194:197], v[120:123]
	v_mfma_f32_16x16x32_bf16 v[108:111], v[132:135], v[202:205], v[108:111]
	v_mfma_f32_16x16x32_bf16 v[104:107], v[140:143], v[202:205], v[104:107]
	v_mfma_f32_16x16x32_bf16 v[92:95], v[132:135], v[210:213], v[92:95]
	v_mfma_f32_16x16x32_bf16 v[88:91], v[140:143], v[210:213], v[88:91]
	v_mfma_f32_16x16x32_bf16 v[76:79], v[132:135], v[218:221], v[76:79]
	v_mfma_f32_16x16x32_bf16 v[72:75], v[140:143], v[218:221], v[72:75]
	s_setprio 0
	s_setprio 1
	v_mfma_f32_16x16x32_bf16 v[116:119], v[162:165], v[190:193], v[116:119]
	v_mfma_f32_16x16x32_bf16 v[112:115], v[182:185], v[190:193], v[112:115]
	v_mfma_f32_16x16x32_bf16 v[100:103], v[162:165], v[198:201], v[100:103]
	v_mfma_f32_16x16x32_bf16 v[96:99], v[182:185], v[198:201], v[96:99]
	v_mfma_f32_16x16x32_bf16 v[84:87], v[162:165], v[206:209], v[84:87]
	v_mfma_f32_16x16x32_bf16 v[80:83], v[182:185], v[206:209], v[80:83]
	v_mfma_f32_16x16x32_bf16 v[68:71], v[162:165], v[214:217], v[68:71]
	v_mfma_f32_16x16x32_bf16 v[64:67], v[182:185], v[214:217], v[64:67]
	v_mfma_f32_16x16x32_bf16 v[116:119], v[166:169], v[194:197], v[116:119]
	v_mfma_f32_16x16x32_bf16 v[112:115], v[186:189], v[194:197], v[112:115]
	v_mfma_f32_16x16x32_bf16 v[100:103], v[166:169], v[202:205], v[100:103]
	v_mfma_f32_16x16x32_bf16 v[96:99], v[186:189], v[202:205], v[96:99]
	v_mfma_f32_16x16x32_bf16 v[84:87], v[166:169], v[210:213], v[84:87]
	v_mfma_f32_16x16x32_bf16 v[80:83], v[186:189], v[210:213], v[80:83]
	v_mfma_f32_16x16x32_bf16 v[68:71], v[166:169], v[218:221], v[68:71]
	v_mfma_f32_16x16x32_bf16 v[64:67], v[186:189], v[218:221], v[64:67]
	s_setprio 0
	s_barrier
	s_add_i32 s49, s40, s26
	v_lshl_add_u64 v[170:171], s[22:23], 0, v[146:147]
	s_mov_b32 m0, s49
	ds_read_b128 v[190:193], v179 offset:16384
	ds_read_b128 v[194:197], v179 offset:17408
	ds_read_b128 v[198:201], v179 offset:18432
	ds_read_b128 v[202:205], v179 offset:19456
	ds_read_b128 v[206:209], v179 offset:20480
	ds_read_b128 v[210:213], v179 offset:21504
	ds_read_b128 v[214:217], v179 offset:22528
	ds_read_b128 v[218:221], v179 offset:23552
	global_load_lds_dwordx4 v[170:171], off
	s_add_i32 m0, s49, 0x2000
	s_add_u32 s50, s22, 0xb0000
	v_lshl_add_u64 v[222:223], s[22:23], 0, v[150:151]
	s_addc_u32 s51, s23, 0
	s_add_i32 s49, s41, s26
	global_load_lds_dwordx4 v[222:223], off
	v_lshl_add_u64 v[224:225], s[50:51], 0, v[146:147]
	s_mov_b32 m0, s49
	v_lshl_add_u64 v[226:227], s[24:25], 0, v[148:149]
	global_load_lds_dwordx4 v[224:225], off
	v_lshl_add_u64 v[224:225], s[50:51], 0, v[150:151]
	s_add_i32 m0, s49, 0x2000
	s_nop 0
	global_load_lds_dwordx4 v[224:225], off
	v_lshl_add_u64 v[224:225], s[24:25], 0, v[144:145]
	s_mov_b32 m0, s27
	s_nop 0
	global_load_lds_dwordx4 v[224:225], off
	s_mov_b32 m0, s28
	s_nop 0
	global_load_lds_dwordx4 v[226:227], off
	s_waitcnt vmcnt(8)
	s_waitcnt lgkmcnt(0)
	s_barrier
; #define PG8_STAGE(bufoff, gbase, voff) do { _Pragma("unroll") for (int _i = 0; _i < 2; ++_i) \
;         __builtin_amdgcn_global_load_lds((const unsigned*)((const char*)(gbase) + (voff)[_i]), (LAS unsigned*)(lds + (bufoff) + ldsw + _i * 8192), 16, 0, 0); } while (0)
; #define PG8_LDA(dst, b, h) do { _Pragma("unroll") for (int m = 0; m < 4; ++m) _Pragma("unroll") for (int k = 0; k < 2; ++k) dst[m][k] = *(const LAS bf16x8*)(lds + PG8_SA(b, h) + aoff + m * 2048 + k * 1024); } while (0)
; #define PG8_LDB(dst, b, h) do { _Pragma("unroll") for (int n = 0; n < 2; ++n) _Pragma("unroll") for (int k = 0; k < 2; ++k) dst[n][k] = *(const LAS bf16x8*)(lds + PG8_SB(b, h) + boff + n * 2048 + k * 1024); } while (0)
; #define PG8_MMA(ai, bj, At, Bt) do { __builtin_amdgcn_s_setprio(1); _Pragma("unroll") for (int m = 0; m < 4; ++m) _Pragma("unroll") for (int n = 0; n < 2; ++n) _Pragma("unroll") for (int k = 0; k < 2; ++k) \
;         acc[ai][bj][m][n] = __builtin_amdgcn_mfma_f32_16x16x32_bf16(Bt[n][k], At[m][k], acc[ai][bj][m][n], 0, 0, 0); __builtin_amdgcn_s_setprio(0); } while (0)
; #define PG8_WAIT_V(n) asm volatile("s_waitcnt vmcnt(" #n ")" ::: "memory")
; #define PG8_WAIT_L(n) asm volatile("s_waitcnt lgkmcnt(" #n ")" ::: "memory")
; #define PG8_BAR __builtin_amdgcn_s_barrier()
; #define PG8_SCHED __builtin_amdgcn_sched_barrier(0)
; template <class Epi, bool ALIGN_EPI>
; DI void gemm_phase(lptr lds, const Gemm g, const StaticOrder& S, const Epi& E) {
;     ...
;             PG8_WAIT_V(8); PG8_WAIT_L(0); PG8_BAR; PG8_MMA(1, 0, At, B0); PG8_MMA(1, 1, At, B1); PG8_BAR; PG8_SCHED;
;             PG8_LDB(B0, 1, 0); PG8_LDB(B1, 1, 1); PG8_SCHED; PG8_LDA(At, 1, 0); PG8_STAGE(PG8_SA(0, 1), a2 + hstepA, voffA);
;             PG8_WAIT_V(8); PG8_WAIT_L(0); PG8_BAR; PG8_MMA(0, 0, At, B0); PG8_MMA(0, 1, At, B1); PG8_BAR; PG8_SCHED;
;             PG8_LDA(At, 1, 1); PG8_STAGE(PG8_SB(1, 0), b3, voffB); PG8_STAGE(PG8_SB(1, 1), b3 + hstepB, voffB); PG8_STAGE(PG8_SA(1, 0), a3, voffA);
	s_setprio 1
	s_waitcnt lgkmcnt(0)
	v_mfma_f32_16x16x32_bf16 v[60:63], v[128:131], v[190:193], v[60:63]
	v_mfma_f32_16x16x32_bf16 v[56:59], v[136:139], v[190:193], v[56:59]
	v_mfma_f32_16x16x32_bf16 v[44:47], v[128:131], v[198:201], v[44:47]
	v_mfma_f32_16x16x32_bf16 v[40:43], v[136:139], v[198:201], v[40:43]
	v_mfma_f32_16x16x32_bf16 v[28:31], v[128:131], v[206:209], v[28:31]
	v_mfma_f32_16x16x32_bf16 v[24:27], v[136:139], v[206:209], v[24:27]
	v_mfma_f32_16x16x32_bf16 v[12:15], v[128:131], v[214:217], v[12:15]
	v_mfma_f32_16x16x32_bf16 v[8:11], v[136:139], v[214:217], v[8:11]
	v_mfma_f32_16x16x32_bf16 v[60:63], v[132:135], v[194:197], v[60:63]
	v_mfma_f32_16x16x32_bf16 v[56:59], v[140:143], v[194:197], v[56:59]
	v_mfma_f32_16x16x32_bf16 v[44:47], v[132:135], v[202:205], v[44:47]
	v_mfma_f32_16x16x32_bf16 v[40:43], v[140:143], v[202:205], v[40:43]
	v_mfma_f32_16x16x32_bf16 v[28:31], v[132:135], v[210:213], v[28:31]
	v_mfma_f32_16x16x32_bf16 v[24:27], v[140:143], v[210:213], v[24:27]
	v_mfma_f32_16x16x32_bf16 v[12:15], v[132:135], v[218:221], v[12:15]
	v_mfma_f32_16x16x32_bf16 v[8:11], v[140:143], v[218:221], v[8:11]
	s_setprio 0
	s_setprio 1
	v_mfma_f32_16x16x32_bf16 v[52:55], v[162:165], v[190:193], v[52:55]
	v_mfma_f32_16x16x32_bf16 v[48:51], v[182:185], v[190:193], v[48:51]
	v_mfma_f32_16x16x32_bf16 v[36:39], v[162:165], v[198:201], v[36:39]
	v_mfma_f32_16x16x32_bf16 v[32:35], v[182:185], v[198:201], v[32:35]
	v_mfma_f32_16x16x32_bf16 v[20:23], v[162:165], v[206:209], v[20:23]
	v_mfma_f32_16x16x32_bf16 v[16:19], v[182:185], v[206:209], v[16:19]
	v_mfma_f32_16x16x32_bf16 v[4:7], v[162:165], v[214:217], v[4:7]
	v_mfma_f32_16x16x32_bf16 v[0:3], v[182:185], v[214:217], v[0:3]
	v_mfma_f32_16x16x32_bf16 v[52:55], v[166:169], v[194:197], v[52:55]
	v_mfma_f32_16x16x32_bf16 v[48:51], v[186:189], v[194:197], v[48:51]
	v_mfma_f32_16x16x32_bf16 v[36:39], v[166:169], v[202:205], v[36:39]
	v_mfma_f32_16x16x32_bf16 v[32:35], v[186:189], v[202:205], v[32:35]
	v_mfma_f32_16x16x32_bf16 v[20:23], v[166:169], v[210:213], v[20:23]
	v_mfma_f32_16x16x32_bf16 v[16:19], v[186:189], v[210:213], v[16:19]
	v_mfma_f32_16x16x32_bf16 v[4:7], v[166:169], v[218:221], v[4:7]
	v_mfma_f32_16x16x32_bf16 v[0:3], v[186:189], v[218:221], v[0:3]
	s_setprio 0
	s_barrier
	s_add_i32 s49, 0, 0x18000
	s_add_i32 s50, 0, 0x1c000
	v_add_u32_e32 v140, s49, v173
	v_add_u32_e32 v181, s50, v173
	ds_read_b128 v[128:131], v140
	ds_read_b128 v[132:135], v140 offset:1024
	ds_read_b128 v[136:139], v140 offset:2048
	ds_read_b128 v[140:143], v140 offset:3072
	ds_read_b128 v[162:165], v181
	ds_read_b128 v[166:169], v181 offset:1024
	ds_read_b128 v[182:185], v181 offset:2048
	ds_read_b128 v[186:189], v181 offset:3072
	s_add_u32 s24, s24, 0xb0000
	s_addc_u32 s25, s25, 0
	s_mov_b32 m0, s29
	v_lshl_add_u64 v[228:229], s[24:25], 0, v[144:145]
	ds_read_b128 v[190:193], v179 offset:32768
	ds_read_b128 v[194:197], v179 offset:33792
	ds_read_b128 v[198:201], v179 offset:34816
	ds_read_b128 v[202:205], v179 offset:35840
	ds_read_b128 v[206:209], v179 offset:36864
	ds_read_b128 v[210:213], v179 offset:37888
	ds_read_b128 v[214:217], v179 offset:38912
	ds_read_b128 v[218:221], v179 offset:39936
	global_load_lds_dwordx4 v[228:229], off
	v_lshl_add_u64 v[228:229], s[24:25], 0, v[148:149]
	s_mov_b32 m0, s30
	s_nop 0
	global_load_lds_dwordx4 v[228:229], off
	s_waitcnt vmcnt(8)
	s_waitcnt lgkmcnt(0)
	s_barrier
	s_setprio 1
	s_waitcnt lgkmcnt(0)
	v_mfma_f32_16x16x32_bf16 v[124:127], v[128:131], v[190:193], v[124:127]
	v_mfma_f32_16x16x32_bf16 v[120:123], v[136:139], v[190:193], v[120:123]
	v_mfma_f32_16x16x32_bf16 v[108:111], v[128:131], v[198:201], v[108:111]
	v_mfma_f32_16x16x32_bf16 v[104:107], v[136:139], v[198:201], v[104:107]
	v_mfma_f32_16x16x32_bf16 v[92:95], v[128:131], v[206:209], v[92:95]
	v_mfma_f32_16x16x32_bf16 v[88:91], v[136:139], v[206:209], v[88:91]
	v_mfma_f32_16x16x32_bf16 v[76:79], v[128:131], v[214:217], v[76:79]
	v_mfma_f32_16x16x32_bf16 v[72:75], v[136:139], v[214:217], v[72:75]
	v_mfma_f32_16x16x32_bf16 v[124:127], v[132:135], v[194:197], v[124:127]
	v_mfma_f32_16x16x32_bf16 v[120:123], v[140:143], v[194:197], v[120:123]
	v_mfma_f32_16x16x32_bf16 v[108:111], v[132:135], v[202:205], v[108:111]
	v_mfma_f32_16x16x32_bf16 v[104:107], v[140:143], v[202:205], v[104:107]
	v_mfma_f32_16x16x32_bf16 v[92:95], v[132:135], v[210:213], v[92:95]
	v_mfma_f32_16x16x32_bf16 v[88:91], v[140:143], v[210:213], v[88:91]
	v_mfma_f32_16x16x32_bf16 v[76:79], v[132:135], v[218:221], v[76:79]
	v_mfma_f32_16x16x32_bf16 v[72:75], v[140:143], v[218:221], v[72:75]
	s_setprio 0
	s_setprio 1
	v_mfma_f32_16x16x32_bf16 v[116:119], v[162:165], v[190:193], v[116:119]
	v_mfma_f32_16x16x32_bf16 v[112:115], v[182:185], v[190:193], v[112:115]
	v_mfma_f32_16x16x32_bf16 v[100:103], v[162:165], v[198:201], v[100:103]
	v_mfma_f32_16x16x32_bf16 v[96:99], v[182:185], v[198:201], v[96:99]
	v_mfma_f32_16x16x32_bf16 v[84:87], v[162:165], v[206:209], v[84:87]
	v_mfma_f32_16x16x32_bf16 v[80:83], v[182:185], v[206:209], v[80:83]
	v_mfma_f32_16x16x32_bf16 v[68:71], v[162:165], v[214:217], v[68:71]
	v_mfma_f32_16x16x32_bf16 v[64:67], v[182:185], v[214:217], v[64:67]
	v_mfma_f32_16x16x32_bf16 v[116:119], v[166:169], v[194:197], v[116:119]
	v_mfma_f32_16x16x32_bf16 v[112:115], v[186:189], v[194:197], v[112:115]
	v_mfma_f32_16x16x32_bf16 v[100:103], v[166:169], v[202:205], v[100:103]
	v_mfma_f32_16x16x32_bf16 v[96:99], v[186:189], v[202:205], v[96:99]
	v_mfma_f32_16x16x32_bf16 v[84:87], v[166:169], v[210:213], v[84:87]
	v_mfma_f32_16x16x32_bf16 v[80:83], v[186:189], v[210:213], v[80:83]
	v_mfma_f32_16x16x32_bf16 v[68:71], v[166:169], v[218:221], v[68:71]
	v_mfma_f32_16x16x32_bf16 v[64:67], v[186:189], v[218:221], v[64:67]
	s_setprio 0
	s_barrier
; #define PG8_STAGE(bufoff, gbase, voff) do { _Pragma("unroll") for (int _i = 0; _i < 2; ++_i) \
;         __builtin_amdgcn_global_load_lds((const unsigned*)((const char*)(gbase) + (voff)[_i]), (LAS unsigned*)(lds + (bufoff) + ldsw + _i * 8192), 16, 0, 0); } while (0)
; #define PG8_LDA(dst, b, h) do { _Pragma("unroll") for (int m = 0; m < 4; ++m) _Pragma("unroll") for (int k = 0; k < 2; ++k) dst[m][k] = *(const LAS bf16x8*)(lds + PG8_SA(b, h) + aoff + m * 2048 + k * 1024); } while (0)
; #define PG8_MMA(ai, bj, At, Bt) do { __builtin_amdgcn_s_setprio(1); _Pragma("unroll") for (int m = 0; m < 4; ++m) _Pragma("unroll") for (int n = 0; n < 2; ++n) _Pragma("unroll") for (int k = 0; k < 2; ++k) \
;         acc[ai][bj][m][n] = __builtin_amdgcn_mfma_f32_16x16x32_bf16(Bt[n][k], At[m][k], acc[ai][bj][m][n], 0, 0, 0); __builtin_amdgcn_s_setprio(0); } while (0)
; #define PG8_WAIT_V(n) asm volatile("s_waitcnt vmcnt(" #n ")" ::: "memory")
; #define PG8_WAIT_L(n) asm volatile("s_waitcnt lgkmcnt(" #n ")" ::: "memory")
; #define PG8_BAR __builtin_amdgcn_s_barrier()
; #define PG8_SCHED __builtin_amdgcn_sched_barrier(0)
; template <class Epi, bool ALIGN_EPI>
; DI void gemm_phase(lptr lds, const Gemm g, const StaticOrder& S, const Epi& E) {
;     ...
;         for (int t = 0; t < nt; t += 2) {
;             const bool last = (t == nt - 2);
;     ...
;             PG8_LDA(At, 1, 1); PG8_STAGE(PG8_SB(1, 0), b3, voffB); PG8_STAGE(PG8_SB(1, 1), b3 + hstepB, voffB); PG8_STAGE(PG8_SA(1, 0), a3, voffA);
;             PG8_WAIT_V(8); PG8_WAIT_L(0); PG8_BAR; PG8_MMA(1, 0, At, B0); PG8_MMA(1, 1, At, B1); PG8_BAR; PG8_SCHED;
;         }
	s_add_i32 s24, s49, s26
	v_lshl_add_u64 v[170:171], v[170:171], 0, s[8:9]
	s_mov_b32 m0, s24
	ds_read_b128 v[190:193], v179 offset:49152
	ds_read_b128 v[194:197], v179 offset:50176
	ds_read_b128 v[198:201], v179 offset:51200
	ds_read_b128 v[202:205], v179 offset:52224
	ds_read_b128 v[206:209], v179 offset:53248
	ds_read_b128 v[210:213], v179 offset:54272
	ds_read_b128 v[214:217], v179 offset:55296
	ds_read_b128 v[218:221], v179 offset:56320
	global_load_lds_dwordx4 v[170:171], off
	s_add_i32 m0, s24, 0x2000
	s_add_u32 s22, s22, 0xb0080
	v_lshl_add_u64 v[170:171], v[222:223], 0, s[8:9]
	s_addc_u32 s23, s23, 0
	s_add_i32 s24, s50, s26
	global_load_lds_dwordx4 v[170:171], off
	v_lshl_add_u64 v[170:171], s[22:23], 0, v[146:147]
	s_mov_b32 m0, s24
	s_nop 0
	global_load_lds_dwordx4 v[170:171], off
	v_lshl_add_u64 v[170:171], s[22:23], 0, v[150:151]
	s_add_i32 m0, s24, 0x2000
	s_nop 0
	global_load_lds_dwordx4 v[170:171], off
	v_lshl_add_u64 v[170:171], v[224:225], 0, s[8:9]
	s_mov_b32 m0, s34
	s_nop 0
	global_load_lds_dwordx4 v[170:171], off
	v_lshl_add_u64 v[170:171], v[226:227], 0, s[8:9]
	s_mov_b32 m0, s35
	s_nop 0
	global_load_lds_dwordx4 v[170:171], off
	s_waitcnt vmcnt(8)
	s_waitcnt lgkmcnt(0)
	s_barrier
	s_setprio 1
	s_waitcnt lgkmcnt(0)
	v_mfma_f32_16x16x32_bf16 v[60:63], v[128:131], v[190:193], v[60:63]
	v_mfma_f32_16x16x32_bf16 v[56:59], v[136:139], v[190:193], v[56:59]
	v_mfma_f32_16x16x32_bf16 v[44:47], v[128:131], v[198:201], v[44:47]
	v_mfma_f32_16x16x32_bf16 v[40:43], v[136:139], v[198:201], v[40:43]
	v_mfma_f32_16x16x32_bf16 v[28:31], v[128:131], v[206:209], v[28:31]
	v_mfma_f32_16x16x32_bf16 v[24:27], v[136:139], v[206:209], v[24:27]
	v_mfma_f32_16x16x32_bf16 v[12:15], v[128:131], v[214:217], v[12:15]
	v_mfma_f32_16x16x32_bf16 v[8:11], v[136:139], v[214:217], v[8:11]
	v_mfma_f32_16x16x32_bf16 v[60:63], v[132:135], v[194:197], v[60:63]
	v_mfma_f32_16x16x32_bf16 v[56:59], v[140:143], v[194:197], v[56:59]
	v_mfma_f32_16x16x32_bf16 v[44:47], v[132:135], v[202:205], v[44:47]
	v_mfma_f32_16x16x32_bf16 v[40:43], v[140:143], v[202:205], v[40:43]
	v_mfma_f32_16x16x32_bf16 v[28:31], v[132:135], v[210:213], v[28:31]
	v_mfma_f32_16x16x32_bf16 v[24:27], v[140:143], v[210:213], v[24:27]
	v_mfma_f32_16x16x32_bf16 v[12:15], v[132:135], v[218:221], v[12:15]
	v_mfma_f32_16x16x32_bf16 v[8:11], v[140:143], v[218:221], v[8:11]
	s_setprio 0
	s_setprio 1
	v_mfma_f32_16x16x32_bf16 v[52:55], v[162:165], v[190:193], v[52:55]
	v_mfma_f32_16x16x32_bf16 v[48:51], v[182:185], v[190:193], v[48:51]
	v_mfma_f32_16x16x32_bf16 v[36:39], v[162:165], v[198:201], v[36:39]
	v_mfma_f32_16x16x32_bf16 v[32:35], v[182:185], v[198:201], v[32:35]
	v_mfma_f32_16x16x32_bf16 v[20:23], v[162:165], v[206:209], v[20:23]
	v_mfma_f32_16x16x32_bf16 v[16:19], v[182:185], v[206:209], v[16:19]
	v_mfma_f32_16x16x32_bf16 v[4:7], v[162:165], v[214:217], v[4:7]
	v_mfma_f32_16x16x32_bf16 v[0:3], v[182:185], v[214:217], v[0:3]
	v_mfma_f32_16x16x32_bf16 v[52:55], v[166:169], v[194:197], v[52:55]
	v_mfma_f32_16x16x32_bf16 v[48:51], v[186:189], v[194:197], v[48:51]
	v_mfma_f32_16x16x32_bf16 v[36:39], v[166:169], v[202:205], v[36:39]
	v_mfma_f32_16x16x32_bf16 v[32:35], v[186:189], v[202:205], v[32:35]
	v_mfma_f32_16x16x32_bf16 v[20:23], v[166:169], v[210:213], v[20:23]
	v_mfma_f32_16x16x32_bf16 v[16:19], v[186:189], v[210:213], v[16:19]
	v_mfma_f32_16x16x32_bf16 v[4:7], v[166:169], v[218:221], v[4:7]
	v_mfma_f32_16x16x32_bf16 v[0:3], v[186:189], v[218:221], v[0:3]
	s_setprio 0
	s_add_i32 s48, s48, 2
	s_add_u32 s20, s20, 0x100
	s_addc_u32 s21, s21, 0
	s_add_u32 s46, s46, 0x100
	s_addc_u32 s47, s47, 0
	s_cmp_gt_u32 s48, 41
	s_barrier
	s_cbranch_scc0 .LBB0_1385
	s_and_b64 vcc, exec, s[16:17]
	s_cbranch_vccz .LBB0_1388
	s_barrier

; #define PG8_STAGE(bufoff, gbase, voff) do { _Pragma("unroll") for (int _i = 0; _i < 2; ++_i) \
;         __builtin_amdgcn_global_load_lds((const unsigned*)((const char*)(gbase) + (voff)[_i]), (LAS unsigned*)(lds + (bufoff) + ldsw + _i * 8192), 16, 0, 0); } while (0)
; #define PG8_LDA(dst, b, h) do { _Pragma("unroll") for (int m = 0; m < 4; ++m) _Pragma("unroll") for (int k = 0; k < 2; ++k) dst[m][k] = *(const LAS bf16x8*)(lds + PG8_SA(b, h) + aoff + m * 2048 + k * 1024); } while (0)
; #define PG8_LDB(dst, b, h) do { _Pragma("unroll") for (int n = 0; n < 2; ++n) _Pragma("unroll") for (int k = 0; k < 2; ++k) dst[n][k] = *(const LAS bf16x8*)(lds + PG8_SB(b, h) + boff + n * 2048 + k * 1024); } while (0)
; #define PG8_MMA(ai, bj, At, Bt) do { __builtin_amdgcn_s_setprio(1); _Pragma("unroll") for (int m = 0; m < 4; ++m) _Pragma("unroll") for (int n = 0; n < 2; ++n) _Pragma("unroll") for (int k = 0; k < 2; ++k) \
;         acc[ai][bj][m][n] = __builtin_amdgcn_mfma_f32_16x16x32_bf16(Bt[n][k], At[m][k], acc[ai][bj][m][n], 0, 0, 0); __builtin_amdgcn_s_setprio(0); } while (0)
; #define PG8_WAIT_V(n) asm volatile("s_waitcnt vmcnt(" #n ")" ::: "memory")
; #define PG8_WAIT_L(n) asm volatile("s_waitcnt lgkmcnt(" #n ")" ::: "memory")
; #define PG8_BAR __builtin_amdgcn_s_barrier()
; #define PG8_SCHED __builtin_amdgcn_sched_barrier(0)
; template <class Epi, bool ALIGN_EPI>
; DI void gemm_phase(lptr lds, const Gemm g, const StaticOrder& S, const Epi& E) {
;     ...
;             const char* a1 = cA + (size_t)(t + 1) * kstep;
;             const char* a2 = last ? nA : cA + (size_t)(t + 2) * kstep; const char* b2 = last ? nB : cB + (size_t)(t + 2) * kstep;
;             const char* a3 = a2 + kstep; const char* b3 = b2 + kstep;
;             PG8_LDB(B0, 0, 0); PG8_LDB(B1, 0, 1); PG8_SCHED; PG8_LDA(At, 0, 0); PG8_STAGE(PG8_SA(1, 1), a1 + hstepA, voffA);
;             PG8_WAIT_V(8); PG8_WAIT_L(0); PG8_BAR; PG8_MMA(0, 0, At, B0); PG8_MMA(0, 1, At, B1); PG8_BAR; PG8_SCHED;
;             PG8_LDA(At, 0, 1); PG8_STAGE(PG8_SB(0, 0), b2, voffB); PG8_STAGE(PG8_SB(0, 1), b2 + hstepB, voffB); PG8_STAGE(PG8_SA(0, 0), a2, voffA);
;             PG8_WAIT_V(8); PG8_WAIT_L(0); PG8_BAR; PG8_MMA(1, 0, At, B0); PG8_MMA(1, 1, At, B1); PG8_BAR; PG8_SCHED;
.LBB0_1432:
	ds_read_b128 v[144:147], v193
	ds_read_b128 v[148:151], v193 offset:1024
	ds_read_b128 v[154:157], v193 offset:2048
	ds_read_b128 v[164:167], v193 offset:3072
	ds_read_b128 v[202:205], v194
	ds_read_b128 v[206:209], v194 offset:1024
	ds_read_b128 v[210:213], v194 offset:2048
	ds_read_b128 v[214:217], v194 offset:3072
	s_add_u32 s34, s30, 0xfff50080
	s_addc_u32 s35, s31, -1
	s_cmp_eq_u32 s58, 40
	s_cselect_b32 s37, s1, s35
	s_cselect_b32 s36, s0, s34
	s_cselect_b32 s35, s27, s33
	s_cselect_b32 s34, s26, s29
	v_lshl_add_u64 v[158:159], s[30:31], 0, v[136:137]
	s_add_i32 m0, s41, 0xc000
	ds_read_b128 v[218:221], v195
	ds_read_b128 v[222:225], v195 offset:1024
	ds_read_b128 v[226:229], v195 offset:2048
	ds_read_b128 v[230:233], v195 offset:3072
	ds_read_b128 v[234:237], v195 offset:4096
	ds_read_b128 v[238:241], v195 offset:5120
	ds_read_b128 v[242:245], v195 offset:6144
	ds_read_b128 v[246:249], v195 offset:7168
	global_load_lds_dwordx4 v[158:159], off
	v_lshl_add_u64 v[158:159], s[30:31], 0, v[138:139]
	s_add_i32 m0, s41, 0xe000
	s_nop 0
	global_load_lds_dwordx4 v[158:159], off
	s_waitcnt vmcnt(8)
	s_waitcnt lgkmcnt(0)
	s_barrier
	s_setprio 1
	s_waitcnt lgkmcnt(0)
	v_mfma_f32_16x16x32_bf16 v[124:127], v[144:147], v[218:221], v[124:127]
	v_mfma_f32_16x16x32_bf16 v[120:123], v[154:157], v[218:221], v[120:123]
	v_mfma_f32_16x16x32_bf16 v[108:111], v[144:147], v[226:229], v[108:111]
	v_mfma_f32_16x16x32_bf16 v[104:107], v[154:157], v[226:229], v[104:107]
	v_mfma_f32_16x16x32_bf16 v[92:95], v[144:147], v[234:237], v[92:95]
	v_mfma_f32_16x16x32_bf16 v[88:91], v[154:157], v[234:237], v[88:91]
	v_mfma_f32_16x16x32_bf16 v[76:79], v[144:147], v[242:245], v[76:79]
	v_mfma_f32_16x16x32_bf16 v[72:75], v[154:157], v[242:245], v[72:75]
	v_mfma_f32_16x16x32_bf16 v[124:127], v[148:151], v[222:225], v[124:127]
	v_mfma_f32_16x16x32_bf16 v[120:123], v[164:167], v[222:225], v[120:123]
	v_mfma_f32_16x16x32_bf16 v[108:111], v[148:151], v[230:233], v[108:111]
	v_mfma_f32_16x16x32_bf16 v[104:107], v[164:167], v[230:233], v[104:107]
	v_mfma_f32_16x16x32_bf16 v[92:95], v[148:151], v[238:241], v[92:95]
	v_mfma_f32_16x16x32_bf16 v[88:91], v[164:167], v[238:241], v[88:91]
	v_mfma_f32_16x16x32_bf16 v[76:79], v[148:151], v[246:249], v[76:79]
	v_mfma_f32_16x16x32_bf16 v[72:75], v[164:167], v[246:249], v[72:75]
	s_setprio 0
	s_setprio 1
	v_mfma_f32_16x16x32_bf16 v[116:119], v[202:205], v[218:221], v[116:119]
	v_mfma_f32_16x16x32_bf16 v[112:115], v[210:213], v[218:221], v[112:115]
	v_mfma_f32_16x16x32_bf16 v[100:103], v[202:205], v[226:229], v[100:103]
	v_mfma_f32_16x16x32_bf16 v[96:99], v[210:213], v[226:229], v[96:99]
	v_mfma_f32_16x16x32_bf16 v[84:87], v[202:205], v[234:237], v[84:87]
	v_mfma_f32_16x16x32_bf16 v[80:83], v[210:213], v[234:237], v[80:83]
	v_mfma_f32_16x16x32_bf16 v[68:71], v[202:205], v[242:245], v[68:71]
	v_mfma_f32_16x16x32_bf16 v[64:67], v[210:213], v[242:245], v[64:67]
	v_mfma_f32_16x16x32_bf16 v[116:119], v[206:209], v[222:225], v[116:119]
	v_mfma_f32_16x16x32_bf16 v[112:115], v[214:217], v[222:225], v[112:115]
	v_mfma_f32_16x16x32_bf16 v[100:103], v[206:209], v[230:233], v[100:103]
	v_mfma_f32_16x16x32_bf16 v[96:99], v[214:217], v[230:233], v[96:99]
	v_mfma_f32_16x16x32_bf16 v[84:87], v[206:209], v[238:241], v[84:87]
	v_mfma_f32_16x16x32_bf16 v[80:83], v[214:217], v[238:241], v[80:83]
	v_mfma_f32_16x16x32_bf16 v[68:71], v[206:209], v[246:249], v[68:71]
	v_mfma_f32_16x16x32_bf16 v[64:67], v[214:217], v[246:249], v[64:67]
	s_setprio 0
	s_barrier
	s_add_i32 s59, s51, s40
	v_lshl_add_u64 v[158:159], s[34:35], 0, v[130:131]
	s_mov_b32 m0, s59
	ds_read_b128 v[218:221], v195 offset:16384
	ds_read_b128 v[222:225], v195 offset:17408
	ds_read_b128 v[226:229], v195 offset:18432
	ds_read_b128 v[230:233], v195 offset:19456
	ds_read_b128 v[234:237], v195 offset:20480
	ds_read_b128 v[238:241], v195 offset:21504
	ds_read_b128 v[242:245], v195 offset:22528
	ds_read_b128 v[246:249], v195 offset:23552
	global_load_lds_dwordx4 v[158:159], off
	s_add_i32 m0, s59, 0x2000
	s_add_u32 s60, s34, 0xb0000
	v_lshl_add_u64 v[168:169], s[34:35], 0, v[134:135]
	s_addc_u32 s61, s35, 0
	s_add_i32 s59, s52, s40
	global_load_lds_dwordx4 v[168:169], off
	v_lshl_add_u64 v[172:173], s[60:61], 0, v[130:131]
	s_mov_b32 m0, s59
	v_lshl_add_u64 v[250:251], s[36:37], 0, v[132:133]
	global_load_lds_dwordx4 v[172:173], off
	v_lshl_add_u64 v[172:173], s[60:61], 0, v[134:135]
	s_add_i32 m0, s59, 0x2000
	s_nop 0
	global_load_lds_dwordx4 v[172:173], off
	v_lshl_add_u64 v[172:173], s[36:37], 0, v[128:129]
	s_mov_b32 m0, s41
	s_nop 0
	global_load_lds_dwordx4 v[172:173], off
	s_mov_b32 m0, s42
	s_nop 0
	global_load_lds_dwordx4 v[250:251], off
	s_waitcnt vmcnt(8)
	s_waitcnt lgkmcnt(0)
	s_barrier
; #define PG8_STAGE(bufoff, gbase, voff) do { _Pragma("unroll") for (int _i = 0; _i < 2; ++_i) \
;         __builtin_amdgcn_global_load_lds((const unsigned*)((const char*)(gbase) + (voff)[_i]), (LAS unsigned*)(lds + (bufoff) + ldsw + _i * 8192), 16, 0, 0); } while (0)
; #define PG8_LDA(dst, b, h) do { _Pragma("unroll") for (int m = 0; m < 4; ++m) _Pragma("unroll") for (int k = 0; k < 2; ++k) dst[m][k] = *(const LAS bf16x8*)(lds + PG8_SA(b, h) + aoff + m * 2048 + k * 1024); } while (0)
; #define PG8_LDB(dst, b, h) do { _Pragma("unroll") for (int n = 0; n < 2; ++n) _Pragma("unroll") for (int k = 0; k < 2; ++k) dst[n][k] = *(const LAS bf16x8*)(lds + PG8_SB(b, h) + boff + n * 2048 + k * 1024); } while (0)
; #define PG8_MMA(ai, bj, At, Bt) do { __builtin_amdgcn_s_setprio(1); _Pragma("unroll") for (int m = 0; m < 4; ++m) _Pragma("unroll") for (int n = 0; n < 2; ++n) _Pragma("unroll") for (int k = 0; k < 2; ++k) \
;         acc[ai][bj][m][n] = __builtin_amdgcn_mfma_f32_16x16x32_bf16(Bt[n][k], At[m][k], acc[ai][bj][m][n], 0, 0, 0); __builtin_amdgcn_s_setprio(0); } while (0)
; #define PG8_WAIT_V(n) asm volatile("s_waitcnt vmcnt(" #n ")" ::: "memory")
; #define PG8_WAIT_L(n) asm volatile("s_waitcnt lgkmcnt(" #n ")" ::: "memory")
; #define PG8_BAR __builtin_amdgcn_s_barrier()
; #define PG8_SCHED __builtin_amdgcn_sched_barrier(0)
; template <class Epi, bool ALIGN_EPI>
; DI void gemm_phase(lptr lds, const Gemm g, const StaticOrder& S, const Epi& E) {
;     ...
;             PG8_WAIT_V(8); PG8_WAIT_L(0); PG8_BAR; PG8_MMA(1, 0, At, B0); PG8_MMA(1, 1, At, B1); PG8_BAR; PG8_SCHED;
;             PG8_LDB(B0, 1, 0); PG8_LDB(B1, 1, 1); PG8_SCHED; PG8_LDA(At, 1, 0); PG8_STAGE(PG8_SA(0, 1), a2 + hstepA, voffA);
;             PG8_WAIT_V(8); PG8_WAIT_L(0); PG8_BAR; PG8_MMA(0, 0, At, B0); PG8_MMA(0, 1, At, B1); PG8_BAR; PG8_SCHED;
	s_setprio 1
	s_waitcnt lgkmcnt(0)
	v_mfma_f32_16x16x32_bf16 v[60:63], v[144:147], v[218:221], v[60:63]
	v_mfma_f32_16x16x32_bf16 v[56:59], v[154:157], v[218:221], v[56:59]
	v_mfma_f32_16x16x32_bf16 v[44:47], v[144:147], v[226:229], v[44:47]
	v_mfma_f32_16x16x32_bf16 v[40:43], v[154:157], v[226:229], v[40:43]
	v_mfma_f32_16x16x32_bf16 v[28:31], v[144:147], v[234:237], v[28:31]
	v_mfma_f32_16x16x32_bf16 v[24:27], v[154:157], v[234:237], v[24:27]
	v_mfma_f32_16x16x32_bf16 v[12:15], v[144:147], v[242:245], v[12:15]
	v_mfma_f32_16x16x32_bf16 v[8:11], v[154:157], v[242:245], v[8:11]
	v_mfma_f32_16x16x32_bf16 v[60:63], v[148:151], v[222:225], v[60:63]
	v_mfma_f32_16x16x32_bf16 v[56:59], v[164:167], v[222:225], v[56:59]
	v_mfma_f32_16x16x32_bf16 v[44:47], v[148:151], v[230:233], v[44:47]
	v_mfma_f32_16x16x32_bf16 v[40:43], v[164:167], v[230:233], v[40:43]
	v_mfma_f32_16x16x32_bf16 v[28:31], v[148:151], v[238:241], v[28:31]
	v_mfma_f32_16x16x32_bf16 v[24:27], v[164:167], v[238:241], v[24:27]
	v_mfma_f32_16x16x32_bf16 v[12:15], v[148:151], v[246:249], v[12:15]
	v_mfma_f32_16x16x32_bf16 v[8:11], v[164:167], v[246:249], v[8:11]
	s_setprio 0
	s_setprio 1
	v_mfma_f32_16x16x32_bf16 v[52:55], v[202:205], v[218:221], v[52:55]
	v_mfma_f32_16x16x32_bf16 v[48:51], v[210:213], v[218:221], v[48:51]
	v_mfma_f32_16x16x32_bf16 v[36:39], v[202:205], v[226:229], v[36:39]
	v_mfma_f32_16x16x32_bf16 v[32:35], v[210:213], v[226:229], v[32:35]
	v_mfma_f32_16x16x32_bf16 v[20:23], v[202:205], v[234:237], v[20:23]
	v_mfma_f32_16x16x32_bf16 v[16:19], v[210:213], v[234:237], v[16:19]
	v_mfma_f32_16x16x32_bf16 v[4:7], v[202:205], v[242:245], v[4:7]
	v_mfma_f32_16x16x32_bf16 v[0:3], v[210:213], v[242:245], v[0:3]
	v_mfma_f32_16x16x32_bf16 v[52:55], v[206:209], v[222:225], v[52:55]
	v_mfma_f32_16x16x32_bf16 v[48:51], v[214:217], v[222:225], v[48:51]
	v_mfma_f32_16x16x32_bf16 v[36:39], v[206:209], v[230:233], v[36:39]
	v_mfma_f32_16x16x32_bf16 v[32:35], v[214:217], v[230:233], v[32:35]
	v_mfma_f32_16x16x32_bf16 v[20:23], v[206:209], v[238:241], v[20:23]
	v_mfma_f32_16x16x32_bf16 v[16:19], v[214:217], v[238:241], v[16:19]
	v_mfma_f32_16x16x32_bf16 v[4:7], v[206:209], v[246:249], v[4:7]
	v_mfma_f32_16x16x32_bf16 v[0:3], v[214:217], v[246:249], v[0:3]
	s_setprio 0
	s_barrier
	s_add_i32 s59, 0, 0x18000
	v_add_u32_e32 v160, s59, v171
	s_add_i32 s60, 0, 0x1c000
	ds_read_b128 v[144:147], v160
	ds_read_b128 v[148:151], v160 offset:1024
	ds_read_b128 v[154:157], v160 offset:2048
	ds_read_b128 v[164:167], v160 offset:3072
	v_add_u32_e32 v160, s60, v171
	ds_read_b128 v[202:205], v160
	ds_read_b128 v[206:209], v160 offset:1024
	ds_read_b128 v[210:213], v160 offset:2048
	ds_read_b128 v[214:217], v160 offset:3072
	s_add_u32 s36, s36, 0xb0000
	s_addc_u32 s37, s37, 0
	s_mov_b32 m0, s43
	v_lshl_add_u64 v[252:253], s[36:37], 0, v[128:129]
	ds_read_b128 v[218:221], v195 offset:32768
	ds_read_b128 v[222:225], v195 offset:33792
	ds_read_b128 v[226:229], v195 offset:34816
	ds_read_b128 v[230:233], v195 offset:35840
	ds_read_b128 v[234:237], v195 offset:36864
	ds_read_b128 v[238:241], v195 offset:37888
	ds_read_b128 v[242:245], v195 offset:38912
	ds_read_b128 v[246:249], v195 offset:39936
	global_load_lds_dwordx4 v[252:253], off
	v_lshl_add_u64 v[252:253], s[36:37], 0, v[132:133]
	s_mov_b32 m0, s44
	s_nop 0
	global_load_lds_dwordx4 v[252:253], off
	s_waitcnt vmcnt(8)
	s_waitcnt lgkmcnt(0)
	s_barrier
	s_setprio 1
	s_waitcnt lgkmcnt(0)
	v_mfma_f32_16x16x32_bf16 v[124:127], v[144:147], v[218:221], v[124:127]
	v_mfma_f32_16x16x32_bf16 v[120:123], v[154:157], v[218:221], v[120:123]
	v_mfma_f32_16x16x32_bf16 v[108:111], v[144:147], v[226:229], v[108:111]
	v_mfma_f32_16x16x32_bf16 v[104:107], v[154:157], v[226:229], v[104:107]
	v_mfma_f32_16x16x32_bf16 v[92:95], v[144:147], v[234:237], v[92:95]
	v_mfma_f32_16x16x32_bf16 v[88:91], v[154:157], v[234:237], v[88:91]
	v_mfma_f32_16x16x32_bf16 v[76:79], v[144:147], v[242:245], v[76:79]
	v_mfma_f32_16x16x32_bf16 v[72:75], v[154:157], v[242:245], v[72:75]
	v_mfma_f32_16x16x32_bf16 v[124:127], v[148:151], v[222:225], v[124:127]
	v_mfma_f32_16x16x32_bf16 v[120:123], v[164:167], v[222:225], v[120:123]
	v_mfma_f32_16x16x32_bf16 v[108:111], v[148:151], v[230:233], v[108:111]
	v_mfma_f32_16x16x32_bf16 v[104:107], v[164:167], v[230:233], v[104:107]
	v_mfma_f32_16x16x32_bf16 v[92:95], v[148:151], v[238:241], v[92:95]
	v_mfma_f32_16x16x32_bf16 v[88:91], v[164:167], v[238:241], v[88:91]
	v_mfma_f32_16x16x32_bf16 v[76:79], v[148:151], v[246:249], v[76:79]
	v_mfma_f32_16x16x32_bf16 v[72:75], v[164:167], v[246:249], v[72:75]
	s_setprio 0
	s_setprio 1
	v_mfma_f32_16x16x32_bf16 v[116:119], v[202:205], v[218:221], v[116:119]
	v_mfma_f32_16x16x32_bf16 v[112:115], v[210:213], v[218:221], v[112:115]
	v_mfma_f32_16x16x32_bf16 v[100:103], v[202:205], v[226:229], v[100:103]
	v_mfma_f32_16x16x32_bf16 v[96:99], v[210:213], v[226:229], v[96:99]
	v_mfma_f32_16x16x32_bf16 v[84:87], v[202:205], v[234:237], v[84:87]
	v_mfma_f32_16x16x32_bf16 v[80:83], v[210:213], v[234:237], v[80:83]
	v_mfma_f32_16x16x32_bf16 v[68:71], v[202:205], v[242:245], v[68:71]
	v_mfma_f32_16x16x32_bf16 v[64:67], v[210:213], v[242:245], v[64:67]
	v_mfma_f32_16x16x32_bf16 v[116:119], v[206:209], v[222:225], v[116:119]
	v_mfma_f32_16x16x32_bf16 v[112:115], v[214:217], v[222:225], v[112:115]
	v_mfma_f32_16x16x32_bf16 v[100:103], v[206:209], v[230:233], v[100:103]
	v_mfma_f32_16x16x32_bf16 v[96:99], v[214:217], v[230:233], v[96:99]
	v_mfma_f32_16x16x32_bf16 v[84:87], v[206:209], v[238:241], v[84:87]
	v_mfma_f32_16x16x32_bf16 v[80:83], v[214:217], v[238:241], v[80:83]
	v_mfma_f32_16x16x32_bf16 v[68:71], v[206:209], v[246:249], v[68:71]
	v_mfma_f32_16x16x32_bf16 v[64:67], v[214:217], v[246:249], v[64:67]
	s_setprio 0
	s_barrier
; #define PG8_STAGE(bufoff, gbase, voff) do { _Pragma("unroll") for (int _i = 0; _i < 2; ++_i) \
;         __builtin_amdgcn_global_load_lds((const unsigned*)((const char*)(gbase) + (voff)[_i]), (LAS unsigned*)(lds + (bufoff) + ldsw + _i * 8192), 16, 0, 0); } while (0)
; #define PG8_LDA(dst, b, h) do { _Pragma("unroll") for (int m = 0; m < 4; ++m) _Pragma("unroll") for (int k = 0; k < 2; ++k) dst[m][k] = *(const LAS bf16x8*)(lds + PG8_SA(b, h) + aoff + m * 2048 + k * 1024); } while (0)
; #define PG8_MMA(ai, bj, At, Bt) do { __builtin_amdgcn_s_setprio(1); _Pragma("unroll") for (int m = 0; m < 4; ++m) _Pragma("unroll") for (int n = 0; n < 2; ++n) _Pragma("unroll") for (int k = 0; k < 2; ++k) \
;         acc[ai][bj][m][n] = __builtin_amdgcn_mfma_f32_16x16x32_bf16(Bt[n][k], At[m][k], acc[ai][bj][m][n], 0, 0, 0); __builtin_amdgcn_s_setprio(0); } while (0)
; #define PG8_WAIT_V(n) asm volatile("s_waitcnt vmcnt(" #n ")" ::: "memory")
; #define PG8_WAIT_L(n) asm volatile("s_waitcnt lgkmcnt(" #n ")" ::: "memory")
; #define PG8_BAR __builtin_amdgcn_s_barrier()
; #define PG8_SCHED __builtin_amdgcn_sched_barrier(0)
; template <class Epi, bool ALIGN_EPI>
; DI void gemm_phase(lptr lds, const Gemm g, const StaticOrder& S, const Epi& E) {
;     ...
;             PG8_LDA(At, 1, 1); PG8_STAGE(PG8_SB(1, 0), b3, voffB); PG8_STAGE(PG8_SB(1, 1), b3 + hstepB, voffB); PG8_STAGE(PG8_SA(1, 0), a3, voffA);
;             PG8_WAIT_V(8); PG8_WAIT_L(0); PG8_BAR; PG8_MMA(1, 0, At, B0); PG8_MMA(1, 1, At, B1); PG8_BAR; PG8_SCHED;
;         }
	s_add_i32 s36, s59, s40
	v_lshl_add_u64 v[158:159], v[158:159], 0, s[22:23]
	s_mov_b32 m0, s36
	ds_read_b128 v[218:221], v195 offset:49152
	ds_read_b128 v[222:225], v195 offset:50176
	ds_read_b128 v[226:229], v195 offset:51200
	ds_read_b128 v[230:233], v195 offset:52224
	ds_read_b128 v[234:237], v195 offset:53248
	ds_read_b128 v[238:241], v195 offset:54272
	ds_read_b128 v[242:245], v195 offset:55296
	ds_read_b128 v[246:249], v195 offset:56320
	global_load_lds_dwordx4 v[158:159], off
	s_add_i32 m0, s36, 0x2000
	s_add_u32 s34, s34, 0xb0080
	v_lshl_add_u64 v[158:159], v[168:169], 0, s[22:23]
	s_addc_u32 s35, s35, 0
	s_add_i32 s36, s60, s40
	global_load_lds_dwordx4 v[158:159], off
	v_lshl_add_u64 v[158:159], s[34:35], 0, v[130:131]
	s_mov_b32 m0, s36
	s_nop 0
	global_load_lds_dwordx4 v[158:159], off
	v_lshl_add_u64 v[158:159], s[34:35], 0, v[134:135]
	s_add_i32 m0, s36, 0x2000
	s_nop 0
	global_load_lds_dwordx4 v[158:159], off
	v_lshl_add_u64 v[158:159], v[172:173], 0, s[22:23]
	s_mov_b32 m0, s48
	s_nop 0
	global_load_lds_dwordx4 v[158:159], off
	v_lshl_add_u64 v[158:159], v[250:251], 0, s[22:23]
	s_mov_b32 m0, s49
	s_nop 0
	global_load_lds_dwordx4 v[158:159], off
	s_waitcnt vmcnt(8)
	s_waitcnt lgkmcnt(0)
	s_barrier
	s_setprio 1
	s_waitcnt lgkmcnt(0)
	v_mfma_f32_16x16x32_bf16 v[60:63], v[144:147], v[218:221], v[60:63]
	v_mfma_f32_16x16x32_bf16 v[56:59], v[154:157], v[218:221], v[56:59]
	v_mfma_f32_16x16x32_bf16 v[44:47], v[144:147], v[226:229], v[44:47]
	v_mfma_f32_16x16x32_bf16 v[40:43], v[154:157], v[226:229], v[40:43]
	v_mfma_f32_16x16x32_bf16 v[28:31], v[144:147], v[234:237], v[28:31]
	v_mfma_f32_16x16x32_bf16 v[24:27], v[154:157], v[234:237], v[24:27]
	v_mfma_f32_16x16x32_bf16 v[12:15], v[144:147], v[242:245], v[12:15]
	v_mfma_f32_16x16x32_bf16 v[8:11], v[154:157], v[242:245], v[8:11]
	v_mfma_f32_16x16x32_bf16 v[60:63], v[148:151], v[222:225], v[60:63]
	v_mfma_f32_16x16x32_bf16 v[56:59], v[164:167], v[222:225], v[56:59]
	v_mfma_f32_16x16x32_bf16 v[44:47], v[148:151], v[230:233], v[44:47]
	v_mfma_f32_16x16x32_bf16 v[40:43], v[164:167], v[230:233], v[40:43]
	v_mfma_f32_16x16x32_bf16 v[28:31], v[148:151], v[238:241], v[28:31]
	v_mfma_f32_16x16x32_bf16 v[24:27], v[164:167], v[238:241], v[24:27]
	v_mfma_f32_16x16x32_bf16 v[12:15], v[148:151], v[246:249], v[12:15]
	v_mfma_f32_16x16x32_bf16 v[8:11], v[164:167], v[246:249], v[8:11]
	s_setprio 0
	s_setprio 1
	v_mfma_f32_16x16x32_bf16 v[52:55], v[202:205], v[218:221], v[52:55]
	v_mfma_f32_16x16x32_bf16 v[48:51], v[210:213], v[218:221], v[48:51]
	v_mfma_f32_16x16x32_bf16 v[36:39], v[202:205], v[226:229], v[36:39]
	v_mfma_f32_16x16x32_bf16 v[32:35], v[210:213], v[226:229], v[32:35]
	v_mfma_f32_16x16x32_bf16 v[20:23], v[202:205], v[234:237], v[20:23]
	v_mfma_f32_16x16x32_bf16 v[16:19], v[210:213], v[234:237], v[16:19]
	v_mfma_f32_16x16x32_bf16 v[4:7], v[202:205], v[242:245], v[4:7]
	v_mfma_f32_16x16x32_bf16 v[0:3], v[210:213], v[242:245], v[0:3]
	v_mfma_f32_16x16x32_bf16 v[52:55], v[206:209], v[222:225], v[52:55]
	v_mfma_f32_16x16x32_bf16 v[48:51], v[214:217], v[222:225], v[48:51]
	v_mfma_f32_16x16x32_bf16 v[36:39], v[206:209], v[230:233], v[36:39]
	v_mfma_f32_16x16x32_bf16 v[32:35], v[214:217], v[230:233], v[32:35]
	v_mfma_f32_16x16x32_bf16 v[20:23], v[206:209], v[238:241], v[20:23]
	v_mfma_f32_16x16x32_bf16 v[16:19], v[214:217], v[238:241], v[16:19]
	v_mfma_f32_16x16x32_bf16 v[4:7], v[206:209], v[246:249], v[4:7]
	v_mfma_f32_16x16x32_bf16 v[0:3], v[214:217], v[246:249], v[0:3]
	s_setprio 0
	s_add_i32 s58, s58, 2
	s_add_u32 s30, s30, 0x100
	s_addc_u32 s31, s31, 0
	s_add_u32 s29, s29, 0x100
	s_addc_u32 s33, s33, 0
	s_cmp_gt_u32 s58, 41
	s_barrier
	s_cbranch_scc0 .LBB0_1432
	s_and_b64 vcc, exec, s[24:25]
	s_cbranch_vccz .LBB0_1435
	s_barrier
